# plus: the redundant s_waitcnt lgkmcnt(0) between each K-loop barrier release and the first MFMA removed (the drain before the barrier already covers it)
# baseline (speedup 1.0000x reference)
; #define PG8_STAGE(bufoff, gbase, voff) do { _Pragma("unroll") for (int _i = 0; _i < 2; ++_i) \
;         __builtin_amdgcn_global_load_lds((const unsigned*)((const char*)(gbase) + (voff)[_i]), (LAS unsigned*)(lds + (bufoff) + ldsw + _i * 8192), 16, 0, 0); } while (0)
; #define PG8_LDA(dst, b, h) do { _Pragma("unroll") for (int m = 0; m < 4; ++m) _Pragma("unroll") for (int k = 0; k < 2; ++k) dst[m][k] = *(const LAS bf16x8*)(lds + PG8_SA(b, h) + aoff + m * 2048 + k * 1024); } while (0)
; #define PG8_LDB(dst, b, h) do { _Pragma("unroll") for (int n = 0; n < 2; ++n) _Pragma("unroll") for (int k = 0; k < 2; ++k) dst[n][k] = *(const LAS bf16x8*)(lds + PG8_SB(b, h) + boff + n * 2048 + k * 1024); } while (0)
; #define PG8_MMA(ai, bj, At, Bt) do { __builtin_amdgcn_s_setprio(1); _Pragma("unroll") for (int m = 0; m < 4; ++m) _Pragma("unroll") for (int n = 0; n < 2; ++n) _Pragma("unroll") for (int k = 0; k < 2; ++k) \
;         acc[ai][bj][m][n] = __builtin_amdgcn_mfma_f32_16x16x32_bf16(Bt[n][k], At[m][k], acc[ai][bj][m][n], 0, 0, 0); __builtin_amdgcn_s_setprio(0); } while (0)
; #define PG8_WAIT_V(n) asm volatile("s_waitcnt vmcnt(" #n ")" ::: "memory")
; #define PG8_WAIT_L(n) asm volatile("s_waitcnt lgkmcnt(" #n ")" ::: "memory")
; #define PG8_BAR __builtin_amdgcn_s_barrier()
; #define PG8_SCHED __builtin_amdgcn_sched_barrier(0)
; template <class Epi, class Map>
; __device__ __forceinline__ void gemm_phase(LAS unsigned char* lds, const Gemm g, const Sched<Map>& S, const Epi& E) {
;     ...
;         for (int t = 0; t < nt; t += 2) {
;             const bool last = (t == nt - 2);
;             const char* a1 = cA + (size_t)(t + 1) * kstep;
;             const char* a2 = last ? nA : cA + (size_t)(t + 2) * kstep; const char* b2 = last ? nB : cB + (size_t)(t + 2) * kstep;
;             const char* a3 = a2 + kstep; const char* b3 = b2 + kstep;
;             PG8_LDB(B0, 0, 0); PG8_LDB(B1, 0, 1); PG8_SCHED; PG8_LDA(At, 0, 0); PG8_STAGE(PG8_SA(1, 1), a1 + hstepA, voffA);
;             PG8_WAIT_V(8); PG8_WAIT_L(0); PG8_BAR; PG8_MMA(0, 0, At, B0); PG8_MMA(0, 1, At, B1); PG8_BAR; PG8_SCHED;
;             PG8_LDA(At, 0, 1); PG8_STAGE(PG8_SB(0, 0), b2, voffB); PG8_STAGE(PG8_SB(0, 1), b2 + hstepB, voffB); PG8_STAGE(PG8_SA(0, 0), a2, voffA);
.LBB0_223:
	s_add_u32 s48, s42, s46
	s_addc_u32 s49, s43, s47
	s_add_u32 s48, s48, 0x100
	s_addc_u32 s49, s49, 0
	s_add_u32 s62, s65, s46
	s_addc_u32 s63, s66, s47
	s_add_i32 s68, 0, 0x10000
	s_cmpk_eq_i32 s46, 0xf00
	s_cselect_b32 s51, s56, s49
	s_cselect_b32 s50, s57, s48
	v_add_u32_e32 v136, s68, v170
	s_cselect_b32 s49, s58, s63
	s_cselect_b32 s48, s59, s62
	s_add_i32 s62, 0, 0x14000
	ds_read_b128 v[132:135], v136
	ds_read_b128 v[162:165], v136 offset:1024
	ds_read_b128 v[172:175], v136 offset:2048
	ds_read_b128 v[176:179], v136 offset:3072
	v_add_u32_e32 v136, s62, v170
	ds_read_b128 v[192:195], v136
	ds_read_b128 v[196:199], v136 offset:1024
	ds_read_b128 v[200:203], v136 offset:2048
	ds_read_b128 v[204:207], v136 offset:3072
	v_lshl_add_u64 v[136:137], v[130:131], 0, s[46:47]
	s_add_i32 m0, s6, 0xc000
	ds_read_b128 v[208:211], v171
	ds_read_b128 v[212:215], v171 offset:1024
	ds_read_b128 v[216:219], v171 offset:2048
	ds_read_b128 v[220:223], v171 offset:3072
	ds_read_b128 v[224:227], v171 offset:4096
	ds_read_b128 v[228:231], v171 offset:5120
	ds_read_b128 v[232:235], v171 offset:6144
	ds_read_b128 v[236:239], v171 offset:7168
	global_load_lds_dwordx4 v[136:137], off
	v_lshl_add_u64 v[136:137], v[128:129], 0, s[46:47]
	s_add_i32 m0, s6, 0xe000
	s_nop 0
	global_load_lds_dwordx4 v[136:137], off
	s_waitcnt vmcnt(8)
	s_waitcnt lgkmcnt(0)
	s_barrier
	v_mfma_f32_16x16x32_bf16 v[124:127], v[132:135], v[208:211], v[124:127]
	v_mfma_f32_16x16x32_bf16 v[120:123], v[172:175], v[208:211], v[120:123]
	v_mfma_f32_16x16x32_bf16 v[108:111], v[132:135], v[216:219], v[108:111]
	v_mfma_f32_16x16x32_bf16 v[104:107], v[172:175], v[216:219], v[104:107]
	v_mfma_f32_16x16x32_bf16 v[92:95], v[132:135], v[224:227], v[92:95]
	v_mfma_f32_16x16x32_bf16 v[88:91], v[172:175], v[224:227], v[88:91]
	v_mfma_f32_16x16x32_bf16 v[76:79], v[132:135], v[232:235], v[76:79]
	v_mfma_f32_16x16x32_bf16 v[72:75], v[172:175], v[232:235], v[72:75]
	v_mfma_f32_16x16x32_bf16 v[124:127], v[162:165], v[212:215], v[124:127]
	v_mfma_f32_16x16x32_bf16 v[120:123], v[176:179], v[212:215], v[120:123]
	v_mfma_f32_16x16x32_bf16 v[108:111], v[162:165], v[220:223], v[108:111]
	v_mfma_f32_16x16x32_bf16 v[104:107], v[176:179], v[220:223], v[104:107]
	v_mfma_f32_16x16x32_bf16 v[92:95], v[162:165], v[228:231], v[92:95]
	v_mfma_f32_16x16x32_bf16 v[88:91], v[176:179], v[228:231], v[88:91]
	v_mfma_f32_16x16x32_bf16 v[76:79], v[162:165], v[236:239], v[76:79]
	v_mfma_f32_16x16x32_bf16 v[72:75], v[176:179], v[236:239], v[72:75]
	v_mfma_f32_16x16x32_bf16 v[116:119], v[192:195], v[208:211], v[116:119]
	v_mfma_f32_16x16x32_bf16 v[112:115], v[200:203], v[208:211], v[112:115]
	v_mfma_f32_16x16x32_bf16 v[100:103], v[192:195], v[216:219], v[100:103]
	v_mfma_f32_16x16x32_bf16 v[96:99], v[200:203], v[216:219], v[96:99]
	v_mfma_f32_16x16x32_bf16 v[84:87], v[192:195], v[224:227], v[84:87]
	v_mfma_f32_16x16x32_bf16 v[80:83], v[200:203], v[224:227], v[80:83]
	v_mfma_f32_16x16x32_bf16 v[68:71], v[192:195], v[232:235], v[68:71]
	v_mfma_f32_16x16x32_bf16 v[64:67], v[200:203], v[232:235], v[64:67]
	v_mfma_f32_16x16x32_bf16 v[116:119], v[196:199], v[212:215], v[116:119]
	v_mfma_f32_16x16x32_bf16 v[112:115], v[204:207], v[212:215], v[112:115]
	v_mfma_f32_16x16x32_bf16 v[100:103], v[196:199], v[220:223], v[100:103]
	v_mfma_f32_16x16x32_bf16 v[96:99], v[204:207], v[220:223], v[96:99]
	v_mfma_f32_16x16x32_bf16 v[84:87], v[196:199], v[228:231], v[84:87]
	v_mfma_f32_16x16x32_bf16 v[80:83], v[204:207], v[228:231], v[80:83]
	v_mfma_f32_16x16x32_bf16 v[68:71], v[196:199], v[236:239], v[68:71]
	v_mfma_f32_16x16x32_bf16 v[64:67], v[204:207], v[236:239], v[64:67]
	s_barrier
	s_add_i32 s63, s68, s5
	v_lshl_add_u64 v[136:137], s[48:49], 0, v[144:145]
	s_mov_b32 m0, s63
	ds_read_b128 v[208:211], v171 offset:16384
	ds_read_b128 v[212:215], v171 offset:17408
	ds_read_b128 v[216:219], v171 offset:18432
	ds_read_b128 v[220:223], v171 offset:19456
	ds_read_b128 v[224:227], v171 offset:20480
	ds_read_b128 v[228:231], v171 offset:21504
	ds_read_b128 v[232:235], v171 offset:22528
	ds_read_b128 v[236:239], v171 offset:23552
	global_load_lds_dwordx4 v[136:137], off
	s_add_i32 m0, s63, 0x2000
	s_add_u32 s68, s48, 0x80000
	v_lshl_add_u64 v[166:167], s[48:49], 0, v[142:143]
	s_addc_u32 s69, s49, 0
	s_add_i32 s62, s62, s5
	global_load_lds_dwordx4 v[166:167], off
	v_lshl_add_u64 v[180:181], s[68:69], 0, v[144:145]
	s_mov_b32 m0, s62
	v_lshl_add_u64 v[240:241], s[50:51], 0, v[140:141]
	global_load_lds_dwordx4 v[180:181], off
	v_lshl_add_u64 v[180:181], s[68:69], 0, v[142:143]
	s_add_i32 m0, s62, 0x2000
	s_nop 0
	global_load_lds_dwordx4 v[180:181], off
	v_lshl_add_u64 v[180:181], s[50:51], 0, v[138:139]
	s_mov_b32 m0, s6
	s_nop 0
	global_load_lds_dwordx4 v[180:181], off
	s_mov_b32 m0, s7
	s_nop 0
	global_load_lds_dwordx4 v[240:241], off
	s_waitcnt vmcnt(8)
	s_waitcnt lgkmcnt(0)
	s_barrier
; #define PG8_STAGE(bufoff, gbase, voff) do { _Pragma("unroll") for (int _i = 0; _i < 2; ++_i) \
;         __builtin_amdgcn_global_load_lds((const unsigned*)((const char*)(gbase) + (voff)[_i]), (LAS unsigned*)(lds + (bufoff) + ldsw + _i * 8192), 16, 0, 0); } while (0)
; #define PG8_LDA(dst, b, h) do { _Pragma("unroll") for (int m = 0; m < 4; ++m) _Pragma("unroll") for (int k = 0; k < 2; ++k) dst[m][k] = *(const LAS bf16x8*)(lds + PG8_SA(b, h) + aoff + m * 2048 + k * 1024); } while (0)
; #define PG8_LDB(dst, b, h) do { _Pragma("unroll") for (int n = 0; n < 2; ++n) _Pragma("unroll") for (int k = 0; k < 2; ++k) dst[n][k] = *(const LAS bf16x8*)(lds + PG8_SB(b, h) + boff + n * 2048 + k * 1024); } while (0)
; #define PG8_MMA(ai, bj, At, Bt) do { __builtin_amdgcn_s_setprio(1); _Pragma("unroll") for (int m = 0; m < 4; ++m) _Pragma("unroll") for (int n = 0; n < 2; ++n) _Pragma("unroll") for (int k = 0; k < 2; ++k) \
;         acc[ai][bj][m][n] = __builtin_amdgcn_mfma_f32_16x16x32_bf16(Bt[n][k], At[m][k], acc[ai][bj][m][n], 0, 0, 0); __builtin_amdgcn_s_setprio(0); } while (0)
; #define PG8_WAIT_V(n) asm volatile("s_waitcnt vmcnt(" #n ")" ::: "memory")
; #define PG8_WAIT_L(n) asm volatile("s_waitcnt lgkmcnt(" #n ")" ::: "memory")
; #define PG8_BAR __builtin_amdgcn_s_barrier()
; #define PG8_SCHED __builtin_amdgcn_sched_barrier(0)
; template <class Epi, class Map>
; __device__ __forceinline__ void gemm_phase(LAS unsigned char* lds, const Gemm g, const Sched<Map>& S, const Epi& E) {
;     ...
;             PG8_WAIT_V(8); PG8_WAIT_L(0); PG8_BAR; PG8_MMA(1, 0, At, B0); PG8_MMA(1, 1, At, B1); PG8_BAR; PG8_SCHED;
;             PG8_LDB(B0, 1, 0); PG8_LDB(B1, 1, 1); PG8_SCHED; PG8_LDA(At, 1, 0); PG8_STAGE(PG8_SA(0, 1), a2 + hstepA, voffA);
;             PG8_WAIT_V(8); PG8_WAIT_L(0); PG8_BAR; PG8_MMA(0, 0, At, B0); PG8_MMA(0, 1, At, B1); PG8_BAR; PG8_SCHED;
	v_mfma_f32_16x16x32_bf16 v[60:63], v[132:135], v[208:211], v[60:63]
	v_mfma_f32_16x16x32_bf16 v[56:59], v[172:175], v[208:211], v[56:59]
	v_mfma_f32_16x16x32_bf16 v[44:47], v[132:135], v[216:219], v[44:47]
	v_mfma_f32_16x16x32_bf16 v[40:43], v[172:175], v[216:219], v[40:43]
	v_mfma_f32_16x16x32_bf16 v[28:31], v[132:135], v[224:227], v[28:31]
	v_mfma_f32_16x16x32_bf16 v[24:27], v[172:175], v[224:227], v[24:27]
	v_mfma_f32_16x16x32_bf16 v[12:15], v[132:135], v[232:235], v[12:15]
	v_mfma_f32_16x16x32_bf16 v[8:11], v[172:175], v[232:235], v[8:11]
	v_mfma_f32_16x16x32_bf16 v[60:63], v[162:165], v[212:215], v[60:63]
	v_mfma_f32_16x16x32_bf16 v[56:59], v[176:179], v[212:215], v[56:59]
	v_mfma_f32_16x16x32_bf16 v[44:47], v[162:165], v[220:223], v[44:47]
	v_mfma_f32_16x16x32_bf16 v[40:43], v[176:179], v[220:223], v[40:43]
	v_mfma_f32_16x16x32_bf16 v[28:31], v[162:165], v[228:231], v[28:31]
	v_mfma_f32_16x16x32_bf16 v[24:27], v[176:179], v[228:231], v[24:27]
	v_mfma_f32_16x16x32_bf16 v[12:15], v[162:165], v[236:239], v[12:15]
	v_mfma_f32_16x16x32_bf16 v[8:11], v[176:179], v[236:239], v[8:11]
	v_mfma_f32_16x16x32_bf16 v[52:55], v[192:195], v[208:211], v[52:55]
	v_mfma_f32_16x16x32_bf16 v[48:51], v[200:203], v[208:211], v[48:51]
	v_mfma_f32_16x16x32_bf16 v[36:39], v[192:195], v[216:219], v[36:39]
	v_mfma_f32_16x16x32_bf16 v[32:35], v[200:203], v[216:219], v[32:35]
	v_mfma_f32_16x16x32_bf16 v[20:23], v[192:195], v[224:227], v[20:23]
	v_mfma_f32_16x16x32_bf16 v[16:19], v[200:203], v[224:227], v[16:19]
	v_mfma_f32_16x16x32_bf16 v[4:7], v[192:195], v[232:235], v[4:7]
	v_mfma_f32_16x16x32_bf16 v[0:3], v[200:203], v[232:235], v[0:3]
	v_mfma_f32_16x16x32_bf16 v[52:55], v[196:199], v[212:215], v[52:55]
	v_mfma_f32_16x16x32_bf16 v[48:51], v[204:207], v[212:215], v[48:51]
	v_mfma_f32_16x16x32_bf16 v[36:39], v[196:199], v[220:223], v[36:39]
	v_mfma_f32_16x16x32_bf16 v[32:35], v[204:207], v[220:223], v[32:35]
	v_mfma_f32_16x16x32_bf16 v[20:23], v[196:199], v[228:231], v[20:23]
	v_mfma_f32_16x16x32_bf16 v[16:19], v[204:207], v[228:231], v[16:19]
	v_mfma_f32_16x16x32_bf16 v[4:7], v[196:199], v[236:239], v[4:7]
	v_mfma_f32_16x16x32_bf16 v[0:3], v[204:207], v[236:239], v[0:3]
	s_barrier
	s_add_i32 s62, 0, 0x18000
	s_add_i32 s63, 0, 0x1c000
	v_add_u32_e32 v176, s62, v170
	v_add_u32_e32 v204, s63, v170
	ds_read_b128 v[132:135], v176
	ds_read_b128 v[162:165], v176 offset:1024
	ds_read_b128 v[172:175], v176 offset:2048
	ds_read_b128 v[176:179], v176 offset:3072
	ds_read_b128 v[192:195], v204
	ds_read_b128 v[196:199], v204 offset:1024
	ds_read_b128 v[200:203], v204 offset:2048
	ds_read_b128 v[204:207], v204 offset:3072
	s_add_u32 s50, s50, s20
	s_addc_u32 s51, s51, 0
	s_mov_b32 m0, s8
	v_lshl_add_u64 v[242:243], s[50:51], 0, v[138:139]
	ds_read_b128 v[208:211], v171 offset:32768
	ds_read_b128 v[212:215], v171 offset:33792
	ds_read_b128 v[216:219], v171 offset:34816
	ds_read_b128 v[220:223], v171 offset:35840
	ds_read_b128 v[224:227], v171 offset:36864
	ds_read_b128 v[228:231], v171 offset:37888
	ds_read_b128 v[232:235], v171 offset:38912
	ds_read_b128 v[236:239], v171 offset:39936
	global_load_lds_dwordx4 v[242:243], off
	v_lshl_add_u64 v[242:243], s[50:51], 0, v[140:141]
	s_mov_b32 m0, s9
	s_nop 0
	global_load_lds_dwordx4 v[242:243], off
	s_waitcnt vmcnt(8)
	s_waitcnt lgkmcnt(0)
	s_barrier
	v_mfma_f32_16x16x32_bf16 v[124:127], v[132:135], v[208:211], v[124:127]
	v_mfma_f32_16x16x32_bf16 v[120:123], v[172:175], v[208:211], v[120:123]
	v_mfma_f32_16x16x32_bf16 v[108:111], v[132:135], v[216:219], v[108:111]
	v_mfma_f32_16x16x32_bf16 v[104:107], v[172:175], v[216:219], v[104:107]
	v_mfma_f32_16x16x32_bf16 v[92:95], v[132:135], v[224:227], v[92:95]
	v_mfma_f32_16x16x32_bf16 v[88:91], v[172:175], v[224:227], v[88:91]
	v_mfma_f32_16x16x32_bf16 v[76:79], v[132:135], v[232:235], v[76:79]
	v_mfma_f32_16x16x32_bf16 v[72:75], v[172:175], v[232:235], v[72:75]
	v_mfma_f32_16x16x32_bf16 v[124:127], v[162:165], v[212:215], v[124:127]
	v_mfma_f32_16x16x32_bf16 v[120:123], v[176:179], v[212:215], v[120:123]
	v_mfma_f32_16x16x32_bf16 v[108:111], v[162:165], v[220:223], v[108:111]
	v_mfma_f32_16x16x32_bf16 v[104:107], v[176:179], v[220:223], v[104:107]
	v_mfma_f32_16x16x32_bf16 v[92:95], v[162:165], v[228:231], v[92:95]
	v_mfma_f32_16x16x32_bf16 v[88:91], v[176:179], v[228:231], v[88:91]
	v_mfma_f32_16x16x32_bf16 v[76:79], v[162:165], v[236:239], v[76:79]
	v_mfma_f32_16x16x32_bf16 v[72:75], v[176:179], v[236:239], v[72:75]
	v_mfma_f32_16x16x32_bf16 v[116:119], v[192:195], v[208:211], v[116:119]
	v_mfma_f32_16x16x32_bf16 v[112:115], v[200:203], v[208:211], v[112:115]
	v_mfma_f32_16x16x32_bf16 v[100:103], v[192:195], v[216:219], v[100:103]
	v_mfma_f32_16x16x32_bf16 v[96:99], v[200:203], v[216:219], v[96:99]
	v_mfma_f32_16x16x32_bf16 v[84:87], v[192:195], v[224:227], v[84:87]
	v_mfma_f32_16x16x32_bf16 v[80:83], v[200:203], v[224:227], v[80:83]
	v_mfma_f32_16x16x32_bf16 v[68:71], v[192:195], v[232:235], v[68:71]
	v_mfma_f32_16x16x32_bf16 v[64:67], v[200:203], v[232:235], v[64:67]
	v_mfma_f32_16x16x32_bf16 v[116:119], v[196:199], v[212:215], v[116:119]
	v_mfma_f32_16x16x32_bf16 v[112:115], v[204:207], v[212:215], v[112:115]
	v_mfma_f32_16x16x32_bf16 v[100:103], v[196:199], v[220:223], v[100:103]
	v_mfma_f32_16x16x32_bf16 v[96:99], v[204:207], v[220:223], v[96:99]
	v_mfma_f32_16x16x32_bf16 v[84:87], v[196:199], v[228:231], v[84:87]
	v_mfma_f32_16x16x32_bf16 v[80:83], v[204:207], v[228:231], v[80:83]
	v_mfma_f32_16x16x32_bf16 v[68:71], v[196:199], v[236:239], v[68:71]
	v_mfma_f32_16x16x32_bf16 v[64:67], v[204:207], v[236:239], v[64:67]
	s_barrier
; #define PG8_STAGE(bufoff, gbase, voff) do { _Pragma("unroll") for (int _i = 0; _i < 2; ++_i) \
;         __builtin_amdgcn_global_load_lds((const unsigned*)((const char*)(gbase) + (voff)[_i]), (LAS unsigned*)(lds + (bufoff) + ldsw + _i * 8192), 16, 0, 0); } while (0)
; #define PG8_LDA(dst, b, h) do { _Pragma("unroll") for (int m = 0; m < 4; ++m) _Pragma("unroll") for (int k = 0; k < 2; ++k) dst[m][k] = *(const LAS bf16x8*)(lds + PG8_SA(b, h) + aoff + m * 2048 + k * 1024); } while (0)
; #define PG8_MMA(ai, bj, At, Bt) do { __builtin_amdgcn_s_setprio(1); _Pragma("unroll") for (int m = 0; m < 4; ++m) _Pragma("unroll") for (int n = 0; n < 2; ++n) _Pragma("unroll") for (int k = 0; k < 2; ++k) \
;         acc[ai][bj][m][n] = __builtin_amdgcn_mfma_f32_16x16x32_bf16(Bt[n][k], At[m][k], acc[ai][bj][m][n], 0, 0, 0); __builtin_amdgcn_s_setprio(0); } while (0)
; #define PG8_WAIT_V(n) asm volatile("s_waitcnt vmcnt(" #n ")" ::: "memory")
; #define PG8_WAIT_L(n) asm volatile("s_waitcnt lgkmcnt(" #n ")" ::: "memory")
; #define PG8_BAR __builtin_amdgcn_s_barrier()
; #define PG8_SCHED __builtin_amdgcn_sched_barrier(0)
; template <class Epi, class Map>
; __device__ __forceinline__ void gemm_phase(LAS unsigned char* lds, const Gemm g, const Sched<Map>& S, const Epi& E) {
;     ...
;             PG8_LDA(At, 1, 1); PG8_STAGE(PG8_SB(1, 0), b3, voffB); PG8_STAGE(PG8_SB(1, 1), b3 + hstepB, voffB); PG8_STAGE(PG8_SA(1, 0), a3, voffA);
;             PG8_WAIT_V(8); PG8_WAIT_L(0); PG8_BAR; PG8_MMA(1, 0, At, B0); PG8_MMA(1, 1, At, B1); PG8_BAR; PG8_SCHED;
;         }
;         if (wr == 0) PG8_BAR;
	s_add_i32 s50, s62, s5
	v_lshl_add_u64 v[136:137], v[136:137], 0, s[82:83]
	s_mov_b32 m0, s50
	ds_read_b128 v[208:211], v171 offset:49152
	ds_read_b128 v[212:215], v171 offset:50176
	ds_read_b128 v[216:219], v171 offset:51200
	ds_read_b128 v[220:223], v171 offset:52224
	ds_read_b128 v[224:227], v171 offset:53248
	ds_read_b128 v[228:231], v171 offset:54272
	ds_read_b128 v[232:235], v171 offset:55296
	ds_read_b128 v[236:239], v171 offset:56320
	global_load_lds_dwordx4 v[136:137], off
	s_add_i32 m0, s50, 0x2000
	s_add_u32 s48, s48, 0x80080
	v_lshl_add_u64 v[136:137], v[166:167], 0, s[82:83]
	s_addc_u32 s49, s49, 0
	s_add_i32 s50, s63, s5
	global_load_lds_dwordx4 v[136:137], off
	v_lshl_add_u64 v[136:137], s[48:49], 0, v[144:145]
	s_mov_b32 m0, s50
	s_nop 0
	global_load_lds_dwordx4 v[136:137], off
	v_lshl_add_u64 v[136:137], s[48:49], 0, v[142:143]
	s_add_i32 m0, s50, 0x2000
	s_nop 0
	global_load_lds_dwordx4 v[136:137], off
	v_lshl_add_u64 v[136:137], v[180:181], 0, s[82:83]
	s_mov_b32 m0, s14
	s_nop 0
	global_load_lds_dwordx4 v[136:137], off
	v_lshl_add_u64 v[136:137], v[240:241], 0, s[82:83]
	s_mov_b32 m0, s15
	s_nop 0
	global_load_lds_dwordx4 v[136:137], off
	s_waitcnt vmcnt(8)
	s_waitcnt lgkmcnt(0)
	s_barrier
	v_mfma_f32_16x16x32_bf16 v[60:63], v[132:135], v[208:211], v[60:63]
	v_mfma_f32_16x16x32_bf16 v[56:59], v[172:175], v[208:211], v[56:59]
	v_mfma_f32_16x16x32_bf16 v[44:47], v[132:135], v[216:219], v[44:47]
	v_mfma_f32_16x16x32_bf16 v[40:43], v[172:175], v[216:219], v[40:43]
	v_mfma_f32_16x16x32_bf16 v[28:31], v[132:135], v[224:227], v[28:31]
	v_mfma_f32_16x16x32_bf16 v[24:27], v[172:175], v[224:227], v[24:27]
	v_mfma_f32_16x16x32_bf16 v[12:15], v[132:135], v[232:235], v[12:15]
	v_mfma_f32_16x16x32_bf16 v[8:11], v[172:175], v[232:235], v[8:11]
	v_mfma_f32_16x16x32_bf16 v[60:63], v[162:165], v[212:215], v[60:63]
	v_mfma_f32_16x16x32_bf16 v[56:59], v[176:179], v[212:215], v[56:59]
	v_mfma_f32_16x16x32_bf16 v[44:47], v[162:165], v[220:223], v[44:47]
	v_mfma_f32_16x16x32_bf16 v[40:43], v[176:179], v[220:223], v[40:43]
	v_mfma_f32_16x16x32_bf16 v[28:31], v[162:165], v[228:231], v[28:31]
	v_mfma_f32_16x16x32_bf16 v[24:27], v[176:179], v[228:231], v[24:27]
	v_mfma_f32_16x16x32_bf16 v[12:15], v[162:165], v[236:239], v[12:15]
	v_mfma_f32_16x16x32_bf16 v[8:11], v[176:179], v[236:239], v[8:11]
	v_mfma_f32_16x16x32_bf16 v[52:55], v[192:195], v[208:211], v[52:55]
	v_mfma_f32_16x16x32_bf16 v[48:51], v[200:203], v[208:211], v[48:51]
	v_mfma_f32_16x16x32_bf16 v[36:39], v[192:195], v[216:219], v[36:39]
	v_mfma_f32_16x16x32_bf16 v[32:35], v[200:203], v[216:219], v[32:35]
	v_mfma_f32_16x16x32_bf16 v[20:23], v[192:195], v[224:227], v[20:23]
	v_mfma_f32_16x16x32_bf16 v[16:19], v[200:203], v[224:227], v[16:19]
	v_mfma_f32_16x16x32_bf16 v[4:7], v[192:195], v[232:235], v[4:7]
	v_mfma_f32_16x16x32_bf16 v[0:3], v[200:203], v[232:235], v[0:3]
	v_mfma_f32_16x16x32_bf16 v[52:55], v[196:199], v[212:215], v[52:55]
	v_mfma_f32_16x16x32_bf16 v[48:51], v[204:207], v[212:215], v[48:51]
	v_mfma_f32_16x16x32_bf16 v[36:39], v[196:199], v[220:223], v[36:39]
	v_mfma_f32_16x16x32_bf16 v[32:35], v[204:207], v[220:223], v[32:35]
	v_mfma_f32_16x16x32_bf16 v[20:23], v[196:199], v[228:231], v[20:23]
	v_mfma_f32_16x16x32_bf16 v[16:19], v[204:207], v[228:231], v[16:19]
	v_mfma_f32_16x16x32_bf16 v[4:7], v[196:199], v[236:239], v[4:7]
	v_mfma_f32_16x16x32_bf16 v[0:3], v[204:207], v[236:239], v[0:3]
	s_barrier
	s_add_i32 s67, s67, 2
	s_add_u32 s46, s46, 0x100
	s_addc_u32 s47, s47, 0
	s_cmp_gt_u32 s67, 29
	s_cbranch_scc0 .LBB0_223
	s_and_b64 vcc, exec, s[28:29]
	s_cbranch_vccz .LBB0_226
	s_barrier

; #define PG8_STAGE(bufoff, gbase, voff) do { _Pragma("unroll") for (int _i = 0; _i < 2; ++_i) \
;         __builtin_amdgcn_global_load_lds((const unsigned*)((const char*)(gbase) + (voff)[_i]), (LAS unsigned*)(lds + (bufoff) + ldsw + _i * 8192), 16, 0, 0); } while (0)
; #define PG8_LDA(dst, b, h) do { _Pragma("unroll") for (int m = 0; m < 4; ++m) _Pragma("unroll") for (int k = 0; k < 2; ++k) dst[m][k] = *(const LAS bf16x8*)(lds + PG8_SA(b, h) + aoff + m * 2048 + k * 1024); } while (0)
; #define PG8_LDB(dst, b, h) do { _Pragma("unroll") for (int n = 0; n < 2; ++n) _Pragma("unroll") for (int k = 0; k < 2; ++k) dst[n][k] = *(const LAS bf16x8*)(lds + PG8_SB(b, h) + boff + n * 2048 + k * 1024); } while (0)
; #define PG8_MMA(ai, bj, At, Bt) do { __builtin_amdgcn_s_setprio(1); _Pragma("unroll") for (int m = 0; m < 4; ++m) _Pragma("unroll") for (int n = 0; n < 2; ++n) _Pragma("unroll") for (int k = 0; k < 2; ++k) \
;         acc[ai][bj][m][n] = __builtin_amdgcn_mfma_f32_16x16x32_bf16(Bt[n][k], At[m][k], acc[ai][bj][m][n], 0, 0, 0); __builtin_amdgcn_s_setprio(0); } while (0)
; #define PG8_WAIT_V(n) asm volatile("s_waitcnt vmcnt(" #n ")" ::: "memory")
; #define PG8_WAIT_L(n) asm volatile("s_waitcnt lgkmcnt(" #n ")" ::: "memory")
; #define PG8_BAR __builtin_amdgcn_s_barrier()
; #define PG8_SCHED __builtin_amdgcn_sched_barrier(0)
; template <class Epi, class Map>
; __device__ __forceinline__ void gemm_phase(LAS unsigned char* lds, const Gemm g, const Sched<Map>& S, const Epi& E) {
;     ...
;         for (int t = 0; t < nt; t += 2) {
;             const bool last = (t == nt - 2);
;             const char* a1 = cA + (size_t)(t + 1) * kstep;
;             const char* a2 = last ? nA : cA + (size_t)(t + 2) * kstep; const char* b2 = last ? nB : cB + (size_t)(t + 2) * kstep;
;             const char* a3 = a2 + kstep; const char* b3 = b2 + kstep;
;             PG8_LDB(B0, 0, 0); PG8_LDB(B1, 0, 1); PG8_SCHED; PG8_LDA(At, 0, 0); PG8_STAGE(PG8_SA(1, 1), a1 + hstepA, voffA);
;             PG8_WAIT_V(8); PG8_WAIT_L(0); PG8_BAR; PG8_MMA(0, 0, At, B0); PG8_MMA(0, 1, At, B1); PG8_BAR; PG8_SCHED;
;             PG8_LDA(At, 0, 1); PG8_STAGE(PG8_SB(0, 0), b2, voffB); PG8_STAGE(PG8_SB(0, 1), b2 + hstepB, voffB); PG8_STAGE(PG8_SA(0, 0), a2, voffA);
.LBB0_261:
	s_add_u32 s36, s34, 0xfff80080
	s_addc_u32 s37, s35, -1
	s_add_i32 s54, 0, 0x10000
	s_cmp_eq_u32 s51, 28
	s_cselect_b32 s37, s25, s37
	s_cselect_b32 s36, s46, s36
	v_add_u32_e32 v138, s54, v142
	s_cselect_b32 s53, s47, s50
	s_cselect_b32 s52, s48, s49
	s_add_i32 s55, 0, 0x14000
	ds_read_b128 v[158:161], v138
	ds_read_b128 v[162:165], v138 offset:1024
	ds_read_b128 v[166:169], v138 offset:2048
	ds_read_b128 v[170:173], v138 offset:3072
	v_add_u32_e32 v138, s55, v142
	ds_read_b128 v[174:177], v138
	ds_read_b128 v[178:181], v138 offset:1024
	ds_read_b128 v[192:195], v138 offset:2048
	ds_read_b128 v[196:199], v138 offset:3072
	v_lshl_add_u64 v[138:139], s[34:35], 0, v[134:135]
	s_add_i32 m0, s7, 0xc000
	ds_read_b128 v[200:203], v143
	ds_read_b128 v[204:207], v143 offset:1024
	ds_read_b128 v[208:211], v143 offset:2048
	ds_read_b128 v[212:215], v143 offset:3072
	ds_read_b128 v[216:219], v143 offset:4096
	ds_read_b128 v[220:223], v143 offset:5120
	ds_read_b128 v[224:227], v143 offset:6144
	ds_read_b128 v[228:231], v143 offset:7168
	global_load_lds_dwordx4 v[138:139], off
	v_lshl_add_u64 v[138:139], s[34:35], 0, v[136:137]
	s_add_i32 m0, s7, 0xe000
	s_nop 0
	global_load_lds_dwordx4 v[138:139], off
	s_waitcnt vmcnt(8)
	s_waitcnt lgkmcnt(0)
	s_barrier
	v_mfma_f32_16x16x32_bf16 v[124:127], v[158:161], v[200:203], v[124:127]
	v_mfma_f32_16x16x32_bf16 v[120:123], v[166:169], v[200:203], v[120:123]
	v_mfma_f32_16x16x32_bf16 v[116:119], v[158:161], v[208:211], v[116:119]
	v_mfma_f32_16x16x32_bf16 v[108:111], v[166:169], v[208:211], v[108:111]
	v_mfma_f32_16x16x32_bf16 v[100:103], v[158:161], v[216:219], v[100:103]
	v_mfma_f32_16x16x32_bf16 v[92:95], v[166:169], v[216:219], v[92:95]
	v_mfma_f32_16x16x32_bf16 v[84:87], v[158:161], v[224:227], v[84:87]
	v_mfma_f32_16x16x32_bf16 v[76:79], v[166:169], v[224:227], v[76:79]
	v_mfma_f32_16x16x32_bf16 v[124:127], v[162:165], v[204:207], v[124:127]
	v_mfma_f32_16x16x32_bf16 v[120:123], v[170:173], v[204:207], v[120:123]
	v_mfma_f32_16x16x32_bf16 v[116:119], v[162:165], v[212:215], v[116:119]
	v_mfma_f32_16x16x32_bf16 v[108:111], v[170:173], v[212:215], v[108:111]
	v_mfma_f32_16x16x32_bf16 v[100:103], v[162:165], v[220:223], v[100:103]
	v_mfma_f32_16x16x32_bf16 v[92:95], v[170:173], v[220:223], v[92:95]
	v_mfma_f32_16x16x32_bf16 v[84:87], v[162:165], v[228:231], v[84:87]
	v_mfma_f32_16x16x32_bf16 v[76:79], v[170:173], v[228:231], v[76:79]
	v_mfma_f32_16x16x32_bf16 v[112:115], v[174:177], v[200:203], v[112:115]
	v_mfma_f32_16x16x32_bf16 v[104:107], v[192:195], v[200:203], v[104:107]
	v_mfma_f32_16x16x32_bf16 v[96:99], v[174:177], v[208:211], v[96:99]
	v_mfma_f32_16x16x32_bf16 v[88:91], v[192:195], v[208:211], v[88:91]
	v_mfma_f32_16x16x32_bf16 v[80:83], v[174:177], v[216:219], v[80:83]
	v_mfma_f32_16x16x32_bf16 v[72:75], v[192:195], v[216:219], v[72:75]
	v_mfma_f32_16x16x32_bf16 v[68:71], v[174:177], v[224:227], v[68:71]
	v_mfma_f32_16x16x32_bf16 v[64:67], v[192:195], v[224:227], v[64:67]
	v_mfma_f32_16x16x32_bf16 v[112:115], v[178:181], v[204:207], v[112:115]
	v_mfma_f32_16x16x32_bf16 v[104:107], v[196:199], v[204:207], v[104:107]
	v_mfma_f32_16x16x32_bf16 v[96:99], v[178:181], v[212:215], v[96:99]
	v_mfma_f32_16x16x32_bf16 v[88:91], v[196:199], v[212:215], v[88:91]
	v_mfma_f32_16x16x32_bf16 v[80:83], v[178:181], v[220:223], v[80:83]
	v_mfma_f32_16x16x32_bf16 v[72:75], v[196:199], v[220:223], v[72:75]
	v_mfma_f32_16x16x32_bf16 v[68:71], v[178:181], v[228:231], v[68:71]
	v_mfma_f32_16x16x32_bf16 v[64:67], v[196:199], v[228:231], v[64:67]
	s_barrier
	s_add_i32 s54, s54, s6
	v_lshl_add_u64 v[138:139], s[52:53], 0, v[144:145]
	s_mov_b32 m0, s54
	ds_read_b128 v[200:203], v143 offset:16384
	ds_read_b128 v[204:207], v143 offset:17408
	ds_read_b128 v[208:211], v143 offset:18432
	ds_read_b128 v[212:215], v143 offset:19456
	ds_read_b128 v[216:219], v143 offset:20480
	ds_read_b128 v[220:223], v143 offset:21504
	ds_read_b128 v[224:227], v143 offset:22528
	ds_read_b128 v[228:231], v143 offset:23552
	global_load_lds_dwordx4 v[138:139], off
	s_add_i32 m0, s54, 0x2000
	v_lshl_add_u64 v[232:233], s[52:53], 0, v[128:129]
	s_add_u32 s52, s52, s5
	s_addc_u32 s53, s53, 0
	s_add_i32 s54, s55, s6
	global_load_lds_dwordx4 v[232:233], off
	v_lshl_add_u64 v[234:235], s[52:53], 0, v[144:145]
	s_mov_b32 m0, s54
	v_lshl_add_u64 v[236:237], s[52:53], 0, v[128:129]
	global_load_lds_dwordx4 v[234:235], off
	s_add_i32 m0, s54, 0x2000
	v_lshl_add_u64 v[238:239], s[36:37], 0, v[132:133]
	global_load_lds_dwordx4 v[236:237], off
	s_mov_b32 m0, s7
	v_lshl_add_u64 v[240:241], s[36:37], 0, v[130:131]
	global_load_lds_dwordx4 v[238:239], off
	s_mov_b32 m0, s8
	s_nop 0
	global_load_lds_dwordx4 v[240:241], off
	s_waitcnt vmcnt(8)
	s_waitcnt lgkmcnt(0)
	s_barrier
; #define PG8_STAGE(bufoff, gbase, voff) do { _Pragma("unroll") for (int _i = 0; _i < 2; ++_i) \
;         __builtin_amdgcn_global_load_lds((const unsigned*)((const char*)(gbase) + (voff)[_i]), (LAS unsigned*)(lds + (bufoff) + ldsw + _i * 8192), 16, 0, 0); } while (0)
; #define PG8_LDA(dst, b, h) do { _Pragma("unroll") for (int m = 0; m < 4; ++m) _Pragma("unroll") for (int k = 0; k < 2; ++k) dst[m][k] = *(const LAS bf16x8*)(lds + PG8_SA(b, h) + aoff + m * 2048 + k * 1024); } while (0)
; #define PG8_LDB(dst, b, h) do { _Pragma("unroll") for (int n = 0; n < 2; ++n) _Pragma("unroll") for (int k = 0; k < 2; ++k) dst[n][k] = *(const LAS bf16x8*)(lds + PG8_SB(b, h) + boff + n * 2048 + k * 1024); } while (0)
; #define PG8_MMA(ai, bj, At, Bt) do { __builtin_amdgcn_s_setprio(1); _Pragma("unroll") for (int m = 0; m < 4; ++m) _Pragma("unroll") for (int n = 0; n < 2; ++n) _Pragma("unroll") for (int k = 0; k < 2; ++k) \
;         acc[ai][bj][m][n] = __builtin_amdgcn_mfma_f32_16x16x32_bf16(Bt[n][k], At[m][k], acc[ai][bj][m][n], 0, 0, 0); __builtin_amdgcn_s_setprio(0); } while (0)
; #define PG8_WAIT_V(n) asm volatile("s_waitcnt vmcnt(" #n ")" ::: "memory")
; #define PG8_WAIT_L(n) asm volatile("s_waitcnt lgkmcnt(" #n ")" ::: "memory")
; #define PG8_BAR __builtin_amdgcn_s_barrier()
; #define PG8_SCHED __builtin_amdgcn_sched_barrier(0)
; template <class Epi, class Map>
; __device__ __forceinline__ void gemm_phase(LAS unsigned char* lds, const Gemm g, const Sched<Map>& S, const Epi& E) {
;     ...
;             PG8_WAIT_V(8); PG8_WAIT_L(0); PG8_BAR; PG8_MMA(1, 0, At, B0); PG8_MMA(1, 1, At, B1); PG8_BAR; PG8_SCHED;
;             PG8_LDB(B0, 1, 0); PG8_LDB(B1, 1, 1); PG8_SCHED; PG8_LDA(At, 1, 0); PG8_STAGE(PG8_SA(0, 1), a2 + hstepA, voffA);
;             PG8_WAIT_V(8); PG8_WAIT_L(0); PG8_BAR; PG8_MMA(0, 0, At, B0); PG8_MMA(0, 1, At, B1); PG8_BAR; PG8_SCHED;
	v_mfma_f32_16x16x32_bf16 v[60:63], v[158:161], v[200:203], v[60:63]
	v_mfma_f32_16x16x32_bf16 v[56:59], v[166:169], v[200:203], v[56:59]
	v_mfma_f32_16x16x32_bf16 v[52:55], v[158:161], v[208:211], v[52:55]
	v_mfma_f32_16x16x32_bf16 v[44:47], v[166:169], v[208:211], v[44:47]
	v_mfma_f32_16x16x32_bf16 v[36:39], v[158:161], v[216:219], v[36:39]
	v_mfma_f32_16x16x32_bf16 v[28:31], v[166:169], v[216:219], v[28:31]
	v_mfma_f32_16x16x32_bf16 v[20:23], v[158:161], v[224:227], v[20:23]
	v_mfma_f32_16x16x32_bf16 v[12:15], v[166:169], v[224:227], v[12:15]
	v_mfma_f32_16x16x32_bf16 v[60:63], v[162:165], v[204:207], v[60:63]
	v_mfma_f32_16x16x32_bf16 v[56:59], v[170:173], v[204:207], v[56:59]
	v_mfma_f32_16x16x32_bf16 v[52:55], v[162:165], v[212:215], v[52:55]
	v_mfma_f32_16x16x32_bf16 v[44:47], v[170:173], v[212:215], v[44:47]
	v_mfma_f32_16x16x32_bf16 v[36:39], v[162:165], v[220:223], v[36:39]
	v_mfma_f32_16x16x32_bf16 v[28:31], v[170:173], v[220:223], v[28:31]
	v_mfma_f32_16x16x32_bf16 v[20:23], v[162:165], v[228:231], v[20:23]
	v_mfma_f32_16x16x32_bf16 v[12:15], v[170:173], v[228:231], v[12:15]
	v_mfma_f32_16x16x32_bf16 v[48:51], v[174:177], v[200:203], v[48:51]
	v_mfma_f32_16x16x32_bf16 v[40:43], v[192:195], v[200:203], v[40:43]
	v_mfma_f32_16x16x32_bf16 v[32:35], v[174:177], v[208:211], v[32:35]
	v_mfma_f32_16x16x32_bf16 v[24:27], v[192:195], v[208:211], v[24:27]
	v_mfma_f32_16x16x32_bf16 v[16:19], v[174:177], v[216:219], v[16:19]
	v_mfma_f32_16x16x32_bf16 v[8:11], v[192:195], v[216:219], v[8:11]
	v_mfma_f32_16x16x32_bf16 v[4:7], v[174:177], v[224:227], v[4:7]
	v_mfma_f32_16x16x32_bf16 v[0:3], v[192:195], v[224:227], v[0:3]
	v_mfma_f32_16x16x32_bf16 v[48:51], v[178:181], v[204:207], v[48:51]
	v_mfma_f32_16x16x32_bf16 v[40:43], v[196:199], v[204:207], v[40:43]
	v_mfma_f32_16x16x32_bf16 v[32:35], v[178:181], v[212:215], v[32:35]
	v_mfma_f32_16x16x32_bf16 v[24:27], v[196:199], v[212:215], v[24:27]
	v_mfma_f32_16x16x32_bf16 v[16:19], v[178:181], v[220:223], v[16:19]
	v_mfma_f32_16x16x32_bf16 v[8:11], v[196:199], v[220:223], v[8:11]
	v_mfma_f32_16x16x32_bf16 v[4:7], v[178:181], v[228:231], v[4:7]
	v_mfma_f32_16x16x32_bf16 v[0:3], v[196:199], v[228:231], v[0:3]
	s_barrier
	s_add_i32 s52, 0, 0x18000
	s_add_i32 s53, 0, 0x1c000
	v_add_u32_e32 v170, s52, v142
	v_add_u32_e32 v196, s53, v142
	ds_read_b128 v[158:161], v170
	ds_read_b128 v[162:165], v170 offset:1024
	ds_read_b128 v[166:169], v170 offset:2048
	ds_read_b128 v[170:173], v170 offset:3072
	ds_read_b128 v[174:177], v196
	ds_read_b128 v[178:181], v196 offset:1024
	ds_read_b128 v[192:195], v196 offset:2048
	ds_read_b128 v[196:199], v196 offset:3072
	s_add_u32 s36, s36, 0x80000
	s_addc_u32 s37, s37, 0
	s_mov_b32 m0, s9
	v_lshl_add_u64 v[242:243], s[36:37], 0, v[132:133]
	ds_read_b128 v[200:203], v143 offset:32768
	ds_read_b128 v[204:207], v143 offset:33792
	ds_read_b128 v[208:211], v143 offset:34816
	ds_read_b128 v[212:215], v143 offset:35840
	ds_read_b128 v[216:219], v143 offset:36864
	ds_read_b128 v[220:223], v143 offset:37888
	ds_read_b128 v[224:227], v143 offset:38912
	ds_read_b128 v[228:231], v143 offset:39936
	global_load_lds_dwordx4 v[242:243], off
	v_lshl_add_u64 v[242:243], s[36:37], 0, v[130:131]
	s_mov_b32 m0, s10
	s_nop 0
	global_load_lds_dwordx4 v[242:243], off
	s_waitcnt vmcnt(8)
	s_waitcnt lgkmcnt(0)
	s_barrier
	v_mfma_f32_16x16x32_bf16 v[124:127], v[158:161], v[200:203], v[124:127]
	v_mfma_f32_16x16x32_bf16 v[120:123], v[166:169], v[200:203], v[120:123]
	v_mfma_f32_16x16x32_bf16 v[116:119], v[158:161], v[208:211], v[116:119]
	v_mfma_f32_16x16x32_bf16 v[108:111], v[166:169], v[208:211], v[108:111]
	v_mfma_f32_16x16x32_bf16 v[100:103], v[158:161], v[216:219], v[100:103]
	v_mfma_f32_16x16x32_bf16 v[92:95], v[166:169], v[216:219], v[92:95]
	v_mfma_f32_16x16x32_bf16 v[84:87], v[158:161], v[224:227], v[84:87]
	v_mfma_f32_16x16x32_bf16 v[76:79], v[166:169], v[224:227], v[76:79]
	v_mfma_f32_16x16x32_bf16 v[124:127], v[162:165], v[204:207], v[124:127]
	v_mfma_f32_16x16x32_bf16 v[120:123], v[170:173], v[204:207], v[120:123]
	v_mfma_f32_16x16x32_bf16 v[116:119], v[162:165], v[212:215], v[116:119]
	v_mfma_f32_16x16x32_bf16 v[108:111], v[170:173], v[212:215], v[108:111]
	v_mfma_f32_16x16x32_bf16 v[100:103], v[162:165], v[220:223], v[100:103]
	v_mfma_f32_16x16x32_bf16 v[92:95], v[170:173], v[220:223], v[92:95]
	v_mfma_f32_16x16x32_bf16 v[84:87], v[162:165], v[228:231], v[84:87]
	v_mfma_f32_16x16x32_bf16 v[76:79], v[170:173], v[228:231], v[76:79]
	v_mfma_f32_16x16x32_bf16 v[112:115], v[174:177], v[200:203], v[112:115]
	v_mfma_f32_16x16x32_bf16 v[104:107], v[192:195], v[200:203], v[104:107]
	v_mfma_f32_16x16x32_bf16 v[96:99], v[174:177], v[208:211], v[96:99]
	v_mfma_f32_16x16x32_bf16 v[88:91], v[192:195], v[208:211], v[88:91]
	v_mfma_f32_16x16x32_bf16 v[80:83], v[174:177], v[216:219], v[80:83]
	v_mfma_f32_16x16x32_bf16 v[72:75], v[192:195], v[216:219], v[72:75]
	v_mfma_f32_16x16x32_bf16 v[68:71], v[174:177], v[224:227], v[68:71]
	v_mfma_f32_16x16x32_bf16 v[64:67], v[192:195], v[224:227], v[64:67]
	v_mfma_f32_16x16x32_bf16 v[112:115], v[178:181], v[204:207], v[112:115]
	v_mfma_f32_16x16x32_bf16 v[104:107], v[196:199], v[204:207], v[104:107]
	v_mfma_f32_16x16x32_bf16 v[96:99], v[178:181], v[212:215], v[96:99]
	v_mfma_f32_16x16x32_bf16 v[88:91], v[196:199], v[212:215], v[88:91]
	v_mfma_f32_16x16x32_bf16 v[80:83], v[178:181], v[220:223], v[80:83]
	v_mfma_f32_16x16x32_bf16 v[72:75], v[196:199], v[220:223], v[72:75]
	v_mfma_f32_16x16x32_bf16 v[68:71], v[178:181], v[228:231], v[68:71]
	v_mfma_f32_16x16x32_bf16 v[64:67], v[196:199], v[228:231], v[64:67]
	s_barrier
; #define PG8_STAGE(bufoff, gbase, voff) do { _Pragma("unroll") for (int _i = 0; _i < 2; ++_i) \
;         __builtin_amdgcn_global_load_lds((const unsigned*)((const char*)(gbase) + (voff)[_i]), (LAS unsigned*)(lds + (bufoff) + ldsw + _i * 8192), 16, 0, 0); } while (0)
; #define PG8_LDA(dst, b, h) do { _Pragma("unroll") for (int m = 0; m < 4; ++m) _Pragma("unroll") for (int k = 0; k < 2; ++k) dst[m][k] = *(const LAS bf16x8*)(lds + PG8_SA(b, h) + aoff + m * 2048 + k * 1024); } while (0)
; #define PG8_MMA(ai, bj, At, Bt) do { __builtin_amdgcn_s_setprio(1); _Pragma("unroll") for (int m = 0; m < 4; ++m) _Pragma("unroll") for (int n = 0; n < 2; ++n) _Pragma("unroll") for (int k = 0; k < 2; ++k) \
;         acc[ai][bj][m][n] = __builtin_amdgcn_mfma_f32_16x16x32_bf16(Bt[n][k], At[m][k], acc[ai][bj][m][n], 0, 0, 0); __builtin_amdgcn_s_setprio(0); } while (0)
; #define PG8_WAIT_V(n) asm volatile("s_waitcnt vmcnt(" #n ")" ::: "memory")
; #define PG8_WAIT_L(n) asm volatile("s_waitcnt lgkmcnt(" #n ")" ::: "memory")
; #define PG8_BAR __builtin_amdgcn_s_barrier()
; #define PG8_SCHED __builtin_amdgcn_sched_barrier(0)
; template <class Epi, class Map>
; __device__ __forceinline__ void gemm_phase(LAS unsigned char* lds, const Gemm g, const Sched<Map>& S, const Epi& E) {
;     ...
;             PG8_LDA(At, 1, 1); PG8_STAGE(PG8_SB(1, 0), b3, voffB); PG8_STAGE(PG8_SB(1, 1), b3 + hstepB, voffB); PG8_STAGE(PG8_SA(1, 0), a3, voffA);
;             PG8_WAIT_V(8); PG8_WAIT_L(0); PG8_BAR; PG8_MMA(1, 0, At, B0); PG8_MMA(1, 1, At, B1); PG8_BAR; PG8_SCHED;
;         }
;         if (wr == 0) PG8_BAR;
	s_add_i32 s36, s52, s6
	v_lshl_add_u64 v[138:139], v[138:139], 0, s[82:83]
	s_mov_b32 m0, s36
	ds_read_b128 v[200:203], v143 offset:49152
	ds_read_b128 v[204:207], v143 offset:50176
	ds_read_b128 v[208:211], v143 offset:51200
	ds_read_b128 v[212:215], v143 offset:52224
	ds_read_b128 v[216:219], v143 offset:53248
	ds_read_b128 v[220:223], v143 offset:54272
	ds_read_b128 v[224:227], v143 offset:55296
	ds_read_b128 v[228:231], v143 offset:56320
	global_load_lds_dwordx4 v[138:139], off
	v_lshl_add_u64 v[138:139], v[232:233], 0, s[82:83]
	s_add_i32 m0, s36, 0x2000
	s_add_i32 s36, s53, s6
	global_load_lds_dwordx4 v[138:139], off
	v_lshl_add_u64 v[138:139], v[234:235], 0, s[82:83]
	s_mov_b32 m0, s36
	s_nop 0
	global_load_lds_dwordx4 v[138:139], off
	v_lshl_add_u64 v[138:139], v[236:237], 0, s[82:83]
	s_add_i32 m0, s36, 0x2000
	s_nop 0
	global_load_lds_dwordx4 v[138:139], off
	v_lshl_add_u64 v[138:139], v[238:239], 0, s[82:83]
	s_mov_b32 m0, s15
	s_nop 0
	global_load_lds_dwordx4 v[138:139], off
	v_lshl_add_u64 v[138:139], v[240:241], 0, s[82:83]
	s_mov_b32 m0, s33
	s_nop 0
	global_load_lds_dwordx4 v[138:139], off
	s_waitcnt vmcnt(8)
	s_waitcnt lgkmcnt(0)
	s_barrier
	v_mfma_f32_16x16x32_bf16 v[60:63], v[158:161], v[200:203], v[60:63]
	v_mfma_f32_16x16x32_bf16 v[56:59], v[166:169], v[200:203], v[56:59]
	v_mfma_f32_16x16x32_bf16 v[52:55], v[158:161], v[208:211], v[52:55]
	v_mfma_f32_16x16x32_bf16 v[44:47], v[166:169], v[208:211], v[44:47]
	v_mfma_f32_16x16x32_bf16 v[36:39], v[158:161], v[216:219], v[36:39]
	v_mfma_f32_16x16x32_bf16 v[28:31], v[166:169], v[216:219], v[28:31]
	v_mfma_f32_16x16x32_bf16 v[20:23], v[158:161], v[224:227], v[20:23]
	v_mfma_f32_16x16x32_bf16 v[12:15], v[166:169], v[224:227], v[12:15]
	v_mfma_f32_16x16x32_bf16 v[60:63], v[162:165], v[204:207], v[60:63]
	v_mfma_f32_16x16x32_bf16 v[56:59], v[170:173], v[204:207], v[56:59]
	v_mfma_f32_16x16x32_bf16 v[52:55], v[162:165], v[212:215], v[52:55]
	v_mfma_f32_16x16x32_bf16 v[44:47], v[170:173], v[212:215], v[44:47]
	v_mfma_f32_16x16x32_bf16 v[36:39], v[162:165], v[220:223], v[36:39]
	v_mfma_f32_16x16x32_bf16 v[28:31], v[170:173], v[220:223], v[28:31]
	v_mfma_f32_16x16x32_bf16 v[20:23], v[162:165], v[228:231], v[20:23]
	v_mfma_f32_16x16x32_bf16 v[12:15], v[170:173], v[228:231], v[12:15]
	v_mfma_f32_16x16x32_bf16 v[48:51], v[174:177], v[200:203], v[48:51]
	v_mfma_f32_16x16x32_bf16 v[40:43], v[192:195], v[200:203], v[40:43]
	v_mfma_f32_16x16x32_bf16 v[32:35], v[174:177], v[208:211], v[32:35]
	v_mfma_f32_16x16x32_bf16 v[24:27], v[192:195], v[208:211], v[24:27]
	v_mfma_f32_16x16x32_bf16 v[16:19], v[174:177], v[216:219], v[16:19]
	v_mfma_f32_16x16x32_bf16 v[8:11], v[192:195], v[216:219], v[8:11]
	v_mfma_f32_16x16x32_bf16 v[4:7], v[174:177], v[224:227], v[4:7]
	v_mfma_f32_16x16x32_bf16 v[0:3], v[192:195], v[224:227], v[0:3]
	v_mfma_f32_16x16x32_bf16 v[48:51], v[178:181], v[204:207], v[48:51]
	v_mfma_f32_16x16x32_bf16 v[40:43], v[196:199], v[204:207], v[40:43]
	v_mfma_f32_16x16x32_bf16 v[32:35], v[178:181], v[212:215], v[32:35]
	v_mfma_f32_16x16x32_bf16 v[24:27], v[196:199], v[212:215], v[24:27]
	v_mfma_f32_16x16x32_bf16 v[16:19], v[178:181], v[220:223], v[16:19]
	v_mfma_f32_16x16x32_bf16 v[8:11], v[196:199], v[220:223], v[8:11]
	v_mfma_f32_16x16x32_bf16 v[4:7], v[178:181], v[228:231], v[4:7]
	v_mfma_f32_16x16x32_bf16 v[0:3], v[196:199], v[228:231], v[0:3]
	s_barrier
	s_add_i32 s51, s51, 2
	s_add_u32 s34, s34, 0x100
	s_addc_u32 s35, s35, 0
	s_add_u32 s49, s49, 0x100
	s_addc_u32 s50, s50, 0
	s_cmp_gt_u32 s51, 29
	s_cbranch_scc0 .LBB0_261
	s_and_b64 vcc, exec, s[20:21]
	s_cbranch_vccz .LBB0_264
	s_barrier

; #define PG8_STAGE(bufoff, gbase, voff) do { _Pragma("unroll") for (int _i = 0; _i < 2; ++_i) \
;         __builtin_amdgcn_global_load_lds((const unsigned*)((const char*)(gbase) + (voff)[_i]), (LAS unsigned*)(lds + (bufoff) + ldsw + _i * 8192), 16, 0, 0); } while (0)
; #define PG8_LDA(dst, b, h) do { _Pragma("unroll") for (int m = 0; m < 4; ++m) _Pragma("unroll") for (int k = 0; k < 2; ++k) dst[m][k] = *(const LAS bf16x8*)(lds + PG8_SA(b, h) + aoff + m * 2048 + k * 1024); } while (0)
; #define PG8_LDB(dst, b, h) do { _Pragma("unroll") for (int n = 0; n < 2; ++n) _Pragma("unroll") for (int k = 0; k < 2; ++k) dst[n][k] = *(const LAS bf16x8*)(lds + PG8_SB(b, h) + boff + n * 2048 + k * 1024); } while (0)
; #define PG8_MMA(ai, bj, At, Bt) do { __builtin_amdgcn_s_setprio(1); _Pragma("unroll") for (int m = 0; m < 4; ++m) _Pragma("unroll") for (int n = 0; n < 2; ++n) _Pragma("unroll") for (int k = 0; k < 2; ++k) \
;         acc[ai][bj][m][n] = __builtin_amdgcn_mfma_f32_16x16x32_bf16(Bt[n][k], At[m][k], acc[ai][bj][m][n], 0, 0, 0); __builtin_amdgcn_s_setprio(0); } while (0)
; #define PG8_WAIT_V(n) asm volatile("s_waitcnt vmcnt(" #n ")" ::: "memory")
; #define PG8_WAIT_L(n) asm volatile("s_waitcnt lgkmcnt(" #n ")" ::: "memory")
; #define PG8_BAR __builtin_amdgcn_s_barrier()
; #define PG8_SCHED __builtin_amdgcn_sched_barrier(0)
; template <class Epi, class Map>
; __device__ __forceinline__ void gemm_phase(LAS unsigned char* lds, const Gemm g, const Sched<Map>& S, const Epi& E) {
;     ...
;         for (int t = 0; t < nt; t += 2) {
;             const bool last = (t == nt - 2);
;             const char* a1 = cA + (size_t)(t + 1) * kstep;
;             const char* a2 = last ? nA : cA + (size_t)(t + 2) * kstep; const char* b2 = last ? nB : cB + (size_t)(t + 2) * kstep;
;             const char* a3 = a2 + kstep; const char* b3 = b2 + kstep;
;             PG8_LDB(B0, 0, 0); PG8_LDB(B1, 0, 1); PG8_SCHED; PG8_LDA(At, 0, 0); PG8_STAGE(PG8_SA(1, 1), a1 + hstepA, voffA);
;             PG8_WAIT_V(8); PG8_WAIT_L(0); PG8_BAR; PG8_MMA(0, 0, At, B0); PG8_MMA(0, 1, At, B1); PG8_BAR; PG8_SCHED;
;             PG8_LDA(At, 0, 1); PG8_STAGE(PG8_SB(0, 0), b2, voffB); PG8_STAGE(PG8_SB(0, 1), b2 + hstepB, voffB); PG8_STAGE(PG8_SA(0, 0), a2, voffA);
.LBB0_405:
	s_add_u32 s30, s28, 0xfff80080
	s_addc_u32 s31, s29, -1
	s_add_i32 s47, 0, 0x10000
	s_cmp_eq_u32 s46, 28
	s_cselect_b32 s35, s40, s31
	s_cselect_b32 s34, s41, s30
	s_cselect_b32 s31, s42, s45
	s_cselect_b32 s30, s43, s44
	s_add_i32 s50, 0, 0x14000
	v_add_u32_e32 v108, s47, v173
	v_add_u32_e32 v170, s50, v173
	ds_read_b128 v[64:67], v108
	ds_read_b128 v[68:71], v108 offset:1024
	ds_read_b128 v[72:75], v108 offset:2048
	ds_read_b128 v[108:111], v108 offset:3072
	ds_read_b128 v[166:169], v170
	ds_read_b128 v[176:179], v170 offset:1024
	ds_read_b128 v[192:195], v170 offset:2048
	ds_read_b128 v[196:199], v170 offset:3072
	v_lshl_add_u64 v[170:171], s[28:29], 0, v[162:163]
	s_add_i32 m0, s1, 0xc000
	ds_read_b128 v[200:203], v174
	ds_read_b128 v[204:207], v174 offset:1024
	ds_read_b128 v[208:211], v174 offset:2048
	ds_read_b128 v[212:215], v174 offset:3072
	ds_read_b128 v[216:219], v174 offset:4096
	ds_read_b128 v[220:223], v174 offset:5120
	ds_read_b128 v[224:227], v174 offset:6144
	ds_read_b128 v[228:231], v174 offset:7168
	global_load_lds_dwordx4 v[170:171], off
	v_lshl_add_u64 v[170:171], s[28:29], 0, v[164:165]
	s_add_i32 m0, s1, 0xe000
	s_nop 0
	global_load_lds_dwordx4 v[170:171], off
	s_waitcnt vmcnt(8)
	s_waitcnt lgkmcnt(0)
	s_barrier
	v_mfma_f32_16x16x32_bf16 v[140:143], v[64:67], v[200:203], v[140:143]
	v_mfma_f32_16x16x32_bf16 v[136:139], v[72:75], v[200:203], v[136:139]
	v_mfma_f32_16x16x32_bf16 v[132:135], v[64:67], v[208:211], v[132:135]
	v_mfma_f32_16x16x32_bf16 v[128:131], v[72:75], v[208:211], v[128:131]
	v_mfma_f32_16x16x32_bf16 v[104:107], v[64:67], v[216:219], v[104:107]
	v_mfma_f32_16x16x32_bf16 v[100:103], v[72:75], v[216:219], v[100:103]
	v_mfma_f32_16x16x32_bf16 v[96:99], v[64:67], v[224:227], v[96:99]
	v_mfma_f32_16x16x32_bf16 v[92:95], v[72:75], v[224:227], v[92:95]
	v_mfma_f32_16x16x32_bf16 v[140:143], v[68:71], v[204:207], v[140:143]
	v_mfma_f32_16x16x32_bf16 v[136:139], v[108:111], v[204:207], v[136:139]
	v_mfma_f32_16x16x32_bf16 v[132:135], v[68:71], v[212:215], v[132:135]
	v_mfma_f32_16x16x32_bf16 v[128:131], v[108:111], v[212:215], v[128:131]
	v_mfma_f32_16x16x32_bf16 v[104:107], v[68:71], v[220:223], v[104:107]
	v_mfma_f32_16x16x32_bf16 v[100:103], v[108:111], v[220:223], v[100:103]
	v_mfma_f32_16x16x32_bf16 v[96:99], v[68:71], v[228:231], v[96:99]
	v_mfma_f32_16x16x32_bf16 v[92:95], v[108:111], v[228:231], v[92:95]
	v_mfma_f32_16x16x32_bf16 v[124:127], v[166:169], v[200:203], v[124:127]
	v_mfma_f32_16x16x32_bf16 v[120:123], v[192:195], v[200:203], v[120:123]
	v_mfma_f32_16x16x32_bf16 v[116:119], v[166:169], v[208:211], v[116:119]
	v_mfma_f32_16x16x32_bf16 v[112:115], v[192:195], v[208:211], v[112:115]
	v_mfma_f32_16x16x32_bf16 v[88:91], v[166:169], v[216:219], v[88:91]
	v_mfma_f32_16x16x32_bf16 v[84:87], v[192:195], v[216:219], v[84:87]
	v_mfma_f32_16x16x32_bf16 v[80:83], v[166:169], v[224:227], v[80:83]
	v_mfma_f32_16x16x32_bf16 v[76:79], v[192:195], v[224:227], v[76:79]
	v_mfma_f32_16x16x32_bf16 v[124:127], v[176:179], v[204:207], v[124:127]
	v_mfma_f32_16x16x32_bf16 v[120:123], v[196:199], v[204:207], v[120:123]
	v_mfma_f32_16x16x32_bf16 v[116:119], v[176:179], v[212:215], v[116:119]
	v_mfma_f32_16x16x32_bf16 v[112:115], v[196:199], v[212:215], v[112:115]
	v_mfma_f32_16x16x32_bf16 v[88:91], v[176:179], v[220:223], v[88:91]
	v_mfma_f32_16x16x32_bf16 v[84:87], v[196:199], v[220:223], v[84:87]
	v_mfma_f32_16x16x32_bf16 v[80:83], v[176:179], v[228:231], v[80:83]
	v_mfma_f32_16x16x32_bf16 v[76:79], v[196:199], v[228:231], v[76:79]
	s_barrier
	s_add_i32 s47, s47, s0
	v_lshl_add_u64 v[170:171], s[30:31], 0, v[144:145]
	s_mov_b32 m0, s47
	ds_read_b128 v[200:203], v174 offset:16384
	ds_read_b128 v[204:207], v174 offset:17408
	ds_read_b128 v[208:211], v174 offset:18432
	ds_read_b128 v[212:215], v174 offset:19456
	ds_read_b128 v[216:219], v174 offset:20480
	ds_read_b128 v[220:223], v174 offset:21504
	ds_read_b128 v[224:227], v174 offset:22528
	ds_read_b128 v[228:231], v174 offset:23552
	global_load_lds_dwordx4 v[170:171], off
	s_add_i32 m0, s47, 0x2000
	s_add_u32 s48, s30, 0x80000
	v_lshl_add_u64 v[180:181], s[30:31], 0, v[160:161]
	s_addc_u32 s49, s31, 0
	s_add_i32 s47, s50, s0
	global_load_lds_dwordx4 v[180:181], off
	v_lshl_add_u64 v[232:233], s[48:49], 0, v[144:145]
	s_mov_b32 m0, s47
	v_lshl_add_u64 v[234:235], s[34:35], 0, v[160:161]
	global_load_lds_dwordx4 v[232:233], off
	v_lshl_add_u64 v[232:233], s[48:49], 0, v[160:161]
	s_add_i32 m0, s47, 0x2000
	s_nop 0
	global_load_lds_dwordx4 v[232:233], off
	v_lshl_add_u64 v[232:233], s[34:35], 0, v[144:145]
	s_mov_b32 m0, s1
	s_nop 0
	global_load_lds_dwordx4 v[232:233], off
	s_mov_b32 m0, s2
	s_nop 0
	global_load_lds_dwordx4 v[234:235], off
	s_waitcnt vmcnt(8)
	s_waitcnt lgkmcnt(0)
	s_barrier
; #define PG8_STAGE(bufoff, gbase, voff) do { _Pragma("unroll") for (int _i = 0; _i < 2; ++_i) \
;         __builtin_amdgcn_global_load_lds((const unsigned*)((const char*)(gbase) + (voff)[_i]), (LAS unsigned*)(lds + (bufoff) + ldsw + _i * 8192), 16, 0, 0); } while (0)
; #define PG8_LDA(dst, b, h) do { _Pragma("unroll") for (int m = 0; m < 4; ++m) _Pragma("unroll") for (int k = 0; k < 2; ++k) dst[m][k] = *(const LAS bf16x8*)(lds + PG8_SA(b, h) + aoff + m * 2048 + k * 1024); } while (0)
; #define PG8_LDB(dst, b, h) do { _Pragma("unroll") for (int n = 0; n < 2; ++n) _Pragma("unroll") for (int k = 0; k < 2; ++k) dst[n][k] = *(const LAS bf16x8*)(lds + PG8_SB(b, h) + boff + n * 2048 + k * 1024); } while (0)
; #define PG8_MMA(ai, bj, At, Bt) do { __builtin_amdgcn_s_setprio(1); _Pragma("unroll") for (int m = 0; m < 4; ++m) _Pragma("unroll") for (int n = 0; n < 2; ++n) _Pragma("unroll") for (int k = 0; k < 2; ++k) \
;         acc[ai][bj][m][n] = __builtin_amdgcn_mfma_f32_16x16x32_bf16(Bt[n][k], At[m][k], acc[ai][bj][m][n], 0, 0, 0); __builtin_amdgcn_s_setprio(0); } while (0)
; #define PG8_WAIT_V(n) asm volatile("s_waitcnt vmcnt(" #n ")" ::: "memory")
; #define PG8_WAIT_L(n) asm volatile("s_waitcnt lgkmcnt(" #n ")" ::: "memory")
; #define PG8_BAR __builtin_amdgcn_s_barrier()
; #define PG8_SCHED __builtin_amdgcn_sched_barrier(0)
; template <class Epi, class Map>
; __device__ __forceinline__ void gemm_phase(LAS unsigned char* lds, const Gemm g, const Sched<Map>& S, const Epi& E) {
;     ...
;             PG8_WAIT_V(8); PG8_WAIT_L(0); PG8_BAR; PG8_MMA(1, 0, At, B0); PG8_MMA(1, 1, At, B1); PG8_BAR; PG8_SCHED;
;             PG8_LDB(B0, 1, 0); PG8_LDB(B1, 1, 1); PG8_SCHED; PG8_LDA(At, 1, 0); PG8_STAGE(PG8_SA(0, 1), a2 + hstepA, voffA);
;             PG8_WAIT_V(8); PG8_WAIT_L(0); PG8_BAR; PG8_MMA(0, 0, At, B0); PG8_MMA(0, 1, At, B1); PG8_BAR; PG8_SCHED;
	v_mfma_f32_16x16x32_bf16 v[60:63], v[64:67], v[200:203], v[60:63]
	v_mfma_f32_16x16x32_bf16 v[56:59], v[72:75], v[200:203], v[56:59]
	v_mfma_f32_16x16x32_bf16 v[52:55], v[64:67], v[208:211], v[52:55]
	v_mfma_f32_16x16x32_bf16 v[48:51], v[72:75], v[208:211], v[48:51]
	v_mfma_f32_16x16x32_bf16 v[28:31], v[64:67], v[216:219], v[28:31]
	v_mfma_f32_16x16x32_bf16 v[24:27], v[72:75], v[216:219], v[24:27]
	v_mfma_f32_16x16x32_bf16 v[20:23], v[64:67], v[224:227], v[20:23]
	v_mfma_f32_16x16x32_bf16 v[8:11], v[72:75], v[224:227], v[8:11]
	v_mfma_f32_16x16x32_bf16 v[60:63], v[68:71], v[204:207], v[60:63]
	v_mfma_f32_16x16x32_bf16 v[56:59], v[108:111], v[204:207], v[56:59]
	v_mfma_f32_16x16x32_bf16 v[52:55], v[68:71], v[212:215], v[52:55]
	v_mfma_f32_16x16x32_bf16 v[48:51], v[108:111], v[212:215], v[48:51]
	v_mfma_f32_16x16x32_bf16 v[28:31], v[68:71], v[220:223], v[28:31]
	v_mfma_f32_16x16x32_bf16 v[24:27], v[108:111], v[220:223], v[24:27]
	v_mfma_f32_16x16x32_bf16 v[20:23], v[68:71], v[228:231], v[20:23]
	v_mfma_f32_16x16x32_bf16 v[8:11], v[108:111], v[228:231], v[8:11]
	v_mfma_f32_16x16x32_bf16 v[44:47], v[166:169], v[200:203], v[44:47]
	v_mfma_f32_16x16x32_bf16 v[40:43], v[192:195], v[200:203], v[40:43]
	v_mfma_f32_16x16x32_bf16 v[36:39], v[166:169], v[208:211], v[36:39]
	v_mfma_f32_16x16x32_bf16 v[32:35], v[192:195], v[208:211], v[32:35]
	v_mfma_f32_16x16x32_bf16 v[16:19], v[166:169], v[216:219], v[16:19]
	v_mfma_f32_16x16x32_bf16 v[12:15], v[192:195], v[216:219], v[12:15]
	v_mfma_f32_16x16x32_bf16 v[4:7], v[166:169], v[224:227], v[4:7]
	v_mfma_f32_16x16x32_bf16 v[0:3], v[192:195], v[224:227], v[0:3]
	v_mfma_f32_16x16x32_bf16 v[44:47], v[176:179], v[204:207], v[44:47]
	v_mfma_f32_16x16x32_bf16 v[40:43], v[196:199], v[204:207], v[40:43]
	v_mfma_f32_16x16x32_bf16 v[36:39], v[176:179], v[212:215], v[36:39]
	v_mfma_f32_16x16x32_bf16 v[32:35], v[196:199], v[212:215], v[32:35]
	v_mfma_f32_16x16x32_bf16 v[16:19], v[176:179], v[220:223], v[16:19]
	v_mfma_f32_16x16x32_bf16 v[12:15], v[196:199], v[220:223], v[12:15]
	v_mfma_f32_16x16x32_bf16 v[4:7], v[176:179], v[228:231], v[4:7]
	v_mfma_f32_16x16x32_bf16 v[0:3], v[196:199], v[228:231], v[0:3]
	s_barrier
	s_add_i32 s47, 0, 0x18000
	s_add_i32 s48, 0, 0x1c000
	v_add_u32_e32 v108, s47, v173
	v_add_u32_e32 v175, s48, v173
	ds_read_b128 v[64:67], v108
	ds_read_b128 v[68:71], v108 offset:1024
	ds_read_b128 v[72:75], v108 offset:2048
	ds_read_b128 v[108:111], v108 offset:3072
	ds_read_b128 v[166:169], v175
	ds_read_b128 v[176:179], v175 offset:1024
	ds_read_b128 v[192:195], v175 offset:2048
	ds_read_b128 v[196:199], v175 offset:3072
	s_add_u32 s34, s34, 0x80000
	s_addc_u32 s35, s35, 0
	s_mov_b32 m0, s3
	v_lshl_add_u64 v[236:237], s[34:35], 0, v[144:145]
	ds_read_b128 v[200:203], v174 offset:32768
	ds_read_b128 v[204:207], v174 offset:33792
	ds_read_b128 v[208:211], v174 offset:34816
	ds_read_b128 v[212:215], v174 offset:35840
	ds_read_b128 v[216:219], v174 offset:36864
	ds_read_b128 v[220:223], v174 offset:37888
	ds_read_b128 v[224:227], v174 offset:38912
	ds_read_b128 v[228:231], v174 offset:39936
	global_load_lds_dwordx4 v[236:237], off
	v_lshl_add_u64 v[236:237], s[34:35], 0, v[160:161]
	s_mov_b32 m0, s4
	s_nop 0
	global_load_lds_dwordx4 v[236:237], off
	s_waitcnt vmcnt(8)
	s_waitcnt lgkmcnt(0)
	s_barrier
	v_mfma_f32_16x16x32_bf16 v[140:143], v[64:67], v[200:203], v[140:143]
	v_mfma_f32_16x16x32_bf16 v[136:139], v[72:75], v[200:203], v[136:139]
	v_mfma_f32_16x16x32_bf16 v[132:135], v[64:67], v[208:211], v[132:135]
	v_mfma_f32_16x16x32_bf16 v[128:131], v[72:75], v[208:211], v[128:131]
	v_mfma_f32_16x16x32_bf16 v[104:107], v[64:67], v[216:219], v[104:107]
	v_mfma_f32_16x16x32_bf16 v[100:103], v[72:75], v[216:219], v[100:103]
	v_mfma_f32_16x16x32_bf16 v[96:99], v[64:67], v[224:227], v[96:99]
	v_mfma_f32_16x16x32_bf16 v[92:95], v[72:75], v[224:227], v[92:95]
	v_mfma_f32_16x16x32_bf16 v[140:143], v[68:71], v[204:207], v[140:143]
	v_mfma_f32_16x16x32_bf16 v[136:139], v[108:111], v[204:207], v[136:139]
	v_mfma_f32_16x16x32_bf16 v[132:135], v[68:71], v[212:215], v[132:135]
	v_mfma_f32_16x16x32_bf16 v[128:131], v[108:111], v[212:215], v[128:131]
	v_mfma_f32_16x16x32_bf16 v[104:107], v[68:71], v[220:223], v[104:107]
	v_mfma_f32_16x16x32_bf16 v[100:103], v[108:111], v[220:223], v[100:103]
	v_mfma_f32_16x16x32_bf16 v[96:99], v[68:71], v[228:231], v[96:99]
	v_mfma_f32_16x16x32_bf16 v[92:95], v[108:111], v[228:231], v[92:95]
	v_mfma_f32_16x16x32_bf16 v[124:127], v[166:169], v[200:203], v[124:127]
	v_mfma_f32_16x16x32_bf16 v[120:123], v[192:195], v[200:203], v[120:123]
	v_mfma_f32_16x16x32_bf16 v[116:119], v[166:169], v[208:211], v[116:119]
	v_mfma_f32_16x16x32_bf16 v[112:115], v[192:195], v[208:211], v[112:115]
	v_mfma_f32_16x16x32_bf16 v[88:91], v[166:169], v[216:219], v[88:91]
	v_mfma_f32_16x16x32_bf16 v[84:87], v[192:195], v[216:219], v[84:87]
	v_mfma_f32_16x16x32_bf16 v[80:83], v[166:169], v[224:227], v[80:83]
	v_mfma_f32_16x16x32_bf16 v[76:79], v[192:195], v[224:227], v[76:79]
	v_mfma_f32_16x16x32_bf16 v[124:127], v[176:179], v[204:207], v[124:127]
	v_mfma_f32_16x16x32_bf16 v[120:123], v[196:199], v[204:207], v[120:123]
	v_mfma_f32_16x16x32_bf16 v[116:119], v[176:179], v[212:215], v[116:119]
	v_mfma_f32_16x16x32_bf16 v[112:115], v[196:199], v[212:215], v[112:115]
	v_mfma_f32_16x16x32_bf16 v[88:91], v[176:179], v[220:223], v[88:91]
	v_mfma_f32_16x16x32_bf16 v[84:87], v[196:199], v[220:223], v[84:87]
	v_mfma_f32_16x16x32_bf16 v[80:83], v[176:179], v[228:231], v[80:83]
	v_mfma_f32_16x16x32_bf16 v[76:79], v[196:199], v[228:231], v[76:79]
	s_barrier
; #define PG8_STAGE(bufoff, gbase, voff) do { _Pragma("unroll") for (int _i = 0; _i < 2; ++_i) \
;         __builtin_amdgcn_global_load_lds((const unsigned*)((const char*)(gbase) + (voff)[_i]), (LAS unsigned*)(lds + (bufoff) + ldsw + _i * 8192), 16, 0, 0); } while (0)
; #define PG8_LDA(dst, b, h) do { _Pragma("unroll") for (int m = 0; m < 4; ++m) _Pragma("unroll") for (int k = 0; k < 2; ++k) dst[m][k] = *(const LAS bf16x8*)(lds + PG8_SA(b, h) + aoff + m * 2048 + k * 1024); } while (0)
; #define PG8_MMA(ai, bj, At, Bt) do { __builtin_amdgcn_s_setprio(1); _Pragma("unroll") for (int m = 0; m < 4; ++m) _Pragma("unroll") for (int n = 0; n < 2; ++n) _Pragma("unroll") for (int k = 0; k < 2; ++k) \
;         acc[ai][bj][m][n] = __builtin_amdgcn_mfma_f32_16x16x32_bf16(Bt[n][k], At[m][k], acc[ai][bj][m][n], 0, 0, 0); __builtin_amdgcn_s_setprio(0); } while (0)
; #define PG8_WAIT_V(n) asm volatile("s_waitcnt vmcnt(" #n ")" ::: "memory")
; #define PG8_WAIT_L(n) asm volatile("s_waitcnt lgkmcnt(" #n ")" ::: "memory")
; #define PG8_BAR __builtin_amdgcn_s_barrier()
; #define PG8_SCHED __builtin_amdgcn_sched_barrier(0)
; template <class Epi, class Map>
; __device__ __forceinline__ void gemm_phase(LAS unsigned char* lds, const Gemm g, const Sched<Map>& S, const Epi& E) {
;     ...
;             PG8_LDA(At, 1, 1); PG8_STAGE(PG8_SB(1, 0), b3, voffB); PG8_STAGE(PG8_SB(1, 1), b3 + hstepB, voffB); PG8_STAGE(PG8_SA(1, 0), a3, voffA);
;             PG8_WAIT_V(8); PG8_WAIT_L(0); PG8_BAR; PG8_MMA(1, 0, At, B0); PG8_MMA(1, 1, At, B1); PG8_BAR; PG8_SCHED;
;         }
;         if (wr == 0) PG8_BAR;
	s_add_i32 s34, s47, s0
	v_lshl_add_u64 v[170:171], v[170:171], 0, s[82:83]
	s_mov_b32 m0, s34
	ds_read_b128 v[200:203], v174 offset:49152
	ds_read_b128 v[204:207], v174 offset:50176
	ds_read_b128 v[208:211], v174 offset:51200
	ds_read_b128 v[212:215], v174 offset:52224
	ds_read_b128 v[216:219], v174 offset:53248
	ds_read_b128 v[220:223], v174 offset:54272
	ds_read_b128 v[224:227], v174 offset:55296
	ds_read_b128 v[228:231], v174 offset:56320
	global_load_lds_dwordx4 v[170:171], off
	s_add_i32 m0, s34, 0x2000
	s_add_u32 s30, s30, 0x80080
	v_lshl_add_u64 v[170:171], v[180:181], 0, s[82:83]
	s_addc_u32 s31, s31, 0
	s_add_i32 s34, s48, s0
	global_load_lds_dwordx4 v[170:171], off
	v_lshl_add_u64 v[170:171], s[30:31], 0, v[144:145]
	s_mov_b32 m0, s34
	s_nop 0
	global_load_lds_dwordx4 v[170:171], off
	v_lshl_add_u64 v[170:171], s[30:31], 0, v[160:161]
	s_add_i32 m0, s34, 0x2000
	s_nop 0
	global_load_lds_dwordx4 v[170:171], off
	v_lshl_add_u64 v[170:171], v[232:233], 0, s[82:83]
	s_mov_b32 m0, s10
	s_nop 0
	global_load_lds_dwordx4 v[170:171], off
	v_lshl_add_u64 v[170:171], v[234:235], 0, s[82:83]
	s_mov_b32 m0, s11
	s_nop 0
	global_load_lds_dwordx4 v[170:171], off
	s_waitcnt vmcnt(8)
	s_waitcnt lgkmcnt(0)
	s_barrier
	v_mfma_f32_16x16x32_bf16 v[60:63], v[64:67], v[200:203], v[60:63]
	v_mfma_f32_16x16x32_bf16 v[56:59], v[72:75], v[200:203], v[56:59]
	v_mfma_f32_16x16x32_bf16 v[52:55], v[64:67], v[208:211], v[52:55]
	v_mfma_f32_16x16x32_bf16 v[48:51], v[72:75], v[208:211], v[48:51]
	v_mfma_f32_16x16x32_bf16 v[28:31], v[64:67], v[216:219], v[28:31]
	v_mfma_f32_16x16x32_bf16 v[24:27], v[72:75], v[216:219], v[24:27]
	v_mfma_f32_16x16x32_bf16 v[20:23], v[64:67], v[224:227], v[20:23]
	v_mfma_f32_16x16x32_bf16 v[8:11], v[72:75], v[224:227], v[8:11]
	v_mfma_f32_16x16x32_bf16 v[60:63], v[68:71], v[204:207], v[60:63]
	v_mfma_f32_16x16x32_bf16 v[56:59], v[108:111], v[204:207], v[56:59]
	v_mfma_f32_16x16x32_bf16 v[52:55], v[68:71], v[212:215], v[52:55]
	v_mfma_f32_16x16x32_bf16 v[48:51], v[108:111], v[212:215], v[48:51]
	v_mfma_f32_16x16x32_bf16 v[28:31], v[68:71], v[220:223], v[28:31]
	v_mfma_f32_16x16x32_bf16 v[24:27], v[108:111], v[220:223], v[24:27]
	v_mfma_f32_16x16x32_bf16 v[20:23], v[68:71], v[228:231], v[20:23]
	v_mfma_f32_16x16x32_bf16 v[8:11], v[108:111], v[228:231], v[8:11]
	v_mfma_f32_16x16x32_bf16 v[44:47], v[166:169], v[200:203], v[44:47]
	v_mfma_f32_16x16x32_bf16 v[40:43], v[192:195], v[200:203], v[40:43]
	v_mfma_f32_16x16x32_bf16 v[36:39], v[166:169], v[208:211], v[36:39]
	v_mfma_f32_16x16x32_bf16 v[32:35], v[192:195], v[208:211], v[32:35]
	v_mfma_f32_16x16x32_bf16 v[16:19], v[166:169], v[216:219], v[16:19]
	v_mfma_f32_16x16x32_bf16 v[12:15], v[192:195], v[216:219], v[12:15]
	v_mfma_f32_16x16x32_bf16 v[4:7], v[166:169], v[224:227], v[4:7]
	v_mfma_f32_16x16x32_bf16 v[0:3], v[192:195], v[224:227], v[0:3]
	v_mfma_f32_16x16x32_bf16 v[44:47], v[176:179], v[204:207], v[44:47]
	v_mfma_f32_16x16x32_bf16 v[40:43], v[196:199], v[204:207], v[40:43]
	v_mfma_f32_16x16x32_bf16 v[36:39], v[176:179], v[212:215], v[36:39]
	v_mfma_f32_16x16x32_bf16 v[32:35], v[196:199], v[212:215], v[32:35]
	v_mfma_f32_16x16x32_bf16 v[16:19], v[176:179], v[220:223], v[16:19]
	v_mfma_f32_16x16x32_bf16 v[12:15], v[196:199], v[220:223], v[12:15]
	v_mfma_f32_16x16x32_bf16 v[4:7], v[176:179], v[228:231], v[4:7]
	v_mfma_f32_16x16x32_bf16 v[0:3], v[196:199], v[228:231], v[0:3]
	s_barrier
	s_add_i32 s46, s46, 2
	s_add_u32 s28, s28, 0x100
	s_addc_u32 s29, s29, 0
	s_add_u32 s44, s44, 0x100
	s_addc_u32 s45, s45, 0
	s_cmp_gt_u32 s46, 29
	s_cbranch_scc0 .LBB0_405
	s_and_b64 vcc, exec, s[18:19]
	s_cbranch_vccz .LBB0_408
	s_barrier

; #define PG8_STAGE(bufoff, gbase, voff) do { _Pragma("unroll") for (int _i = 0; _i < 2; ++_i) \
;         __builtin_amdgcn_global_load_lds((const unsigned*)((const char*)(gbase) + (voff)[_i]), (LAS unsigned*)(lds + (bufoff) + ldsw + _i * 8192), 16, 0, 0); } while (0)
; #define PG8_LDA(dst, b, h) do { _Pragma("unroll") for (int m = 0; m < 4; ++m) _Pragma("unroll") for (int k = 0; k < 2; ++k) dst[m][k] = *(const LAS bf16x8*)(lds + PG8_SA(b, h) + aoff + m * 2048 + k * 1024); } while (0)
; #define PG8_LDB(dst, b, h) do { _Pragma("unroll") for (int n = 0; n < 2; ++n) _Pragma("unroll") for (int k = 0; k < 2; ++k) dst[n][k] = *(const LAS bf16x8*)(lds + PG8_SB(b, h) + boff + n * 2048 + k * 1024); } while (0)
; #define PG8_MMA(ai, bj, At, Bt) do { __builtin_amdgcn_s_setprio(1); _Pragma("unroll") for (int m = 0; m < 4; ++m) _Pragma("unroll") for (int n = 0; n < 2; ++n) _Pragma("unroll") for (int k = 0; k < 2; ++k) \
;         acc[ai][bj][m][n] = __builtin_amdgcn_mfma_f32_16x16x32_bf16(Bt[n][k], At[m][k], acc[ai][bj][m][n], 0, 0, 0); __builtin_amdgcn_s_setprio(0); } while (0)
; #define PG8_WAIT_V(n) asm volatile("s_waitcnt vmcnt(" #n ")" ::: "memory")
; #define PG8_WAIT_L(n) asm volatile("s_waitcnt lgkmcnt(" #n ")" ::: "memory")
; #define PG8_BAR __builtin_amdgcn_s_barrier()
; #define PG8_SCHED __builtin_amdgcn_sched_barrier(0)
; template <class Epi, class Map>
; __device__ __forceinline__ void gemm_phase(LAS unsigned char* lds, const Gemm g, const Sched<Map>& S, const Epi& E) {
;     ...
;         for (int t = 0; t < nt; t += 2) {
;             const bool last = (t == nt - 2);
;             const char* a1 = cA + (size_t)(t + 1) * kstep;
;             const char* a2 = last ? nA : cA + (size_t)(t + 2) * kstep; const char* b2 = last ? nB : cB + (size_t)(t + 2) * kstep;
;             const char* a3 = a2 + kstep; const char* b3 = b2 + kstep;
;             PG8_LDB(B0, 0, 0); PG8_LDB(B1, 0, 1); PG8_SCHED; PG8_LDA(At, 0, 0); PG8_STAGE(PG8_SA(1, 1), a1 + hstepA, voffA);
;             PG8_WAIT_V(8); PG8_WAIT_L(0); PG8_BAR; PG8_MMA(0, 0, At, B0); PG8_MMA(0, 1, At, B1); PG8_BAR; PG8_SCHED;
;             PG8_LDA(At, 0, 1); PG8_STAGE(PG8_SB(0, 0), b2, voffB); PG8_STAGE(PG8_SB(0, 1), b2 + hstepB, voffB); PG8_STAGE(PG8_SA(0, 0), a2, voffA);
.LBB0_552:
	s_add_u32 s14, s24, 0xfff80080
	s_addc_u32 s15, s25, -1
	s_add_i32 s19, 0, 0x10000
	s_cmp_eq_u32 s13, 28
	s_cselect_b32 s31, s3, s15
	s_cselect_b32 s30, s8, s14
	v_add_u32_e32 v142, s19, v168
	s_cselect_b32 s29, s9, s12
	s_cselect_b32 s28, s10, s11
	s_add_i32 s21, 0, 0x14000
	ds_read_b128 v[128:131], v142
	ds_read_b128 v[160:163], v142 offset:1024
	ds_read_b128 v[170:173], v142 offset:2048
	ds_read_b128 v[174:177], v142 offset:3072
	v_add_u32_e32 v142, s21, v168
	ds_read_b128 v[178:181], v142
	ds_read_b128 v[192:195], v142 offset:1024
	ds_read_b128 v[196:199], v142 offset:2048
	ds_read_b128 v[200:203], v142 offset:3072
	v_lshl_add_u64 v[142:143], s[24:25], 0, v[138:139]
	s_add_i32 m0, s35, 0xc000
	ds_read_b128 v[204:207], v169
	ds_read_b128 v[208:211], v169 offset:1024
	ds_read_b128 v[212:215], v169 offset:2048
	ds_read_b128 v[216:219], v169 offset:3072
	ds_read_b128 v[220:223], v169 offset:4096
	ds_read_b128 v[224:227], v169 offset:5120
	ds_read_b128 v[228:231], v169 offset:6144
	ds_read_b128 v[232:235], v169 offset:7168
	global_load_lds_dwordx4 v[142:143], off
	v_lshl_add_u64 v[142:143], s[24:25], 0, v[140:141]
	s_add_i32 m0, s35, 0xe000
	s_nop 0
	global_load_lds_dwordx4 v[142:143], off
	s_waitcnt vmcnt(8)
	s_waitcnt lgkmcnt(0)
	s_barrier
	v_mfma_f32_16x16x32_bf16 v[124:127], v[128:131], v[204:207], v[124:127]
	v_mfma_f32_16x16x32_bf16 v[116:119], v[170:173], v[204:207], v[116:119]
	v_mfma_f32_16x16x32_bf16 v[108:111], v[128:131], v[212:215], v[108:111]
	v_mfma_f32_16x16x32_bf16 v[96:99], v[170:173], v[212:215], v[96:99]
	v_mfma_f32_16x16x32_bf16 v[92:95], v[128:131], v[220:223], v[92:95]
	v_mfma_f32_16x16x32_bf16 v[80:83], v[170:173], v[220:223], v[80:83]
	v_mfma_f32_16x16x32_bf16 v[76:79], v[128:131], v[228:231], v[76:79]
	v_mfma_f32_16x16x32_bf16 v[64:67], v[170:173], v[228:231], v[64:67]
	v_mfma_f32_16x16x32_bf16 v[124:127], v[160:163], v[208:211], v[124:127]
	v_mfma_f32_16x16x32_bf16 v[116:119], v[174:177], v[208:211], v[116:119]
	v_mfma_f32_16x16x32_bf16 v[108:111], v[160:163], v[216:219], v[108:111]
	v_mfma_f32_16x16x32_bf16 v[96:99], v[174:177], v[216:219], v[96:99]
	v_mfma_f32_16x16x32_bf16 v[92:95], v[160:163], v[224:227], v[92:95]
	v_mfma_f32_16x16x32_bf16 v[80:83], v[174:177], v[224:227], v[80:83]
	v_mfma_f32_16x16x32_bf16 v[76:79], v[160:163], v[232:235], v[76:79]
	v_mfma_f32_16x16x32_bf16 v[64:67], v[174:177], v[232:235], v[64:67]
	v_mfma_f32_16x16x32_bf16 v[120:123], v[178:181], v[204:207], v[120:123]
	v_mfma_f32_16x16x32_bf16 v[112:115], v[196:199], v[204:207], v[112:115]
	v_mfma_f32_16x16x32_bf16 v[104:107], v[178:181], v[212:215], v[104:107]
	v_mfma_f32_16x16x32_bf16 v[100:103], v[196:199], v[212:215], v[100:103]
	v_mfma_f32_16x16x32_bf16 v[88:91], v[178:181], v[220:223], v[88:91]
	v_mfma_f32_16x16x32_bf16 v[84:87], v[196:199], v[220:223], v[84:87]
	v_mfma_f32_16x16x32_bf16 v[72:75], v[178:181], v[228:231], v[72:75]
	v_mfma_f32_16x16x32_bf16 v[68:71], v[196:199], v[228:231], v[68:71]
	v_mfma_f32_16x16x32_bf16 v[120:123], v[192:195], v[208:211], v[120:123]
	v_mfma_f32_16x16x32_bf16 v[112:115], v[200:203], v[208:211], v[112:115]
	v_mfma_f32_16x16x32_bf16 v[104:107], v[192:195], v[216:219], v[104:107]
	v_mfma_f32_16x16x32_bf16 v[100:103], v[200:203], v[216:219], v[100:103]
	v_mfma_f32_16x16x32_bf16 v[88:91], v[192:195], v[224:227], v[88:91]
	v_mfma_f32_16x16x32_bf16 v[84:87], v[200:203], v[224:227], v[84:87]
	v_mfma_f32_16x16x32_bf16 v[72:75], v[192:195], v[232:235], v[72:75]
	v_mfma_f32_16x16x32_bf16 v[68:71], v[200:203], v[232:235], v[68:71]
	s_barrier
	s_add_i32 s14, s19, s34
	v_lshl_add_u64 v[142:143], s[28:29], 0, v[144:145]
	s_mov_b32 m0, s14
	ds_read_b128 v[204:207], v169 offset:16384
	ds_read_b128 v[208:211], v169 offset:17408
	ds_read_b128 v[212:215], v169 offset:18432
	ds_read_b128 v[216:219], v169 offset:19456
	ds_read_b128 v[220:223], v169 offset:20480
	ds_read_b128 v[224:227], v169 offset:21504
	ds_read_b128 v[228:231], v169 offset:22528
	ds_read_b128 v[232:235], v169 offset:23552
	global_load_lds_dwordx4 v[142:143], off
	s_add_i32 m0, s14, 0x2000
	s_add_u32 s14, s28, 0x80000
	v_lshl_add_u64 v[164:165], s[28:29], 0, v[136:137]
	s_addc_u32 s15, s29, 0
	s_add_i32 s19, s21, s34
	global_load_lds_dwordx4 v[164:165], off
	v_lshl_add_u64 v[236:237], s[14:15], 0, v[144:145]
	s_mov_b32 m0, s19
	v_lshl_add_u64 v[238:239], s[30:31], 0, v[134:135]
	global_load_lds_dwordx4 v[236:237], off
	v_lshl_add_u64 v[236:237], s[14:15], 0, v[136:137]
	s_add_i32 m0, s19, 0x2000
	s_nop 0
	global_load_lds_dwordx4 v[236:237], off
	v_lshl_add_u64 v[236:237], s[30:31], 0, v[132:133]
	s_mov_b32 m0, s35
	s_nop 0
	global_load_lds_dwordx4 v[236:237], off
	s_mov_b32 m0, s84
	s_nop 0
	global_load_lds_dwordx4 v[238:239], off
	s_waitcnt vmcnt(8)
	s_waitcnt lgkmcnt(0)
	s_barrier
; #define PG8_STAGE(bufoff, gbase, voff) do { _Pragma("unroll") for (int _i = 0; _i < 2; ++_i) \
;         __builtin_amdgcn_global_load_lds((const unsigned*)((const char*)(gbase) + (voff)[_i]), (LAS unsigned*)(lds + (bufoff) + ldsw + _i * 8192), 16, 0, 0); } while (0)
; #define PG8_LDA(dst, b, h) do { _Pragma("unroll") for (int m = 0; m < 4; ++m) _Pragma("unroll") for (int k = 0; k < 2; ++k) dst[m][k] = *(const LAS bf16x8*)(lds + PG8_SA(b, h) + aoff + m * 2048 + k * 1024); } while (0)
; #define PG8_LDB(dst, b, h) do { _Pragma("unroll") for (int n = 0; n < 2; ++n) _Pragma("unroll") for (int k = 0; k < 2; ++k) dst[n][k] = *(const LAS bf16x8*)(lds + PG8_SB(b, h) + boff + n * 2048 + k * 1024); } while (0)
; #define PG8_MMA(ai, bj, At, Bt) do { __builtin_amdgcn_s_setprio(1); _Pragma("unroll") for (int m = 0; m < 4; ++m) _Pragma("unroll") for (int n = 0; n < 2; ++n) _Pragma("unroll") for (int k = 0; k < 2; ++k) \
;         acc[ai][bj][m][n] = __builtin_amdgcn_mfma_f32_16x16x32_bf16(Bt[n][k], At[m][k], acc[ai][bj][m][n], 0, 0, 0); __builtin_amdgcn_s_setprio(0); } while (0)
; #define PG8_WAIT_V(n) asm volatile("s_waitcnt vmcnt(" #n ")" ::: "memory")
; #define PG8_WAIT_L(n) asm volatile("s_waitcnt lgkmcnt(" #n ")" ::: "memory")
; #define PG8_BAR __builtin_amdgcn_s_barrier()
; #define PG8_SCHED __builtin_amdgcn_sched_barrier(0)
; template <class Epi, class Map>
; __device__ __forceinline__ void gemm_phase(LAS unsigned char* lds, const Gemm g, const Sched<Map>& S, const Epi& E) {
;     ...
;             PG8_WAIT_V(8); PG8_WAIT_L(0); PG8_BAR; PG8_MMA(1, 0, At, B0); PG8_MMA(1, 1, At, B1); PG8_BAR; PG8_SCHED;
;             PG8_LDB(B0, 1, 0); PG8_LDB(B1, 1, 1); PG8_SCHED; PG8_LDA(At, 1, 0); PG8_STAGE(PG8_SA(0, 1), a2 + hstepA, voffA);
;             PG8_WAIT_V(8); PG8_WAIT_L(0); PG8_BAR; PG8_MMA(0, 0, At, B0); PG8_MMA(0, 1, At, B1); PG8_BAR; PG8_SCHED;
	v_mfma_f32_16x16x32_bf16 v[60:63], v[128:131], v[204:207], v[60:63]
	v_mfma_f32_16x16x32_bf16 v[48:51], v[170:173], v[204:207], v[48:51]
	v_mfma_f32_16x16x32_bf16 v[44:47], v[128:131], v[212:215], v[44:47]
	v_mfma_f32_16x16x32_bf16 v[32:35], v[170:173], v[212:215], v[32:35]
	v_mfma_f32_16x16x32_bf16 v[28:31], v[128:131], v[220:223], v[28:31]
	v_mfma_f32_16x16x32_bf16 v[16:19], v[170:173], v[220:223], v[16:19]
	v_mfma_f32_16x16x32_bf16 v[12:15], v[128:131], v[228:231], v[12:15]
	v_mfma_f32_16x16x32_bf16 v[0:3], v[170:173], v[228:231], v[0:3]
	v_mfma_f32_16x16x32_bf16 v[60:63], v[160:163], v[208:211], v[60:63]
	v_mfma_f32_16x16x32_bf16 v[48:51], v[174:177], v[208:211], v[48:51]
	v_mfma_f32_16x16x32_bf16 v[44:47], v[160:163], v[216:219], v[44:47]
	v_mfma_f32_16x16x32_bf16 v[32:35], v[174:177], v[216:219], v[32:35]
	v_mfma_f32_16x16x32_bf16 v[28:31], v[160:163], v[224:227], v[28:31]
	v_mfma_f32_16x16x32_bf16 v[16:19], v[174:177], v[224:227], v[16:19]
	v_mfma_f32_16x16x32_bf16 v[12:15], v[160:163], v[232:235], v[12:15]
	v_mfma_f32_16x16x32_bf16 v[0:3], v[174:177], v[232:235], v[0:3]
	v_mfma_f32_16x16x32_bf16 v[56:59], v[178:181], v[204:207], v[56:59]
	v_mfma_f32_16x16x32_bf16 v[52:55], v[196:199], v[204:207], v[52:55]
	v_mfma_f32_16x16x32_bf16 v[40:43], v[178:181], v[212:215], v[40:43]
	v_mfma_f32_16x16x32_bf16 v[36:39], v[196:199], v[212:215], v[36:39]
	v_mfma_f32_16x16x32_bf16 v[24:27], v[178:181], v[220:223], v[24:27]
	v_mfma_f32_16x16x32_bf16 v[20:23], v[196:199], v[220:223], v[20:23]
	v_mfma_f32_16x16x32_bf16 v[8:11], v[178:181], v[228:231], v[8:11]
	v_mfma_f32_16x16x32_bf16 v[4:7], v[196:199], v[228:231], v[4:7]
	v_mfma_f32_16x16x32_bf16 v[56:59], v[192:195], v[208:211], v[56:59]
	v_mfma_f32_16x16x32_bf16 v[52:55], v[200:203], v[208:211], v[52:55]
	v_mfma_f32_16x16x32_bf16 v[40:43], v[192:195], v[216:219], v[40:43]
	v_mfma_f32_16x16x32_bf16 v[36:39], v[200:203], v[216:219], v[36:39]
	v_mfma_f32_16x16x32_bf16 v[24:27], v[192:195], v[224:227], v[24:27]
	v_mfma_f32_16x16x32_bf16 v[20:23], v[200:203], v[224:227], v[20:23]
	v_mfma_f32_16x16x32_bf16 v[8:11], v[192:195], v[232:235], v[8:11]
	v_mfma_f32_16x16x32_bf16 v[4:7], v[200:203], v[232:235], v[4:7]
	s_barrier
	s_add_i32 s19, 0, 0x18000
	s_add_i32 s21, 0, 0x1c000
	v_add_u32_e32 v174, s19, v168
	v_add_u32_e32 v200, s21, v168
	ds_read_b128 v[128:131], v174
	ds_read_b128 v[160:163], v174 offset:1024
	ds_read_b128 v[170:173], v174 offset:2048
	ds_read_b128 v[174:177], v174 offset:3072
	ds_read_b128 v[178:181], v200
	ds_read_b128 v[192:195], v200 offset:1024
	ds_read_b128 v[196:199], v200 offset:2048
	ds_read_b128 v[200:203], v200 offset:3072
	s_add_u32 s14, s30, 0x80000
	s_addc_u32 s15, s31, 0
	s_mov_b32 m0, s85
	v_lshl_add_u64 v[240:241], s[14:15], 0, v[132:133]
	ds_read_b128 v[204:207], v169 offset:32768
	ds_read_b128 v[208:211], v169 offset:33792
	ds_read_b128 v[212:215], v169 offset:34816
	ds_read_b128 v[216:219], v169 offset:35840
	ds_read_b128 v[220:223], v169 offset:36864
	ds_read_b128 v[224:227], v169 offset:37888
	ds_read_b128 v[228:231], v169 offset:38912
	ds_read_b128 v[232:235], v169 offset:39936
	global_load_lds_dwordx4 v[240:241], off
	v_lshl_add_u64 v[240:241], s[14:15], 0, v[134:135]
	s_mov_b32 m0, s90
	s_nop 0
	global_load_lds_dwordx4 v[240:241], off
	s_waitcnt vmcnt(8)
	s_waitcnt lgkmcnt(0)
	s_barrier
	v_mfma_f32_16x16x32_bf16 v[124:127], v[128:131], v[204:207], v[124:127]
	v_mfma_f32_16x16x32_bf16 v[116:119], v[170:173], v[204:207], v[116:119]
	v_mfma_f32_16x16x32_bf16 v[108:111], v[128:131], v[212:215], v[108:111]
	v_mfma_f32_16x16x32_bf16 v[96:99], v[170:173], v[212:215], v[96:99]
	v_mfma_f32_16x16x32_bf16 v[92:95], v[128:131], v[220:223], v[92:95]
	v_mfma_f32_16x16x32_bf16 v[80:83], v[170:173], v[220:223], v[80:83]
	v_mfma_f32_16x16x32_bf16 v[76:79], v[128:131], v[228:231], v[76:79]
	v_mfma_f32_16x16x32_bf16 v[64:67], v[170:173], v[228:231], v[64:67]
	v_mfma_f32_16x16x32_bf16 v[124:127], v[160:163], v[208:211], v[124:127]
	v_mfma_f32_16x16x32_bf16 v[116:119], v[174:177], v[208:211], v[116:119]
	v_mfma_f32_16x16x32_bf16 v[108:111], v[160:163], v[216:219], v[108:111]
	v_mfma_f32_16x16x32_bf16 v[96:99], v[174:177], v[216:219], v[96:99]
	v_mfma_f32_16x16x32_bf16 v[92:95], v[160:163], v[224:227], v[92:95]
	v_mfma_f32_16x16x32_bf16 v[80:83], v[174:177], v[224:227], v[80:83]
	v_mfma_f32_16x16x32_bf16 v[76:79], v[160:163], v[232:235], v[76:79]
	v_mfma_f32_16x16x32_bf16 v[64:67], v[174:177], v[232:235], v[64:67]
	v_mfma_f32_16x16x32_bf16 v[120:123], v[178:181], v[204:207], v[120:123]
	v_mfma_f32_16x16x32_bf16 v[112:115], v[196:199], v[204:207], v[112:115]
	v_mfma_f32_16x16x32_bf16 v[104:107], v[178:181], v[212:215], v[104:107]
	v_mfma_f32_16x16x32_bf16 v[100:103], v[196:199], v[212:215], v[100:103]
	v_mfma_f32_16x16x32_bf16 v[88:91], v[178:181], v[220:223], v[88:91]
	v_mfma_f32_16x16x32_bf16 v[84:87], v[196:199], v[220:223], v[84:87]
	v_mfma_f32_16x16x32_bf16 v[72:75], v[178:181], v[228:231], v[72:75]
	v_mfma_f32_16x16x32_bf16 v[68:71], v[196:199], v[228:231], v[68:71]
	v_mfma_f32_16x16x32_bf16 v[120:123], v[192:195], v[208:211], v[120:123]
	v_mfma_f32_16x16x32_bf16 v[112:115], v[200:203], v[208:211], v[112:115]
	v_mfma_f32_16x16x32_bf16 v[104:107], v[192:195], v[216:219], v[104:107]
	v_mfma_f32_16x16x32_bf16 v[100:103], v[200:203], v[216:219], v[100:103]
	v_mfma_f32_16x16x32_bf16 v[88:91], v[192:195], v[224:227], v[88:91]
	v_mfma_f32_16x16x32_bf16 v[84:87], v[200:203], v[224:227], v[84:87]
	v_mfma_f32_16x16x32_bf16 v[72:75], v[192:195], v[232:235], v[72:75]
	v_mfma_f32_16x16x32_bf16 v[68:71], v[200:203], v[232:235], v[68:71]
	s_barrier
; #define PG8_STAGE(bufoff, gbase, voff) do { _Pragma("unroll") for (int _i = 0; _i < 2; ++_i) \
;         __builtin_amdgcn_global_load_lds((const unsigned*)((const char*)(gbase) + (voff)[_i]), (LAS unsigned*)(lds + (bufoff) + ldsw + _i * 8192), 16, 0, 0); } while (0)
; #define PG8_LDA(dst, b, h) do { _Pragma("unroll") for (int m = 0; m < 4; ++m) _Pragma("unroll") for (int k = 0; k < 2; ++k) dst[m][k] = *(const LAS bf16x8*)(lds + PG8_SA(b, h) + aoff + m * 2048 + k * 1024); } while (0)
; #define PG8_MMA(ai, bj, At, Bt) do { __builtin_amdgcn_s_setprio(1); _Pragma("unroll") for (int m = 0; m < 4; ++m) _Pragma("unroll") for (int n = 0; n < 2; ++n) _Pragma("unroll") for (int k = 0; k < 2; ++k) \
;         acc[ai][bj][m][n] = __builtin_amdgcn_mfma_f32_16x16x32_bf16(Bt[n][k], At[m][k], acc[ai][bj][m][n], 0, 0, 0); __builtin_amdgcn_s_setprio(0); } while (0)
; #define PG8_WAIT_V(n) asm volatile("s_waitcnt vmcnt(" #n ")" ::: "memory")
; #define PG8_WAIT_L(n) asm volatile("s_waitcnt lgkmcnt(" #n ")" ::: "memory")
; #define PG8_BAR __builtin_amdgcn_s_barrier()
; #define PG8_SCHED __builtin_amdgcn_sched_barrier(0)
; template <class Epi, class Map>
; __device__ __forceinline__ void gemm_phase(LAS unsigned char* lds, const Gemm g, const Sched<Map>& S, const Epi& E) {
;     ...
;             PG8_LDA(At, 1, 1); PG8_STAGE(PG8_SB(1, 0), b3, voffB); PG8_STAGE(PG8_SB(1, 1), b3 + hstepB, voffB); PG8_STAGE(PG8_SA(1, 0), a3, voffA);
;             PG8_WAIT_V(8); PG8_WAIT_L(0); PG8_BAR; PG8_MMA(1, 0, At, B0); PG8_MMA(1, 1, At, B1); PG8_BAR; PG8_SCHED;
;         }
;         if (wr == 0) PG8_BAR;
	s_add_i32 s14, s19, s34
	v_lshl_add_u64 v[142:143], v[142:143], 0, s[82:83]
	s_mov_b32 m0, s14
	ds_read_b128 v[204:207], v169 offset:49152
	ds_read_b128 v[208:211], v169 offset:50176
	ds_read_b128 v[212:215], v169 offset:51200
	ds_read_b128 v[216:219], v169 offset:52224
	ds_read_b128 v[220:223], v169 offset:53248
	ds_read_b128 v[224:227], v169 offset:54272
	ds_read_b128 v[228:231], v169 offset:55296
	ds_read_b128 v[232:235], v169 offset:56320
	global_load_lds_dwordx4 v[142:143], off
	s_add_i32 m0, s14, 0x2000
	s_add_u32 s14, s28, 0x80080
	v_lshl_add_u64 v[142:143], v[164:165], 0, s[82:83]
	s_addc_u32 s15, s29, 0
	s_add_i32 s19, s21, s34
	global_load_lds_dwordx4 v[142:143], off
	v_lshl_add_u64 v[142:143], s[14:15], 0, v[144:145]
	s_mov_b32 m0, s19
	s_nop 0
	global_load_lds_dwordx4 v[142:143], off
	v_lshl_add_u64 v[142:143], s[14:15], 0, v[136:137]
	s_add_i32 m0, s19, 0x2000
	s_nop 0
	global_load_lds_dwordx4 v[142:143], off
	v_lshl_add_u64 v[142:143], v[236:237], 0, s[82:83]
	s_mov_b32 m0, s97
	s_nop 0
	global_load_lds_dwordx4 v[142:143], off
	v_lshl_add_u64 v[142:143], v[238:239], 0, s[82:83]
	s_mov_b32 m0, s56
	s_nop 0
	global_load_lds_dwordx4 v[142:143], off
	s_waitcnt vmcnt(8)
	s_waitcnt lgkmcnt(0)
	s_barrier
	v_mfma_f32_16x16x32_bf16 v[60:63], v[128:131], v[204:207], v[60:63]
	v_mfma_f32_16x16x32_bf16 v[48:51], v[170:173], v[204:207], v[48:51]
	v_mfma_f32_16x16x32_bf16 v[44:47], v[128:131], v[212:215], v[44:47]
	v_mfma_f32_16x16x32_bf16 v[32:35], v[170:173], v[212:215], v[32:35]
	v_mfma_f32_16x16x32_bf16 v[28:31], v[128:131], v[220:223], v[28:31]
	v_mfma_f32_16x16x32_bf16 v[16:19], v[170:173], v[220:223], v[16:19]
	v_mfma_f32_16x16x32_bf16 v[12:15], v[128:131], v[228:231], v[12:15]
	v_mfma_f32_16x16x32_bf16 v[0:3], v[170:173], v[228:231], v[0:3]
	v_mfma_f32_16x16x32_bf16 v[60:63], v[160:163], v[208:211], v[60:63]
	v_mfma_f32_16x16x32_bf16 v[48:51], v[174:177], v[208:211], v[48:51]
	v_mfma_f32_16x16x32_bf16 v[44:47], v[160:163], v[216:219], v[44:47]
	v_mfma_f32_16x16x32_bf16 v[32:35], v[174:177], v[216:219], v[32:35]
	v_mfma_f32_16x16x32_bf16 v[28:31], v[160:163], v[224:227], v[28:31]
	v_mfma_f32_16x16x32_bf16 v[16:19], v[174:177], v[224:227], v[16:19]
	v_mfma_f32_16x16x32_bf16 v[12:15], v[160:163], v[232:235], v[12:15]
	v_mfma_f32_16x16x32_bf16 v[0:3], v[174:177], v[232:235], v[0:3]
	v_mfma_f32_16x16x32_bf16 v[56:59], v[178:181], v[204:207], v[56:59]
	v_mfma_f32_16x16x32_bf16 v[52:55], v[196:199], v[204:207], v[52:55]
	v_mfma_f32_16x16x32_bf16 v[40:43], v[178:181], v[212:215], v[40:43]
	v_mfma_f32_16x16x32_bf16 v[36:39], v[196:199], v[212:215], v[36:39]
	v_mfma_f32_16x16x32_bf16 v[24:27], v[178:181], v[220:223], v[24:27]
	v_mfma_f32_16x16x32_bf16 v[20:23], v[196:199], v[220:223], v[20:23]
	v_mfma_f32_16x16x32_bf16 v[8:11], v[178:181], v[228:231], v[8:11]
	v_mfma_f32_16x16x32_bf16 v[4:7], v[196:199], v[228:231], v[4:7]
	v_mfma_f32_16x16x32_bf16 v[56:59], v[192:195], v[208:211], v[56:59]
	v_mfma_f32_16x16x32_bf16 v[52:55], v[200:203], v[208:211], v[52:55]
	v_mfma_f32_16x16x32_bf16 v[40:43], v[192:195], v[216:219], v[40:43]
	v_mfma_f32_16x16x32_bf16 v[36:39], v[200:203], v[216:219], v[36:39]
	v_mfma_f32_16x16x32_bf16 v[24:27], v[192:195], v[224:227], v[24:27]
	v_mfma_f32_16x16x32_bf16 v[20:23], v[200:203], v[224:227], v[20:23]
	v_mfma_f32_16x16x32_bf16 v[8:11], v[192:195], v[232:235], v[8:11]
	v_mfma_f32_16x16x32_bf16 v[4:7], v[200:203], v[232:235], v[4:7]
	s_barrier
	s_add_i32 s13, s13, 2
	s_add_u32 s24, s24, 0x100
	s_addc_u32 s25, s25, 0
	s_add_u32 s11, s11, 0x100
	s_addc_u32 s12, s12, 0
	s_cmp_gt_u32 s13, 29
	s_cbranch_scc0 .LBB0_552
	s_and_b64 vcc, exec, s[52:53]
	s_cbranch_vccz .LBB0_555
	s_barrier

; #define PG8_STAGE(bufoff, gbase, voff) do { _Pragma("unroll") for (int _i = 0; _i < 2; ++_i) \
;         __builtin_amdgcn_global_load_lds((const unsigned*)((const char*)(gbase) + (voff)[_i]), (LAS unsigned*)(lds + (bufoff) + ldsw + _i * 8192), 16, 0, 0); } while (0)
; #define PG8_LDA(dst, b, h) do { _Pragma("unroll") for (int m = 0; m < 4; ++m) _Pragma("unroll") for (int k = 0; k < 2; ++k) dst[m][k] = *(const LAS bf16x8*)(lds + PG8_SA(b, h) + aoff + m * 2048 + k * 1024); } while (0)
; #define PG8_LDB(dst, b, h) do { _Pragma("unroll") for (int n = 0; n < 2; ++n) _Pragma("unroll") for (int k = 0; k < 2; ++k) dst[n][k] = *(const LAS bf16x8*)(lds + PG8_SB(b, h) + boff + n * 2048 + k * 1024); } while (0)
; #define PG8_MMA(ai, bj, At, Bt) do { __builtin_amdgcn_s_setprio(1); _Pragma("unroll") for (int m = 0; m < 4; ++m) _Pragma("unroll") for (int n = 0; n < 2; ++n) _Pragma("unroll") for (int k = 0; k < 2; ++k) \
;         acc[ai][bj][m][n] = __builtin_amdgcn_mfma_f32_16x16x32_bf16(Bt[n][k], At[m][k], acc[ai][bj][m][n], 0, 0, 0); __builtin_amdgcn_s_setprio(0); } while (0)
; #define PG8_WAIT_V(n) asm volatile("s_waitcnt vmcnt(" #n ")" ::: "memory")
; #define PG8_WAIT_L(n) asm volatile("s_waitcnt lgkmcnt(" #n ")" ::: "memory")
; #define PG8_BAR __builtin_amdgcn_s_barrier()
; #define PG8_SCHED __builtin_amdgcn_sched_barrier(0)
; template <class Epi, class Map>
; __device__ __forceinline__ void gemm_phase(LAS unsigned char* lds, const Gemm g, const Sched<Map>& S, const Epi& E) {
;     ...
;         for (int t = 0; t < nt; t += 2) {
;             const bool last = (t == nt - 2);
;             const char* a1 = cA + (size_t)(t + 1) * kstep;
;             const char* a2 = last ? nA : cA + (size_t)(t + 2) * kstep; const char* b2 = last ? nB : cB + (size_t)(t + 2) * kstep;
;             const char* a3 = a2 + kstep; const char* b3 = b2 + kstep;
;             PG8_LDB(B0, 0, 0); PG8_LDB(B1, 0, 1); PG8_SCHED; PG8_LDA(At, 0, 0); PG8_STAGE(PG8_SA(1, 1), a1 + hstepA, voffA);
;             PG8_WAIT_V(8); PG8_WAIT_L(0); PG8_BAR; PG8_MMA(0, 0, At, B0); PG8_MMA(0, 1, At, B1); PG8_BAR; PG8_SCHED;
;             PG8_LDA(At, 0, 1); PG8_STAGE(PG8_SB(0, 0), b2, voffB); PG8_STAGE(PG8_SB(0, 1), b2 + hstepB, voffB); PG8_STAGE(PG8_SA(0, 0), a2, voffA);
.LBB0_587:
	s_add_u32 s34, s30, 0xfff80080
	s_addc_u32 s35, s31, -1
	s_add_i32 s39, 0, 0x10000
	s_cmp_eq_u32 s38, 28
	s_cselect_b32 s37, s12, s35
	s_cselect_b32 s36, s13, s34
	v_add_u32_e32 v138, s39, v142
	s_cselect_b32 s35, s14, s33
	s_cselect_b32 s34, s15, s21
	s_add_i32 s46, 0, 0x14000
	ds_read_b128 v[160:163], v138
	ds_read_b128 v[164:167], v138 offset:1024
	ds_read_b128 v[168:171], v138 offset:2048
	ds_read_b128 v[172:175], v138 offset:3072
	v_add_u32_e32 v138, s46, v142
	ds_read_b128 v[176:179], v138
	ds_read_b128 v[192:195], v138 offset:1024
	ds_read_b128 v[196:199], v138 offset:2048
	ds_read_b128 v[200:203], v138 offset:3072
	v_lshl_add_u64 v[138:139], s[30:31], 0, v[134:135]
	s_add_i32 m0, s1, 0xc000
	ds_read_b128 v[204:207], v143
	ds_read_b128 v[208:211], v143 offset:1024
	ds_read_b128 v[212:215], v143 offset:2048
	ds_read_b128 v[216:219], v143 offset:3072
	ds_read_b128 v[220:223], v143 offset:4096
	ds_read_b128 v[224:227], v143 offset:5120
	ds_read_b128 v[228:231], v143 offset:6144
	ds_read_b128 v[232:235], v143 offset:7168
	global_load_lds_dwordx4 v[138:139], off
	v_lshl_add_u64 v[138:139], s[30:31], 0, v[136:137]
	s_add_i32 m0, s1, 0xe000
	s_nop 0
	global_load_lds_dwordx4 v[138:139], off
	s_waitcnt vmcnt(8)
	s_waitcnt lgkmcnt(0)
	s_barrier
	v_mfma_f32_16x16x32_bf16 v[124:127], v[160:163], v[204:207], v[124:127]
	v_mfma_f32_16x16x32_bf16 v[120:123], v[168:171], v[204:207], v[120:123]
	v_mfma_f32_16x16x32_bf16 v[116:119], v[160:163], v[212:215], v[116:119]
	v_mfma_f32_16x16x32_bf16 v[108:111], v[168:171], v[212:215], v[108:111]
	v_mfma_f32_16x16x32_bf16 v[100:103], v[160:163], v[220:223], v[100:103]
	v_mfma_f32_16x16x32_bf16 v[92:95], v[168:171], v[220:223], v[92:95]
	v_mfma_f32_16x16x32_bf16 v[84:87], v[160:163], v[228:231], v[84:87]
	v_mfma_f32_16x16x32_bf16 v[76:79], v[168:171], v[228:231], v[76:79]
	v_mfma_f32_16x16x32_bf16 v[124:127], v[164:167], v[208:211], v[124:127]
	v_mfma_f32_16x16x32_bf16 v[120:123], v[172:175], v[208:211], v[120:123]
	v_mfma_f32_16x16x32_bf16 v[116:119], v[164:167], v[216:219], v[116:119]
	v_mfma_f32_16x16x32_bf16 v[108:111], v[172:175], v[216:219], v[108:111]
	v_mfma_f32_16x16x32_bf16 v[100:103], v[164:167], v[224:227], v[100:103]
	v_mfma_f32_16x16x32_bf16 v[92:95], v[172:175], v[224:227], v[92:95]
	v_mfma_f32_16x16x32_bf16 v[84:87], v[164:167], v[232:235], v[84:87]
	v_mfma_f32_16x16x32_bf16 v[76:79], v[172:175], v[232:235], v[76:79]
	v_mfma_f32_16x16x32_bf16 v[112:115], v[176:179], v[204:207], v[112:115]
	v_mfma_f32_16x16x32_bf16 v[104:107], v[196:199], v[204:207], v[104:107]
	v_mfma_f32_16x16x32_bf16 v[96:99], v[176:179], v[212:215], v[96:99]
	v_mfma_f32_16x16x32_bf16 v[88:91], v[196:199], v[212:215], v[88:91]
	v_mfma_f32_16x16x32_bf16 v[80:83], v[176:179], v[220:223], v[80:83]
	v_mfma_f32_16x16x32_bf16 v[72:75], v[196:199], v[220:223], v[72:75]
	v_mfma_f32_16x16x32_bf16 v[68:71], v[176:179], v[228:231], v[68:71]
	v_mfma_f32_16x16x32_bf16 v[64:67], v[196:199], v[228:231], v[64:67]
	v_mfma_f32_16x16x32_bf16 v[112:115], v[192:195], v[208:211], v[112:115]
	v_mfma_f32_16x16x32_bf16 v[104:107], v[200:203], v[208:211], v[104:107]
	v_mfma_f32_16x16x32_bf16 v[96:99], v[192:195], v[216:219], v[96:99]
	v_mfma_f32_16x16x32_bf16 v[88:91], v[200:203], v[216:219], v[88:91]
	v_mfma_f32_16x16x32_bf16 v[80:83], v[192:195], v[224:227], v[80:83]
	v_mfma_f32_16x16x32_bf16 v[72:75], v[200:203], v[224:227], v[72:75]
	v_mfma_f32_16x16x32_bf16 v[68:71], v[192:195], v[232:235], v[68:71]
	v_mfma_f32_16x16x32_bf16 v[64:67], v[200:203], v[232:235], v[64:67]
	s_barrier
	s_add_i32 s39, s39, s0
	v_lshl_add_u64 v[138:139], s[34:35], 0, v[144:145]
	s_mov_b32 m0, s39
	ds_read_b128 v[204:207], v143 offset:16384
	ds_read_b128 v[208:211], v143 offset:17408
	ds_read_b128 v[212:215], v143 offset:18432
	ds_read_b128 v[216:219], v143 offset:19456
	ds_read_b128 v[220:223], v143 offset:20480
	ds_read_b128 v[224:227], v143 offset:21504
	ds_read_b128 v[228:231], v143 offset:22528
	ds_read_b128 v[232:235], v143 offset:23552
	global_load_lds_dwordx4 v[138:139], off
	s_add_i32 m0, s39, 0x2000
	s_add_u32 s44, s34, 0x80000
	v_lshl_add_u64 v[180:181], s[34:35], 0, v[128:129]
	s_addc_u32 s45, s35, 0
	s_add_i32 s39, s46, s0
	global_load_lds_dwordx4 v[180:181], off
	v_lshl_add_u64 v[236:237], s[44:45], 0, v[144:145]
	s_mov_b32 m0, s39
	v_lshl_add_u64 v[238:239], s[36:37], 0, v[130:131]
	global_load_lds_dwordx4 v[236:237], off
	v_lshl_add_u64 v[236:237], s[44:45], 0, v[128:129]
	s_add_i32 m0, s39, 0x2000
	s_nop 0
	global_load_lds_dwordx4 v[236:237], off
	v_lshl_add_u64 v[236:237], s[36:37], 0, v[132:133]
	s_mov_b32 m0, s1
	s_nop 0
	global_load_lds_dwordx4 v[236:237], off
	s_mov_b32 m0, s2
	s_nop 0
	global_load_lds_dwordx4 v[238:239], off
	s_waitcnt vmcnt(8)
	s_waitcnt lgkmcnt(0)
	s_barrier
; #define PG8_STAGE(bufoff, gbase, voff) do { _Pragma("unroll") for (int _i = 0; _i < 2; ++_i) \
;         __builtin_amdgcn_global_load_lds((const unsigned*)((const char*)(gbase) + (voff)[_i]), (LAS unsigned*)(lds + (bufoff) + ldsw + _i * 8192), 16, 0, 0); } while (0)
; #define PG8_LDA(dst, b, h) do { _Pragma("unroll") for (int m = 0; m < 4; ++m) _Pragma("unroll") for (int k = 0; k < 2; ++k) dst[m][k] = *(const LAS bf16x8*)(lds + PG8_SA(b, h) + aoff + m * 2048 + k * 1024); } while (0)
; #define PG8_LDB(dst, b, h) do { _Pragma("unroll") for (int n = 0; n < 2; ++n) _Pragma("unroll") for (int k = 0; k < 2; ++k) dst[n][k] = *(const LAS bf16x8*)(lds + PG8_SB(b, h) + boff + n * 2048 + k * 1024); } while (0)
; #define PG8_MMA(ai, bj, At, Bt) do { __builtin_amdgcn_s_setprio(1); _Pragma("unroll") for (int m = 0; m < 4; ++m) _Pragma("unroll") for (int n = 0; n < 2; ++n) _Pragma("unroll") for (int k = 0; k < 2; ++k) \
;         acc[ai][bj][m][n] = __builtin_amdgcn_mfma_f32_16x16x32_bf16(Bt[n][k], At[m][k], acc[ai][bj][m][n], 0, 0, 0); __builtin_amdgcn_s_setprio(0); } while (0)
; #define PG8_WAIT_V(n) asm volatile("s_waitcnt vmcnt(" #n ")" ::: "memory")
; #define PG8_WAIT_L(n) asm volatile("s_waitcnt lgkmcnt(" #n ")" ::: "memory")
; #define PG8_BAR __builtin_amdgcn_s_barrier()
; #define PG8_SCHED __builtin_amdgcn_sched_barrier(0)
; template <class Epi, class Map>
; __device__ __forceinline__ void gemm_phase(LAS unsigned char* lds, const Gemm g, const Sched<Map>& S, const Epi& E) {
;     ...
;             PG8_WAIT_V(8); PG8_WAIT_L(0); PG8_BAR; PG8_MMA(1, 0, At, B0); PG8_MMA(1, 1, At, B1); PG8_BAR; PG8_SCHED;
;             PG8_LDB(B0, 1, 0); PG8_LDB(B1, 1, 1); PG8_SCHED; PG8_LDA(At, 1, 0); PG8_STAGE(PG8_SA(0, 1), a2 + hstepA, voffA);
;             PG8_WAIT_V(8); PG8_WAIT_L(0); PG8_BAR; PG8_MMA(0, 0, At, B0); PG8_MMA(0, 1, At, B1); PG8_BAR; PG8_SCHED;
	v_mfma_f32_16x16x32_bf16 v[60:63], v[160:163], v[204:207], v[60:63]
	v_mfma_f32_16x16x32_bf16 v[56:59], v[168:171], v[204:207], v[56:59]
	v_mfma_f32_16x16x32_bf16 v[52:55], v[160:163], v[212:215], v[52:55]
	v_mfma_f32_16x16x32_bf16 v[44:47], v[168:171], v[212:215], v[44:47]
	v_mfma_f32_16x16x32_bf16 v[36:39], v[160:163], v[220:223], v[36:39]
	v_mfma_f32_16x16x32_bf16 v[28:31], v[168:171], v[220:223], v[28:31]
	v_mfma_f32_16x16x32_bf16 v[20:23], v[160:163], v[228:231], v[20:23]
	v_mfma_f32_16x16x32_bf16 v[12:15], v[168:171], v[228:231], v[12:15]
	v_mfma_f32_16x16x32_bf16 v[60:63], v[164:167], v[208:211], v[60:63]
	v_mfma_f32_16x16x32_bf16 v[56:59], v[172:175], v[208:211], v[56:59]
	v_mfma_f32_16x16x32_bf16 v[52:55], v[164:167], v[216:219], v[52:55]
	v_mfma_f32_16x16x32_bf16 v[44:47], v[172:175], v[216:219], v[44:47]
	v_mfma_f32_16x16x32_bf16 v[36:39], v[164:167], v[224:227], v[36:39]
	v_mfma_f32_16x16x32_bf16 v[28:31], v[172:175], v[224:227], v[28:31]
	v_mfma_f32_16x16x32_bf16 v[20:23], v[164:167], v[232:235], v[20:23]
	v_mfma_f32_16x16x32_bf16 v[12:15], v[172:175], v[232:235], v[12:15]
	v_mfma_f32_16x16x32_bf16 v[48:51], v[176:179], v[204:207], v[48:51]
	v_mfma_f32_16x16x32_bf16 v[40:43], v[196:199], v[204:207], v[40:43]
	v_mfma_f32_16x16x32_bf16 v[32:35], v[176:179], v[212:215], v[32:35]
	v_mfma_f32_16x16x32_bf16 v[24:27], v[196:199], v[212:215], v[24:27]
	v_mfma_f32_16x16x32_bf16 v[16:19], v[176:179], v[220:223], v[16:19]
	v_mfma_f32_16x16x32_bf16 v[8:11], v[196:199], v[220:223], v[8:11]
	v_mfma_f32_16x16x32_bf16 v[4:7], v[176:179], v[228:231], v[4:7]
	v_mfma_f32_16x16x32_bf16 v[0:3], v[196:199], v[228:231], v[0:3]
	v_mfma_f32_16x16x32_bf16 v[48:51], v[192:195], v[208:211], v[48:51]
	v_mfma_f32_16x16x32_bf16 v[40:43], v[200:203], v[208:211], v[40:43]
	v_mfma_f32_16x16x32_bf16 v[32:35], v[192:195], v[216:219], v[32:35]
	v_mfma_f32_16x16x32_bf16 v[24:27], v[200:203], v[216:219], v[24:27]
	v_mfma_f32_16x16x32_bf16 v[16:19], v[192:195], v[224:227], v[16:19]
	v_mfma_f32_16x16x32_bf16 v[8:11], v[200:203], v[224:227], v[8:11]
	v_mfma_f32_16x16x32_bf16 v[4:7], v[192:195], v[232:235], v[4:7]
	v_mfma_f32_16x16x32_bf16 v[0:3], v[200:203], v[232:235], v[0:3]
	s_barrier
	s_add_i32 s39, 0, 0x18000
	s_add_i32 s44, 0, 0x1c000
	v_add_u32_e32 v172, s39, v142
	v_add_u32_e32 v200, s44, v142
	ds_read_b128 v[160:163], v172
	ds_read_b128 v[164:167], v172 offset:1024
	ds_read_b128 v[168:171], v172 offset:2048
	ds_read_b128 v[172:175], v172 offset:3072
	ds_read_b128 v[176:179], v200
	ds_read_b128 v[192:195], v200 offset:1024
	ds_read_b128 v[196:199], v200 offset:2048
	ds_read_b128 v[200:203], v200 offset:3072
	s_add_u32 s36, s36, 0x80000
	s_addc_u32 s37, s37, 0
	s_mov_b32 m0, s3
	v_lshl_add_u64 v[240:241], s[36:37], 0, v[132:133]
	ds_read_b128 v[204:207], v143 offset:32768
	ds_read_b128 v[208:211], v143 offset:33792
	ds_read_b128 v[212:215], v143 offset:34816
	ds_read_b128 v[216:219], v143 offset:35840
	ds_read_b128 v[220:223], v143 offset:36864
	ds_read_b128 v[224:227], v143 offset:37888
	ds_read_b128 v[228:231], v143 offset:38912
	ds_read_b128 v[232:235], v143 offset:39936
	global_load_lds_dwordx4 v[240:241], off
	v_lshl_add_u64 v[240:241], s[36:37], 0, v[130:131]
	s_mov_b32 m0, s4
	s_nop 0
	global_load_lds_dwordx4 v[240:241], off
	s_waitcnt vmcnt(8)
	s_waitcnt lgkmcnt(0)
	s_barrier
	v_mfma_f32_16x16x32_bf16 v[124:127], v[160:163], v[204:207], v[124:127]
	v_mfma_f32_16x16x32_bf16 v[120:123], v[168:171], v[204:207], v[120:123]
	v_mfma_f32_16x16x32_bf16 v[116:119], v[160:163], v[212:215], v[116:119]
	v_mfma_f32_16x16x32_bf16 v[108:111], v[168:171], v[212:215], v[108:111]
	v_mfma_f32_16x16x32_bf16 v[100:103], v[160:163], v[220:223], v[100:103]
	v_mfma_f32_16x16x32_bf16 v[92:95], v[168:171], v[220:223], v[92:95]
	v_mfma_f32_16x16x32_bf16 v[84:87], v[160:163], v[228:231], v[84:87]
	v_mfma_f32_16x16x32_bf16 v[76:79], v[168:171], v[228:231], v[76:79]
	v_mfma_f32_16x16x32_bf16 v[124:127], v[164:167], v[208:211], v[124:127]
	v_mfma_f32_16x16x32_bf16 v[120:123], v[172:175], v[208:211], v[120:123]
	v_mfma_f32_16x16x32_bf16 v[116:119], v[164:167], v[216:219], v[116:119]
	v_mfma_f32_16x16x32_bf16 v[108:111], v[172:175], v[216:219], v[108:111]
	v_mfma_f32_16x16x32_bf16 v[100:103], v[164:167], v[224:227], v[100:103]
	v_mfma_f32_16x16x32_bf16 v[92:95], v[172:175], v[224:227], v[92:95]
	v_mfma_f32_16x16x32_bf16 v[84:87], v[164:167], v[232:235], v[84:87]
	v_mfma_f32_16x16x32_bf16 v[76:79], v[172:175], v[232:235], v[76:79]
	v_mfma_f32_16x16x32_bf16 v[112:115], v[176:179], v[204:207], v[112:115]
	v_mfma_f32_16x16x32_bf16 v[104:107], v[196:199], v[204:207], v[104:107]
	v_mfma_f32_16x16x32_bf16 v[96:99], v[176:179], v[212:215], v[96:99]
	v_mfma_f32_16x16x32_bf16 v[88:91], v[196:199], v[212:215], v[88:91]
	v_mfma_f32_16x16x32_bf16 v[80:83], v[176:179], v[220:223], v[80:83]
	v_mfma_f32_16x16x32_bf16 v[72:75], v[196:199], v[220:223], v[72:75]
	v_mfma_f32_16x16x32_bf16 v[68:71], v[176:179], v[228:231], v[68:71]
	v_mfma_f32_16x16x32_bf16 v[64:67], v[196:199], v[228:231], v[64:67]
	v_mfma_f32_16x16x32_bf16 v[112:115], v[192:195], v[208:211], v[112:115]
	v_mfma_f32_16x16x32_bf16 v[104:107], v[200:203], v[208:211], v[104:107]
	v_mfma_f32_16x16x32_bf16 v[96:99], v[192:195], v[216:219], v[96:99]
	v_mfma_f32_16x16x32_bf16 v[88:91], v[200:203], v[216:219], v[88:91]
	v_mfma_f32_16x16x32_bf16 v[80:83], v[192:195], v[224:227], v[80:83]
	v_mfma_f32_16x16x32_bf16 v[72:75], v[200:203], v[224:227], v[72:75]
	v_mfma_f32_16x16x32_bf16 v[68:71], v[192:195], v[232:235], v[68:71]
	v_mfma_f32_16x16x32_bf16 v[64:67], v[200:203], v[232:235], v[64:67]
	s_barrier
; #define PG8_STAGE(bufoff, gbase, voff) do { _Pragma("unroll") for (int _i = 0; _i < 2; ++_i) \
;         __builtin_amdgcn_global_load_lds((const unsigned*)((const char*)(gbase) + (voff)[_i]), (LAS unsigned*)(lds + (bufoff) + ldsw + _i * 8192), 16, 0, 0); } while (0)
; #define PG8_LDA(dst, b, h) do { _Pragma("unroll") for (int m = 0; m < 4; ++m) _Pragma("unroll") for (int k = 0; k < 2; ++k) dst[m][k] = *(const LAS bf16x8*)(lds + PG8_SA(b, h) + aoff + m * 2048 + k * 1024); } while (0)
; #define PG8_MMA(ai, bj, At, Bt) do { __builtin_amdgcn_s_setprio(1); _Pragma("unroll") for (int m = 0; m < 4; ++m) _Pragma("unroll") for (int n = 0; n < 2; ++n) _Pragma("unroll") for (int k = 0; k < 2; ++k) \
;         acc[ai][bj][m][n] = __builtin_amdgcn_mfma_f32_16x16x32_bf16(Bt[n][k], At[m][k], acc[ai][bj][m][n], 0, 0, 0); __builtin_amdgcn_s_setprio(0); } while (0)
; #define PG8_WAIT_V(n) asm volatile("s_waitcnt vmcnt(" #n ")" ::: "memory")
; #define PG8_WAIT_L(n) asm volatile("s_waitcnt lgkmcnt(" #n ")" ::: "memory")
; #define PG8_BAR __builtin_amdgcn_s_barrier()
; #define PG8_SCHED __builtin_amdgcn_sched_barrier(0)
; template <class Epi, class Map>
; __device__ __forceinline__ void gemm_phase(LAS unsigned char* lds, const Gemm g, const Sched<Map>& S, const Epi& E) {
;     ...
;             PG8_LDA(At, 1, 1); PG8_STAGE(PG8_SB(1, 0), b3, voffB); PG8_STAGE(PG8_SB(1, 1), b3 + hstepB, voffB); PG8_STAGE(PG8_SA(1, 0), a3, voffA);
;             PG8_WAIT_V(8); PG8_WAIT_L(0); PG8_BAR; PG8_MMA(1, 0, At, B0); PG8_MMA(1, 1, At, B1); PG8_BAR; PG8_SCHED;
;         }
;         if (wr == 0) PG8_BAR;
	s_add_i32 s36, s39, s0
	v_lshl_add_u64 v[138:139], v[138:139], 0, s[82:83]
	s_mov_b32 m0, s36
	ds_read_b128 v[204:207], v143 offset:49152
	ds_read_b128 v[208:211], v143 offset:50176
	ds_read_b128 v[212:215], v143 offset:51200
	ds_read_b128 v[216:219], v143 offset:52224
	ds_read_b128 v[220:223], v143 offset:53248
	ds_read_b128 v[224:227], v143 offset:54272
	ds_read_b128 v[228:231], v143 offset:55296
	ds_read_b128 v[232:235], v143 offset:56320
	global_load_lds_dwordx4 v[138:139], off
	s_add_i32 m0, s36, 0x2000
	s_add_u32 s34, s34, 0x80080
	v_lshl_add_u64 v[138:139], v[180:181], 0, s[82:83]
	s_addc_u32 s35, s35, 0
	s_add_i32 s36, s44, s0
	global_load_lds_dwordx4 v[138:139], off
	v_lshl_add_u64 v[138:139], s[34:35], 0, v[144:145]
	s_mov_b32 m0, s36
	s_nop 0
	global_load_lds_dwordx4 v[138:139], off
	v_lshl_add_u64 v[138:139], s[34:35], 0, v[128:129]
	s_add_i32 m0, s36, 0x2000
	s_nop 0
	global_load_lds_dwordx4 v[138:139], off
	v_lshl_add_u64 v[138:139], v[236:237], 0, s[82:83]
	s_mov_b32 m0, s6
	s_nop 0
	global_load_lds_dwordx4 v[138:139], off
	v_lshl_add_u64 v[138:139], v[238:239], 0, s[82:83]
	s_mov_b32 m0, s7
	s_nop 0
	global_load_lds_dwordx4 v[138:139], off
	s_waitcnt vmcnt(8)
	s_waitcnt lgkmcnt(0)
	s_barrier
	v_mfma_f32_16x16x32_bf16 v[60:63], v[160:163], v[204:207], v[60:63]
	v_mfma_f32_16x16x32_bf16 v[56:59], v[168:171], v[204:207], v[56:59]
	v_mfma_f32_16x16x32_bf16 v[52:55], v[160:163], v[212:215], v[52:55]
	v_mfma_f32_16x16x32_bf16 v[44:47], v[168:171], v[212:215], v[44:47]
	v_mfma_f32_16x16x32_bf16 v[36:39], v[160:163], v[220:223], v[36:39]
	v_mfma_f32_16x16x32_bf16 v[28:31], v[168:171], v[220:223], v[28:31]
	v_mfma_f32_16x16x32_bf16 v[20:23], v[160:163], v[228:231], v[20:23]
	v_mfma_f32_16x16x32_bf16 v[12:15], v[168:171], v[228:231], v[12:15]
	v_mfma_f32_16x16x32_bf16 v[60:63], v[164:167], v[208:211], v[60:63]
	v_mfma_f32_16x16x32_bf16 v[56:59], v[172:175], v[208:211], v[56:59]
	v_mfma_f32_16x16x32_bf16 v[52:55], v[164:167], v[216:219], v[52:55]
	v_mfma_f32_16x16x32_bf16 v[44:47], v[172:175], v[216:219], v[44:47]
	v_mfma_f32_16x16x32_bf16 v[36:39], v[164:167], v[224:227], v[36:39]
	v_mfma_f32_16x16x32_bf16 v[28:31], v[172:175], v[224:227], v[28:31]
	v_mfma_f32_16x16x32_bf16 v[20:23], v[164:167], v[232:235], v[20:23]
	v_mfma_f32_16x16x32_bf16 v[12:15], v[172:175], v[232:235], v[12:15]
	v_mfma_f32_16x16x32_bf16 v[48:51], v[176:179], v[204:207], v[48:51]
	v_mfma_f32_16x16x32_bf16 v[40:43], v[196:199], v[204:207], v[40:43]
	v_mfma_f32_16x16x32_bf16 v[32:35], v[176:179], v[212:215], v[32:35]
	v_mfma_f32_16x16x32_bf16 v[24:27], v[196:199], v[212:215], v[24:27]
	v_mfma_f32_16x16x32_bf16 v[16:19], v[176:179], v[220:223], v[16:19]
	v_mfma_f32_16x16x32_bf16 v[8:11], v[196:199], v[220:223], v[8:11]
	v_mfma_f32_16x16x32_bf16 v[4:7], v[176:179], v[228:231], v[4:7]
	v_mfma_f32_16x16x32_bf16 v[0:3], v[196:199], v[228:231], v[0:3]
	v_mfma_f32_16x16x32_bf16 v[48:51], v[192:195], v[208:211], v[48:51]
	v_mfma_f32_16x16x32_bf16 v[40:43], v[200:203], v[208:211], v[40:43]
	v_mfma_f32_16x16x32_bf16 v[32:35], v[192:195], v[216:219], v[32:35]
	v_mfma_f32_16x16x32_bf16 v[24:27], v[200:203], v[216:219], v[24:27]
	v_mfma_f32_16x16x32_bf16 v[16:19], v[192:195], v[224:227], v[16:19]
	v_mfma_f32_16x16x32_bf16 v[8:11], v[200:203], v[224:227], v[8:11]
	v_mfma_f32_16x16x32_bf16 v[4:7], v[192:195], v[232:235], v[4:7]
	v_mfma_f32_16x16x32_bf16 v[0:3], v[200:203], v[232:235], v[0:3]
	s_barrier
	s_add_i32 s38, s38, 2
	s_add_u32 s30, s30, 0x100
	s_addc_u32 s31, s31, 0
	s_add_u32 s21, s21, 0x100
	s_addc_u32 s33, s33, 0
	s_cmp_gt_u32 s38, 29
	s_cbranch_scc0 .LBB0_587
	s_and_b64 vcc, exec, s[18:19]
	s_cbranch_vccz .LBB0_590
	s_barrier

; #define PG8_STAGE(bufoff, gbase, voff) do { _Pragma("unroll") for (int _i = 0; _i < 2; ++_i) \
;         __builtin_amdgcn_global_load_lds((const unsigned*)((const char*)(gbase) + (voff)[_i]), (LAS unsigned*)(lds + (bufoff) + ldsw + _i * 8192), 16, 0, 0); } while (0)
; #define PG8_LDA(dst, b, h) do { _Pragma("unroll") for (int m = 0; m < 4; ++m) _Pragma("unroll") for (int k = 0; k < 2; ++k) dst[m][k] = *(const LAS bf16x8*)(lds + PG8_SA(b, h) + aoff + m * 2048 + k * 1024); } while (0)
; #define PG8_LDB(dst, b, h) do { _Pragma("unroll") for (int n = 0; n < 2; ++n) _Pragma("unroll") for (int k = 0; k < 2; ++k) dst[n][k] = *(const LAS bf16x8*)(lds + PG8_SB(b, h) + boff + n * 2048 + k * 1024); } while (0)
; #define PG8_MMA(ai, bj, At, Bt) do { __builtin_amdgcn_s_setprio(1); _Pragma("unroll") for (int m = 0; m < 4; ++m) _Pragma("unroll") for (int n = 0; n < 2; ++n) _Pragma("unroll") for (int k = 0; k < 2; ++k) \
;         acc[ai][bj][m][n] = __builtin_amdgcn_mfma_f32_16x16x32_bf16(Bt[n][k], At[m][k], acc[ai][bj][m][n], 0, 0, 0); __builtin_amdgcn_s_setprio(0); } while (0)
; #define PG8_WAIT_V(n) asm volatile("s_waitcnt vmcnt(" #n ")" ::: "memory")
; #define PG8_WAIT_L(n) asm volatile("s_waitcnt lgkmcnt(" #n ")" ::: "memory")
; #define PG8_BAR __builtin_amdgcn_s_barrier()
; #define PG8_SCHED __builtin_amdgcn_sched_barrier(0)
; template <class Epi, class Map>
; __device__ __forceinline__ void gemm_phase(LAS unsigned char* lds, const Gemm g, const Sched<Map>& S, const Epi& E) {
;     ...
;         for (int t = 0; t < nt; t += 2) {
;             const bool last = (t == nt - 2);
;             const char* a1 = cA + (size_t)(t + 1) * kstep;
;             const char* a2 = last ? nA : cA + (size_t)(t + 2) * kstep; const char* b2 = last ? nB : cB + (size_t)(t + 2) * kstep;
;             const char* a3 = a2 + kstep; const char* b3 = b2 + kstep;
;             PG8_LDB(B0, 0, 0); PG8_LDB(B1, 0, 1); PG8_SCHED; PG8_LDA(At, 0, 0); PG8_STAGE(PG8_SA(1, 1), a1 + hstepA, voffA);
;             PG8_WAIT_V(8); PG8_WAIT_L(0); PG8_BAR; PG8_MMA(0, 0, At, B0); PG8_MMA(0, 1, At, B1); PG8_BAR; PG8_SCHED;
;             PG8_LDA(At, 0, 1); PG8_STAGE(PG8_SB(0, 0), b2, voffB); PG8_STAGE(PG8_SB(0, 1), b2 + hstepB, voffB); PG8_STAGE(PG8_SA(0, 0), a2, voffA);
.LBB0_659:
	s_add_u32 s50, s30, s44
	s_addc_u32 s51, s31, s45
	s_add_u32 s48, s50, 0x100
	s_addc_u32 s49, s51, 0
	s_and_b64 s[46:47], s[36:37], exec
	s_cselect_b32 s47, s15, s49
	s_cselect_b32 s46, s33, s48
	s_add_u32 s44, s28, s44
	s_addc_u32 s45, s29, s45
	s_add_u32 s44, s44, 0x100
	s_addc_u32 s45, s45, 0
	s_add_i32 s62, 0, 0x10000
	s_and_b64 s[36:37], s[36:37], exec
	s_cselect_b32 s49, s38, s45
	s_cselect_b32 s48, s39, s44
	s_add_i32 s37, 0, 0x14000
	s_add_u32 s52, s50, 0x20080
	s_addc_u32 s53, s51, 0
	s_add_i32 s66, s62, s0
	s_add_i32 m0, s1, 0xc000
	s_add_i32 s63, s1, 0xe000
	s_add_i32 s58, s66, 0x2000
	v_add_u32_e32 v142, s62, v140
	s_add_u32 s50, s48, 0x10000
	ds_read_b128 v[134:137], v142
	ds_read_b128 v[160:163], v142 offset:1024
	ds_read_b128 v[164:167], v142 offset:2048
	ds_read_b128 v[168:171], v142 offset:3072
	v_add_u32_e32 v142, s37, v140
	s_addc_u32 s51, s49, 0
	s_add_i32 s65, s37, s0
	ds_read_b128 v[172:175], v142
	ds_read_b128 v[176:179], v142 offset:1024
	ds_read_b128 v[192:195], v142 offset:2048
	ds_read_b128 v[196:199], v142 offset:3072
	s_add_i32 s59, s65, 0x2000
	s_add_i32 s57, 0, 0x18000
	s_add_i32 s56, 0, 0x1c000
	s_add_u32 s44, s46, 0x20000
	s_addc_u32 s45, s47, 0
	s_add_i32 s55, s57, s0
	s_add_i32 s54, s55, 0x2000
	s_add_u32 s36, s48, 0x10080
	s_addc_u32 s37, s49, 0
	s_add_i32 s68, s56, s0
	s_add_i32 s67, s68, 0x2000
	v_lshl_add_u64 v[142:143], s[52:53], 0, v[132:133]
	ds_read_b128 v[200:203], v141
	ds_read_b128 v[204:207], v141 offset:1024
	ds_read_b128 v[208:211], v141 offset:2048
	ds_read_b128 v[212:215], v141 offset:3072
	ds_read_b128 v[216:219], v141 offset:4096
	ds_read_b128 v[220:223], v141 offset:5120
	ds_read_b128 v[224:227], v141 offset:6144
	ds_read_b128 v[228:231], v141 offset:7168
	global_load_lds_dwordx4 v[142:143], off
	v_lshl_add_u64 v[142:143], s[52:53], 0, v[130:131]
	s_mov_b32 m0, s63
	s_nop 0
	global_load_lds_dwordx4 v[142:143], off
	s_waitcnt vmcnt(8)
	s_waitcnt lgkmcnt(0)
	s_barrier
	v_mfma_f32_16x16x32_bf16 v[124:127], v[134:137], v[200:203], v[124:127]
	v_mfma_f32_16x16x32_bf16 v[120:123], v[164:167], v[200:203], v[120:123]
	v_mfma_f32_16x16x32_bf16 v[116:119], v[134:137], v[208:211], v[116:119]
	v_mfma_f32_16x16x32_bf16 v[112:115], v[164:167], v[208:211], v[112:115]
	v_mfma_f32_16x16x32_bf16 v[108:111], v[134:137], v[216:219], v[108:111]
	v_mfma_f32_16x16x32_bf16 v[104:107], v[164:167], v[216:219], v[104:107]
	v_mfma_f32_16x16x32_bf16 v[100:103], v[134:137], v[224:227], v[100:103]
	v_mfma_f32_16x16x32_bf16 v[96:99], v[164:167], v[224:227], v[96:99]
	v_mfma_f32_16x16x32_bf16 v[124:127], v[160:163], v[204:207], v[124:127]
	v_mfma_f32_16x16x32_bf16 v[120:123], v[168:171], v[204:207], v[120:123]
	v_mfma_f32_16x16x32_bf16 v[116:119], v[160:163], v[212:215], v[116:119]
	v_mfma_f32_16x16x32_bf16 v[112:115], v[168:171], v[212:215], v[112:115]
	v_mfma_f32_16x16x32_bf16 v[108:111], v[160:163], v[220:223], v[108:111]
	v_mfma_f32_16x16x32_bf16 v[104:107], v[168:171], v[220:223], v[104:107]
	v_mfma_f32_16x16x32_bf16 v[100:103], v[160:163], v[228:231], v[100:103]
	v_mfma_f32_16x16x32_bf16 v[96:99], v[168:171], v[228:231], v[96:99]
	v_mfma_f32_16x16x32_bf16 v[60:63], v[172:175], v[200:203], v[60:63]
	v_mfma_f32_16x16x32_bf16 v[56:59], v[192:195], v[200:203], v[56:59]
	v_mfma_f32_16x16x32_bf16 v[52:55], v[172:175], v[208:211], v[52:55]
	v_mfma_f32_16x16x32_bf16 v[48:51], v[192:195], v[208:211], v[48:51]
	v_mfma_f32_16x16x32_bf16 v[44:47], v[172:175], v[216:219], v[44:47]
	v_mfma_f32_16x16x32_bf16 v[40:43], v[192:195], v[216:219], v[40:43]
	v_mfma_f32_16x16x32_bf16 v[36:39], v[172:175], v[224:227], v[36:39]
	v_mfma_f32_16x16x32_bf16 v[32:35], v[192:195], v[224:227], v[32:35]
	v_mfma_f32_16x16x32_bf16 v[60:63], v[176:179], v[204:207], v[60:63]
	v_mfma_f32_16x16x32_bf16 v[56:59], v[196:199], v[204:207], v[56:59]
	v_mfma_f32_16x16x32_bf16 v[52:55], v[176:179], v[212:215], v[52:55]
	v_mfma_f32_16x16x32_bf16 v[48:51], v[196:199], v[212:215], v[48:51]
	v_mfma_f32_16x16x32_bf16 v[44:47], v[176:179], v[220:223], v[44:47]
	v_mfma_f32_16x16x32_bf16 v[40:43], v[196:199], v[220:223], v[40:43]
	v_mfma_f32_16x16x32_bf16 v[36:39], v[176:179], v[228:231], v[36:39]
	v_mfma_f32_16x16x32_bf16 v[32:35], v[196:199], v[228:231], v[32:35]
	s_barrier
	s_mov_b32 m0, s66
	v_lshl_add_u64 v[142:143], s[48:49], 0, v[144:145]
	ds_read_b128 v[200:203], v141 offset:16384
	ds_read_b128 v[204:207], v141 offset:17408
	ds_read_b128 v[208:211], v141 offset:18432
	ds_read_b128 v[212:215], v141 offset:19456
	ds_read_b128 v[216:219], v141 offset:20480
	ds_read_b128 v[220:223], v141 offset:21504
	ds_read_b128 v[224:227], v141 offset:22528
	ds_read_b128 v[228:231], v141 offset:23552
	global_load_lds_dwordx4 v[142:143], off
	v_lshl_add_u64 v[180:181], s[48:49], 0, v[128:129]
	s_mov_b32 m0, s58
	v_lshl_add_u64 v[232:233], s[50:51], 0, v[144:145]
	global_load_lds_dwordx4 v[180:181], off
	s_mov_b32 m0, s65
	v_lshl_add_u64 v[234:235], s[46:47], 0, v[130:131]
	global_load_lds_dwordx4 v[232:233], off
	v_lshl_add_u64 v[232:233], s[50:51], 0, v[128:129]
	s_mov_b32 m0, s59
	s_nop 0
	global_load_lds_dwordx4 v[232:233], off
	v_lshl_add_u64 v[232:233], s[46:47], 0, v[132:133]
	s_mov_b32 m0, s1
	s_nop 0
	global_load_lds_dwordx4 v[232:233], off
	s_mov_b32 m0, s2
	s_nop 0
	global_load_lds_dwordx4 v[234:235], off
	s_waitcnt vmcnt(8)
	s_waitcnt lgkmcnt(0)
	s_barrier
; #define PG8_STAGE(bufoff, gbase, voff) do { _Pragma("unroll") for (int _i = 0; _i < 2; ++_i) \
;         __builtin_amdgcn_global_load_lds((const unsigned*)((const char*)(gbase) + (voff)[_i]), (LAS unsigned*)(lds + (bufoff) + ldsw + _i * 8192), 16, 0, 0); } while (0)
; #define PG8_LDA(dst, b, h) do { _Pragma("unroll") for (int m = 0; m < 4; ++m) _Pragma("unroll") for (int k = 0; k < 2; ++k) dst[m][k] = *(const LAS bf16x8*)(lds + PG8_SA(b, h) + aoff + m * 2048 + k * 1024); } while (0)
; #define PG8_LDB(dst, b, h) do { _Pragma("unroll") for (int n = 0; n < 2; ++n) _Pragma("unroll") for (int k = 0; k < 2; ++k) dst[n][k] = *(const LAS bf16x8*)(lds + PG8_SB(b, h) + boff + n * 2048 + k * 1024); } while (0)
; #define PG8_MMA(ai, bj, At, Bt) do { __builtin_amdgcn_s_setprio(1); _Pragma("unroll") for (int m = 0; m < 4; ++m) _Pragma("unroll") for (int n = 0; n < 2; ++n) _Pragma("unroll") for (int k = 0; k < 2; ++k) \
;         acc[ai][bj][m][n] = __builtin_amdgcn_mfma_f32_16x16x32_bf16(Bt[n][k], At[m][k], acc[ai][bj][m][n], 0, 0, 0); __builtin_amdgcn_s_setprio(0); } while (0)
; #define PG8_WAIT_V(n) asm volatile("s_waitcnt vmcnt(" #n ")" ::: "memory")
; #define PG8_WAIT_L(n) asm volatile("s_waitcnt lgkmcnt(" #n ")" ::: "memory")
; #define PG8_BAR __builtin_amdgcn_s_barrier()
; #define PG8_SCHED __builtin_amdgcn_sched_barrier(0)
; template <class Epi, class Map>
; __device__ __forceinline__ void gemm_phase(LAS unsigned char* lds, const Gemm g, const Sched<Map>& S, const Epi& E) {
;     ...
;             PG8_WAIT_V(8); PG8_WAIT_L(0); PG8_BAR; PG8_MMA(1, 0, At, B0); PG8_MMA(1, 1, At, B1); PG8_BAR; PG8_SCHED;
;             PG8_LDB(B0, 1, 0); PG8_LDB(B1, 1, 1); PG8_SCHED; PG8_LDA(At, 1, 0); PG8_STAGE(PG8_SA(0, 1), a2 + hstepA, voffA);
;             PG8_WAIT_V(8); PG8_WAIT_L(0); PG8_BAR; PG8_MMA(0, 0, At, B0); PG8_MMA(0, 1, At, B1); PG8_BAR; PG8_SCHED;
	v_mfma_f32_16x16x32_bf16 v[92:95], v[134:137], v[200:203], v[92:95]
	v_mfma_f32_16x16x32_bf16 v[88:91], v[164:167], v[200:203], v[88:91]
	v_mfma_f32_16x16x32_bf16 v[84:87], v[134:137], v[208:211], v[84:87]
	v_mfma_f32_16x16x32_bf16 v[80:83], v[164:167], v[208:211], v[80:83]
	v_mfma_f32_16x16x32_bf16 v[76:79], v[134:137], v[216:219], v[76:79]
	v_mfma_f32_16x16x32_bf16 v[72:75], v[164:167], v[216:219], v[72:75]
	v_mfma_f32_16x16x32_bf16 v[68:71], v[134:137], v[224:227], v[68:71]
	v_mfma_f32_16x16x32_bf16 v[64:67], v[164:167], v[224:227], v[64:67]
	v_mfma_f32_16x16x32_bf16 v[92:95], v[160:163], v[204:207], v[92:95]
	v_mfma_f32_16x16x32_bf16 v[88:91], v[168:171], v[204:207], v[88:91]
	v_mfma_f32_16x16x32_bf16 v[84:87], v[160:163], v[212:215], v[84:87]
	v_mfma_f32_16x16x32_bf16 v[80:83], v[168:171], v[212:215], v[80:83]
	v_mfma_f32_16x16x32_bf16 v[76:79], v[160:163], v[220:223], v[76:79]
	v_mfma_f32_16x16x32_bf16 v[72:75], v[168:171], v[220:223], v[72:75]
	v_mfma_f32_16x16x32_bf16 v[68:71], v[160:163], v[228:231], v[68:71]
	v_mfma_f32_16x16x32_bf16 v[64:67], v[168:171], v[228:231], v[64:67]
	v_mfma_f32_16x16x32_bf16 v[28:31], v[172:175], v[200:203], v[28:31]
	v_mfma_f32_16x16x32_bf16 v[24:27], v[192:195], v[200:203], v[24:27]
	v_mfma_f32_16x16x32_bf16 v[20:23], v[172:175], v[208:211], v[20:23]
	v_mfma_f32_16x16x32_bf16 v[16:19], v[192:195], v[208:211], v[16:19]
	v_mfma_f32_16x16x32_bf16 v[12:15], v[172:175], v[216:219], v[12:15]
	v_mfma_f32_16x16x32_bf16 v[8:11], v[192:195], v[216:219], v[8:11]
	v_mfma_f32_16x16x32_bf16 v[4:7], v[172:175], v[224:227], v[4:7]
	v_mfma_f32_16x16x32_bf16 v[0:3], v[192:195], v[224:227], v[0:3]
	v_mfma_f32_16x16x32_bf16 v[28:31], v[176:179], v[204:207], v[28:31]
	v_mfma_f32_16x16x32_bf16 v[24:27], v[196:199], v[204:207], v[24:27]
	v_mfma_f32_16x16x32_bf16 v[20:23], v[176:179], v[212:215], v[20:23]
	v_mfma_f32_16x16x32_bf16 v[16:19], v[196:199], v[212:215], v[16:19]
	v_mfma_f32_16x16x32_bf16 v[12:15], v[176:179], v[220:223], v[12:15]
	v_mfma_f32_16x16x32_bf16 v[8:11], v[196:199], v[220:223], v[8:11]
	v_mfma_f32_16x16x32_bf16 v[4:7], v[176:179], v[228:231], v[4:7]
	v_mfma_f32_16x16x32_bf16 v[0:3], v[196:199], v[228:231], v[0:3]
	s_barrier
	v_add_u32_e32 v168, s57, v140
	v_add_u32_e32 v196, s56, v140
	ds_read_b128 v[134:137], v168
	ds_read_b128 v[160:163], v168 offset:1024
	ds_read_b128 v[164:167], v168 offset:2048
	ds_read_b128 v[168:171], v168 offset:3072
	ds_read_b128 v[172:175], v196
	ds_read_b128 v[176:179], v196 offset:1024
	ds_read_b128 v[192:195], v196 offset:2048
	ds_read_b128 v[196:199], v196 offset:3072
	s_mov_b32 m0, s3
	v_lshl_add_u64 v[236:237], s[44:45], 0, v[132:133]
	ds_read_b128 v[200:203], v141 offset:32768
	ds_read_b128 v[204:207], v141 offset:33792
	ds_read_b128 v[208:211], v141 offset:34816
	ds_read_b128 v[212:215], v141 offset:35840
	ds_read_b128 v[216:219], v141 offset:36864
	ds_read_b128 v[220:223], v141 offset:37888
	ds_read_b128 v[224:227], v141 offset:38912
	ds_read_b128 v[228:231], v141 offset:39936
	global_load_lds_dwordx4 v[236:237], off
	v_lshl_add_u64 v[236:237], s[44:45], 0, v[130:131]
	s_mov_b32 m0, s4
	s_nop 0
	global_load_lds_dwordx4 v[236:237], off
	s_waitcnt vmcnt(8)
	s_waitcnt lgkmcnt(0)
	s_barrier
	v_mfma_f32_16x16x32_bf16 v[124:127], v[134:137], v[200:203], v[124:127]
	v_mfma_f32_16x16x32_bf16 v[120:123], v[164:167], v[200:203], v[120:123]
	v_mfma_f32_16x16x32_bf16 v[116:119], v[134:137], v[208:211], v[116:119]
	v_mfma_f32_16x16x32_bf16 v[112:115], v[164:167], v[208:211], v[112:115]
	v_mfma_f32_16x16x32_bf16 v[108:111], v[134:137], v[216:219], v[108:111]
	v_mfma_f32_16x16x32_bf16 v[104:107], v[164:167], v[216:219], v[104:107]
	v_mfma_f32_16x16x32_bf16 v[100:103], v[134:137], v[224:227], v[100:103]
	v_mfma_f32_16x16x32_bf16 v[96:99], v[164:167], v[224:227], v[96:99]
	v_mfma_f32_16x16x32_bf16 v[124:127], v[160:163], v[204:207], v[124:127]
	v_mfma_f32_16x16x32_bf16 v[120:123], v[168:171], v[204:207], v[120:123]
	v_mfma_f32_16x16x32_bf16 v[116:119], v[160:163], v[212:215], v[116:119]
	v_mfma_f32_16x16x32_bf16 v[112:115], v[168:171], v[212:215], v[112:115]
	v_mfma_f32_16x16x32_bf16 v[108:111], v[160:163], v[220:223], v[108:111]
	v_mfma_f32_16x16x32_bf16 v[104:107], v[168:171], v[220:223], v[104:107]
	v_mfma_f32_16x16x32_bf16 v[100:103], v[160:163], v[228:231], v[100:103]
	v_mfma_f32_16x16x32_bf16 v[96:99], v[168:171], v[228:231], v[96:99]
	v_mfma_f32_16x16x32_bf16 v[60:63], v[172:175], v[200:203], v[60:63]
	v_mfma_f32_16x16x32_bf16 v[56:59], v[192:195], v[200:203], v[56:59]
	v_mfma_f32_16x16x32_bf16 v[52:55], v[172:175], v[208:211], v[52:55]
	v_mfma_f32_16x16x32_bf16 v[48:51], v[192:195], v[208:211], v[48:51]
	v_mfma_f32_16x16x32_bf16 v[44:47], v[172:175], v[216:219], v[44:47]
	v_mfma_f32_16x16x32_bf16 v[40:43], v[192:195], v[216:219], v[40:43]
	v_mfma_f32_16x16x32_bf16 v[36:39], v[172:175], v[224:227], v[36:39]
	v_mfma_f32_16x16x32_bf16 v[32:35], v[192:195], v[224:227], v[32:35]
	v_mfma_f32_16x16x32_bf16 v[60:63], v[176:179], v[204:207], v[60:63]
	v_mfma_f32_16x16x32_bf16 v[56:59], v[196:199], v[204:207], v[56:59]
	v_mfma_f32_16x16x32_bf16 v[52:55], v[176:179], v[212:215], v[52:55]
	v_mfma_f32_16x16x32_bf16 v[48:51], v[196:199], v[212:215], v[48:51]
	v_mfma_f32_16x16x32_bf16 v[44:47], v[176:179], v[220:223], v[44:47]
	v_mfma_f32_16x16x32_bf16 v[40:43], v[196:199], v[220:223], v[40:43]
	v_mfma_f32_16x16x32_bf16 v[36:39], v[176:179], v[228:231], v[36:39]
	v_mfma_f32_16x16x32_bf16 v[32:35], v[196:199], v[228:231], v[32:35]
	s_barrier
; #define PG8_STAGE(bufoff, gbase, voff) do { _Pragma("unroll") for (int _i = 0; _i < 2; ++_i) \
;         __builtin_amdgcn_global_load_lds((const unsigned*)((const char*)(gbase) + (voff)[_i]), (LAS unsigned*)(lds + (bufoff) + ldsw + _i * 8192), 16, 0, 0); } while (0)
; #define PG8_LDA(dst, b, h) do { _Pragma("unroll") for (int m = 0; m < 4; ++m) _Pragma("unroll") for (int k = 0; k < 2; ++k) dst[m][k] = *(const LAS bf16x8*)(lds + PG8_SA(b, h) + aoff + m * 2048 + k * 1024); } while (0)
; #define PG8_MMA(ai, bj, At, Bt) do { __builtin_amdgcn_s_setprio(1); _Pragma("unroll") for (int m = 0; m < 4; ++m) _Pragma("unroll") for (int n = 0; n < 2; ++n) _Pragma("unroll") for (int k = 0; k < 2; ++k) \
;         acc[ai][bj][m][n] = __builtin_amdgcn_mfma_f32_16x16x32_bf16(Bt[n][k], At[m][k], acc[ai][bj][m][n], 0, 0, 0); __builtin_amdgcn_s_setprio(0); } while (0)
; #define PG8_WAIT_V(n) asm volatile("s_waitcnt vmcnt(" #n ")" ::: "memory")
; #define PG8_WAIT_L(n) asm volatile("s_waitcnt lgkmcnt(" #n ")" ::: "memory")
; #define PG8_BAR __builtin_amdgcn_s_barrier()
; #define PG8_SCHED __builtin_amdgcn_sched_barrier(0)
; template <class Epi, class Map>
; __device__ __forceinline__ void gemm_phase(LAS unsigned char* lds, const Gemm g, const Sched<Map>& S, const Epi& E) {
;     ...
;             PG8_LDA(At, 1, 1); PG8_STAGE(PG8_SB(1, 0), b3, voffB); PG8_STAGE(PG8_SB(1, 1), b3 + hstepB, voffB); PG8_STAGE(PG8_SA(1, 0), a3, voffA);
;             PG8_WAIT_V(8); PG8_WAIT_L(0); PG8_BAR; PG8_MMA(1, 0, At, B0); PG8_MMA(1, 1, At, B1); PG8_BAR; PG8_SCHED;
;         }
;         if (wr == 0) PG8_BAR;
	s_mov_b32 m0, s55
	v_lshl_add_u64 v[142:143], v[142:143], 0, s[82:83]
	ds_read_b128 v[200:203], v141 offset:49152
	ds_read_b128 v[204:207], v141 offset:50176
	ds_read_b128 v[208:211], v141 offset:51200
	ds_read_b128 v[212:215], v141 offset:52224
	ds_read_b128 v[216:219], v141 offset:53248
	ds_read_b128 v[220:223], v141 offset:54272
	ds_read_b128 v[224:227], v141 offset:55296
	ds_read_b128 v[228:231], v141 offset:56320
	global_load_lds_dwordx4 v[142:143], off
	v_lshl_add_u64 v[142:143], v[180:181], 0, s[82:83]
	s_mov_b32 m0, s54
	s_nop 0
	global_load_lds_dwordx4 v[142:143], off
	v_lshl_add_u64 v[142:143], s[36:37], 0, v[144:145]
	s_mov_b32 m0, s68
	s_nop 0
	global_load_lds_dwordx4 v[142:143], off
	v_lshl_add_u64 v[142:143], s[36:37], 0, v[128:129]
	s_mov_b32 m0, s67
	s_nop 0
	global_load_lds_dwordx4 v[142:143], off
	v_lshl_add_u64 v[142:143], v[232:233], 0, s[82:83]
	s_mov_b32 m0, s7
	s_nop 0
	global_load_lds_dwordx4 v[142:143], off
	v_lshl_add_u64 v[142:143], v[234:235], 0, s[82:83]
	s_mov_b32 m0, s8
	s_nop 0
	global_load_lds_dwordx4 v[142:143], off
	s_waitcnt vmcnt(8)
	s_waitcnt lgkmcnt(0)
	s_barrier
	v_mfma_f32_16x16x32_bf16 v[92:95], v[134:137], v[200:203], v[92:95]
	v_mfma_f32_16x16x32_bf16 v[88:91], v[164:167], v[200:203], v[88:91]
	v_mfma_f32_16x16x32_bf16 v[84:87], v[134:137], v[208:211], v[84:87]
	v_mfma_f32_16x16x32_bf16 v[80:83], v[164:167], v[208:211], v[80:83]
	v_mfma_f32_16x16x32_bf16 v[76:79], v[134:137], v[216:219], v[76:79]
	v_mfma_f32_16x16x32_bf16 v[72:75], v[164:167], v[216:219], v[72:75]
	v_mfma_f32_16x16x32_bf16 v[68:71], v[134:137], v[224:227], v[68:71]
	v_mfma_f32_16x16x32_bf16 v[64:67], v[164:167], v[224:227], v[64:67]
	v_mfma_f32_16x16x32_bf16 v[92:95], v[160:163], v[204:207], v[92:95]
	v_mfma_f32_16x16x32_bf16 v[88:91], v[168:171], v[204:207], v[88:91]
	v_mfma_f32_16x16x32_bf16 v[84:87], v[160:163], v[212:215], v[84:87]
	v_mfma_f32_16x16x32_bf16 v[80:83], v[168:171], v[212:215], v[80:83]
	v_mfma_f32_16x16x32_bf16 v[76:79], v[160:163], v[220:223], v[76:79]
	v_mfma_f32_16x16x32_bf16 v[72:75], v[168:171], v[220:223], v[72:75]
	v_mfma_f32_16x16x32_bf16 v[68:71], v[160:163], v[228:231], v[68:71]
	v_mfma_f32_16x16x32_bf16 v[64:67], v[168:171], v[228:231], v[64:67]
	v_mfma_f32_16x16x32_bf16 v[28:31], v[172:175], v[200:203], v[28:31]
	v_mfma_f32_16x16x32_bf16 v[24:27], v[192:195], v[200:203], v[24:27]
	v_mfma_f32_16x16x32_bf16 v[20:23], v[172:175], v[208:211], v[20:23]
	v_mfma_f32_16x16x32_bf16 v[16:19], v[192:195], v[208:211], v[16:19]
	v_mfma_f32_16x16x32_bf16 v[12:15], v[172:175], v[216:219], v[12:15]
	v_mfma_f32_16x16x32_bf16 v[8:11], v[192:195], v[216:219], v[8:11]
	v_mfma_f32_16x16x32_bf16 v[4:7], v[172:175], v[224:227], v[4:7]
	v_mfma_f32_16x16x32_bf16 v[0:3], v[192:195], v[224:227], v[0:3]
	v_mfma_f32_16x16x32_bf16 v[28:31], v[176:179], v[204:207], v[28:31]
	v_mfma_f32_16x16x32_bf16 v[24:27], v[196:199], v[204:207], v[24:27]
	v_mfma_f32_16x16x32_bf16 v[20:23], v[176:179], v[212:215], v[20:23]
	v_mfma_f32_16x16x32_bf16 v[16:19], v[196:199], v[212:215], v[16:19]
	v_mfma_f32_16x16x32_bf16 v[12:15], v[176:179], v[220:223], v[12:15]
	v_mfma_f32_16x16x32_bf16 v[8:11], v[196:199], v[220:223], v[8:11]
	v_mfma_f32_16x16x32_bf16 v[4:7], v[176:179], v[228:231], v[4:7]
	v_mfma_f32_16x16x32_bf16 v[0:3], v[196:199], v[228:231], v[0:3]
	s_barrier
	s_andn2_b64 vcc, exec, s[34:35]
	s_mov_b64 s[36:37], -1
	s_mov_b64 s[34:35], 0
	s_mov_b64 s[44:45], 0x100
	s_cbranch_vccz .LBB0_659
	s_and_b64 vcc, exec, s[18:19]
	s_cbranch_vccz .LBB0_662
	s_barrier

; #define PG8_STAGE(bufoff, gbase, voff) do { _Pragma("unroll") for (int _i = 0; _i < 2; ++_i) \
;         __builtin_amdgcn_global_load_lds((const unsigned*)((const char*)(gbase) + (voff)[_i]), (LAS unsigned*)(lds + (bufoff) + ldsw + _i * 8192), 16, 0, 0); } while (0)
; #define PG8_LDA(dst, b, h) do { _Pragma("unroll") for (int m = 0; m < 4; ++m) _Pragma("unroll") for (int k = 0; k < 2; ++k) dst[m][k] = *(const LAS bf16x8*)(lds + PG8_SA(b, h) + aoff + m * 2048 + k * 1024); } while (0)
; #define PG8_LDB(dst, b, h) do { _Pragma("unroll") for (int n = 0; n < 2; ++n) _Pragma("unroll") for (int k = 0; k < 2; ++k) dst[n][k] = *(const LAS bf16x8*)(lds + PG8_SB(b, h) + boff + n * 2048 + k * 1024); } while (0)
; #define PG8_MMA(ai, bj, At, Bt) do { __builtin_amdgcn_s_setprio(1); _Pragma("unroll") for (int m = 0; m < 4; ++m) _Pragma("unroll") for (int n = 0; n < 2; ++n) _Pragma("unroll") for (int k = 0; k < 2; ++k) \
;         acc[ai][bj][m][n] = __builtin_amdgcn_mfma_f32_16x16x32_bf16(Bt[n][k], At[m][k], acc[ai][bj][m][n], 0, 0, 0); __builtin_amdgcn_s_setprio(0); } while (0)
; #define PG8_WAIT_V(n) asm volatile("s_waitcnt vmcnt(" #n ")" ::: "memory")
; #define PG8_WAIT_L(n) asm volatile("s_waitcnt lgkmcnt(" #n ")" ::: "memory")
; #define PG8_BAR __builtin_amdgcn_s_barrier()
; #define PG8_SCHED __builtin_amdgcn_sched_barrier(0)
; template <class Epi, class Map>
; __device__ __forceinline__ void gemm_phase(LAS unsigned char* lds, const Gemm g, const Sched<Map>& S, const Epi& E) {
;     ...
;         for (int t = 0; t < nt; t += 2) {
;             const bool last = (t == nt - 2);
;             const char* a1 = cA + (size_t)(t + 1) * kstep;
;             const char* a2 = last ? nA : cA + (size_t)(t + 2) * kstep; const char* b2 = last ? nB : cB + (size_t)(t + 2) * kstep;
;             const char* a3 = a2 + kstep; const char* b3 = b2 + kstep;
;             PG8_LDB(B0, 0, 0); PG8_LDB(B1, 0, 1); PG8_SCHED; PG8_LDA(At, 0, 0); PG8_STAGE(PG8_SA(1, 1), a1 + hstepA, voffA);
;             PG8_WAIT_V(8); PG8_WAIT_L(0); PG8_BAR; PG8_MMA(0, 0, At, B0); PG8_MMA(0, 1, At, B1); PG8_BAR; PG8_SCHED;
;             PG8_LDA(At, 0, 1); PG8_STAGE(PG8_SB(0, 0), b2, voffB); PG8_STAGE(PG8_SB(0, 1), b2 + hstepB, voffB); PG8_STAGE(PG8_SA(0, 0), a2, voffA);
.LBB0_679:
	s_add_u32 s21, s34, s46
	s_addc_u32 s33, s35, s47
	s_add_u32 s48, s21, 0x100
	s_addc_u32 s49, s33, 0
	s_and_b64 s[38:39], s[44:45], exec
	s_cselect_b32 s49, s12, s49
	s_cselect_b32 s48, s13, s48
	s_add_u32 s38, s30, s46
	s_addc_u32 s39, s31, s47
	s_add_u32 s46, s38, 0x100
	s_addc_u32 s47, s39, 0
	s_add_i32 s62, 0, 0x10000
	s_and_b64 s[38:39], s[44:45], exec
	s_cselect_b32 s51, s14, s47
	s_cselect_b32 s50, s15, s46
	s_add_i32 s45, 0, 0x14000
	s_add_u32 s54, s21, 0x20080
	s_addc_u32 s55, s33, 0
	s_add_i32 s59, s62, s0
	s_add_i32 m0, s1, 0xc000
	s_add_i32 s63, s1, 0xe000
	s_add_i32 s56, s59, 0x2000
	v_add_u32_e32 v134, s62, v138
	s_add_u32 s52, s50, 0x10000
	ds_read_b128 v[140:143], v134
	ds_read_b128 v[160:163], v134 offset:1024
	ds_read_b128 v[164:167], v134 offset:2048
	ds_read_b128 v[168:171], v134 offset:3072
	v_add_u32_e32 v134, s45, v138
	s_addc_u32 s53, s51, 0
	s_add_i32 s58, s45, s0
	ds_read_b128 v[172:175], v134
	ds_read_b128 v[176:179], v134 offset:1024
	ds_read_b128 v[192:195], v134 offset:2048
	ds_read_b128 v[196:199], v134 offset:3072
	s_add_i32 s57, s58, 0x2000
	s_add_i32 s39, 0, 0x18000
	s_add_i32 s38, 0, 0x1c000
	s_add_u32 s46, s48, 0x20000
	s_addc_u32 s47, s49, 0
	s_add_i32 s33, s39, s0
	s_add_i32 s21, s33, 0x2000
	s_add_u32 s44, s50, 0x10080
	s_addc_u32 s45, s51, 0
	s_add_i32 s66, s38, s0
	s_add_i32 s65, s66, 0x2000
	v_lshl_add_u64 v[134:135], s[54:55], 0, v[132:133]
	ds_read_b128 v[200:203], v139
	ds_read_b128 v[204:207], v139 offset:1024
	ds_read_b128 v[208:211], v139 offset:2048
	ds_read_b128 v[212:215], v139 offset:3072
	ds_read_b128 v[216:219], v139 offset:4096
	ds_read_b128 v[220:223], v139 offset:5120
	ds_read_b128 v[224:227], v139 offset:6144
	ds_read_b128 v[228:231], v139 offset:7168
	global_load_lds_dwordx4 v[134:135], off
	v_lshl_add_u64 v[134:135], s[54:55], 0, v[130:131]
	s_mov_b32 m0, s63
	s_nop 0
	global_load_lds_dwordx4 v[134:135], off
	s_waitcnt vmcnt(8)
	s_waitcnt lgkmcnt(0)
	s_barrier
	v_mfma_f32_16x16x32_bf16 v[124:127], v[140:143], v[200:203], v[124:127]
	v_mfma_f32_16x16x32_bf16 v[120:123], v[164:167], v[200:203], v[120:123]
	v_mfma_f32_16x16x32_bf16 v[116:119], v[140:143], v[208:211], v[116:119]
	v_mfma_f32_16x16x32_bf16 v[108:111], v[164:167], v[208:211], v[108:111]
	v_mfma_f32_16x16x32_bf16 v[100:103], v[140:143], v[216:219], v[100:103]
	v_mfma_f32_16x16x32_bf16 v[92:95], v[164:167], v[216:219], v[92:95]
	v_mfma_f32_16x16x32_bf16 v[84:87], v[140:143], v[224:227], v[84:87]
	v_mfma_f32_16x16x32_bf16 v[76:79], v[164:167], v[224:227], v[76:79]
	v_mfma_f32_16x16x32_bf16 v[124:127], v[160:163], v[204:207], v[124:127]
	v_mfma_f32_16x16x32_bf16 v[120:123], v[168:171], v[204:207], v[120:123]
	v_mfma_f32_16x16x32_bf16 v[116:119], v[160:163], v[212:215], v[116:119]
	v_mfma_f32_16x16x32_bf16 v[108:111], v[168:171], v[212:215], v[108:111]
	v_mfma_f32_16x16x32_bf16 v[100:103], v[160:163], v[220:223], v[100:103]
	v_mfma_f32_16x16x32_bf16 v[92:95], v[168:171], v[220:223], v[92:95]
	v_mfma_f32_16x16x32_bf16 v[84:87], v[160:163], v[228:231], v[84:87]
	v_mfma_f32_16x16x32_bf16 v[76:79], v[168:171], v[228:231], v[76:79]
	v_mfma_f32_16x16x32_bf16 v[112:115], v[172:175], v[200:203], v[112:115]
	v_mfma_f32_16x16x32_bf16 v[104:107], v[192:195], v[200:203], v[104:107]
	v_mfma_f32_16x16x32_bf16 v[96:99], v[172:175], v[208:211], v[96:99]
	v_mfma_f32_16x16x32_bf16 v[88:91], v[192:195], v[208:211], v[88:91]
	v_mfma_f32_16x16x32_bf16 v[80:83], v[172:175], v[216:219], v[80:83]
	v_mfma_f32_16x16x32_bf16 v[72:75], v[192:195], v[216:219], v[72:75]
	v_mfma_f32_16x16x32_bf16 v[68:71], v[172:175], v[224:227], v[68:71]
	v_mfma_f32_16x16x32_bf16 v[64:67], v[192:195], v[224:227], v[64:67]
	v_mfma_f32_16x16x32_bf16 v[112:115], v[176:179], v[204:207], v[112:115]
	v_mfma_f32_16x16x32_bf16 v[104:107], v[196:199], v[204:207], v[104:107]
	v_mfma_f32_16x16x32_bf16 v[96:99], v[176:179], v[212:215], v[96:99]
	v_mfma_f32_16x16x32_bf16 v[88:91], v[196:199], v[212:215], v[88:91]
	v_mfma_f32_16x16x32_bf16 v[80:83], v[176:179], v[220:223], v[80:83]
	v_mfma_f32_16x16x32_bf16 v[72:75], v[196:199], v[220:223], v[72:75]
	v_mfma_f32_16x16x32_bf16 v[68:71], v[176:179], v[228:231], v[68:71]
	v_mfma_f32_16x16x32_bf16 v[64:67], v[196:199], v[228:231], v[64:67]
	s_barrier
	s_mov_b32 m0, s59
	v_lshl_add_u64 v[134:135], s[50:51], 0, v[144:145]
	ds_read_b128 v[200:203], v139 offset:16384
	ds_read_b128 v[204:207], v139 offset:17408
	ds_read_b128 v[208:211], v139 offset:18432
	ds_read_b128 v[212:215], v139 offset:19456
	ds_read_b128 v[216:219], v139 offset:20480
	ds_read_b128 v[220:223], v139 offset:21504
	ds_read_b128 v[224:227], v139 offset:22528
	ds_read_b128 v[228:231], v139 offset:23552
	global_load_lds_dwordx4 v[134:135], off
	v_lshl_add_u64 v[180:181], s[50:51], 0, v[128:129]
	s_mov_b32 m0, s56
	v_lshl_add_u64 v[232:233], s[52:53], 0, v[144:145]
	global_load_lds_dwordx4 v[180:181], off
	s_mov_b32 m0, s58
	v_lshl_add_u64 v[234:235], s[48:49], 0, v[130:131]
	global_load_lds_dwordx4 v[232:233], off
	v_lshl_add_u64 v[232:233], s[52:53], 0, v[128:129]
	s_mov_b32 m0, s57
	s_nop 0
	global_load_lds_dwordx4 v[232:233], off
	v_lshl_add_u64 v[232:233], s[48:49], 0, v[132:133]
	s_mov_b32 m0, s1
	s_nop 0
	global_load_lds_dwordx4 v[232:233], off
	s_mov_b32 m0, s2
	s_nop 0
	global_load_lds_dwordx4 v[234:235], off
	s_waitcnt vmcnt(8)
	s_waitcnt lgkmcnt(0)
	s_barrier
; #define PG8_STAGE(bufoff, gbase, voff) do { _Pragma("unroll") for (int _i = 0; _i < 2; ++_i) \
;         __builtin_amdgcn_global_load_lds((const unsigned*)((const char*)(gbase) + (voff)[_i]), (LAS unsigned*)(lds + (bufoff) + ldsw + _i * 8192), 16, 0, 0); } while (0)
; #define PG8_LDA(dst, b, h) do { _Pragma("unroll") for (int m = 0; m < 4; ++m) _Pragma("unroll") for (int k = 0; k < 2; ++k) dst[m][k] = *(const LAS bf16x8*)(lds + PG8_SA(b, h) + aoff + m * 2048 + k * 1024); } while (0)
; #define PG8_LDB(dst, b, h) do { _Pragma("unroll") for (int n = 0; n < 2; ++n) _Pragma("unroll") for (int k = 0; k < 2; ++k) dst[n][k] = *(const LAS bf16x8*)(lds + PG8_SB(b, h) + boff + n * 2048 + k * 1024); } while (0)
; #define PG8_MMA(ai, bj, At, Bt) do { __builtin_amdgcn_s_setprio(1); _Pragma("unroll") for (int m = 0; m < 4; ++m) _Pragma("unroll") for (int n = 0; n < 2; ++n) _Pragma("unroll") for (int k = 0; k < 2; ++k) \
;         acc[ai][bj][m][n] = __builtin_amdgcn_mfma_f32_16x16x32_bf16(Bt[n][k], At[m][k], acc[ai][bj][m][n], 0, 0, 0); __builtin_amdgcn_s_setprio(0); } while (0)
; #define PG8_WAIT_V(n) asm volatile("s_waitcnt vmcnt(" #n ")" ::: "memory")
; #define PG8_WAIT_L(n) asm volatile("s_waitcnt lgkmcnt(" #n ")" ::: "memory")
; #define PG8_BAR __builtin_amdgcn_s_barrier()
; #define PG8_SCHED __builtin_amdgcn_sched_barrier(0)
; template <class Epi, class Map>
; __device__ __forceinline__ void gemm_phase(LAS unsigned char* lds, const Gemm g, const Sched<Map>& S, const Epi& E) {
;     ...
;             PG8_WAIT_V(8); PG8_WAIT_L(0); PG8_BAR; PG8_MMA(1, 0, At, B0); PG8_MMA(1, 1, At, B1); PG8_BAR; PG8_SCHED;
;             PG8_LDB(B0, 1, 0); PG8_LDB(B1, 1, 1); PG8_SCHED; PG8_LDA(At, 1, 0); PG8_STAGE(PG8_SA(0, 1), a2 + hstepA, voffA);
;             PG8_WAIT_V(8); PG8_WAIT_L(0); PG8_BAR; PG8_MMA(0, 0, At, B0); PG8_MMA(0, 1, At, B1); PG8_BAR; PG8_SCHED;
	v_mfma_f32_16x16x32_bf16 v[60:63], v[140:143], v[200:203], v[60:63]
	v_mfma_f32_16x16x32_bf16 v[56:59], v[164:167], v[200:203], v[56:59]
	v_mfma_f32_16x16x32_bf16 v[52:55], v[140:143], v[208:211], v[52:55]
	v_mfma_f32_16x16x32_bf16 v[44:47], v[164:167], v[208:211], v[44:47]
	v_mfma_f32_16x16x32_bf16 v[36:39], v[140:143], v[216:219], v[36:39]
	v_mfma_f32_16x16x32_bf16 v[28:31], v[164:167], v[216:219], v[28:31]
	v_mfma_f32_16x16x32_bf16 v[20:23], v[140:143], v[224:227], v[20:23]
	v_mfma_f32_16x16x32_bf16 v[12:15], v[164:167], v[224:227], v[12:15]
	v_mfma_f32_16x16x32_bf16 v[60:63], v[160:163], v[204:207], v[60:63]
	v_mfma_f32_16x16x32_bf16 v[56:59], v[168:171], v[204:207], v[56:59]
	v_mfma_f32_16x16x32_bf16 v[52:55], v[160:163], v[212:215], v[52:55]
	v_mfma_f32_16x16x32_bf16 v[44:47], v[168:171], v[212:215], v[44:47]
	v_mfma_f32_16x16x32_bf16 v[36:39], v[160:163], v[220:223], v[36:39]
	v_mfma_f32_16x16x32_bf16 v[28:31], v[168:171], v[220:223], v[28:31]
	v_mfma_f32_16x16x32_bf16 v[20:23], v[160:163], v[228:231], v[20:23]
	v_mfma_f32_16x16x32_bf16 v[12:15], v[168:171], v[228:231], v[12:15]
	v_mfma_f32_16x16x32_bf16 v[48:51], v[172:175], v[200:203], v[48:51]
	v_mfma_f32_16x16x32_bf16 v[40:43], v[192:195], v[200:203], v[40:43]
	v_mfma_f32_16x16x32_bf16 v[32:35], v[172:175], v[208:211], v[32:35]
	v_mfma_f32_16x16x32_bf16 v[24:27], v[192:195], v[208:211], v[24:27]
	v_mfma_f32_16x16x32_bf16 v[16:19], v[172:175], v[216:219], v[16:19]
	v_mfma_f32_16x16x32_bf16 v[8:11], v[192:195], v[216:219], v[8:11]
	v_mfma_f32_16x16x32_bf16 v[4:7], v[172:175], v[224:227], v[4:7]
	v_mfma_f32_16x16x32_bf16 v[0:3], v[192:195], v[224:227], v[0:3]
	v_mfma_f32_16x16x32_bf16 v[48:51], v[176:179], v[204:207], v[48:51]
	v_mfma_f32_16x16x32_bf16 v[40:43], v[196:199], v[204:207], v[40:43]
	v_mfma_f32_16x16x32_bf16 v[32:35], v[176:179], v[212:215], v[32:35]
	v_mfma_f32_16x16x32_bf16 v[24:27], v[196:199], v[212:215], v[24:27]
	v_mfma_f32_16x16x32_bf16 v[16:19], v[176:179], v[220:223], v[16:19]
	v_mfma_f32_16x16x32_bf16 v[8:11], v[196:199], v[220:223], v[8:11]
	v_mfma_f32_16x16x32_bf16 v[4:7], v[176:179], v[228:231], v[4:7]
	v_mfma_f32_16x16x32_bf16 v[0:3], v[196:199], v[228:231], v[0:3]
	s_barrier
	v_add_u32_e32 v168, s39, v138
	v_add_u32_e32 v196, s38, v138
	ds_read_b128 v[140:143], v168
	ds_read_b128 v[160:163], v168 offset:1024
	ds_read_b128 v[164:167], v168 offset:2048
	ds_read_b128 v[168:171], v168 offset:3072
	ds_read_b128 v[172:175], v196
	ds_read_b128 v[176:179], v196 offset:1024
	ds_read_b128 v[192:195], v196 offset:2048
	ds_read_b128 v[196:199], v196 offset:3072
	s_mov_b32 m0, s3
	v_lshl_add_u64 v[236:237], s[46:47], 0, v[132:133]
	ds_read_b128 v[200:203], v139 offset:32768
	ds_read_b128 v[204:207], v139 offset:33792
	ds_read_b128 v[208:211], v139 offset:34816
	ds_read_b128 v[212:215], v139 offset:35840
	ds_read_b128 v[216:219], v139 offset:36864
	ds_read_b128 v[220:223], v139 offset:37888
	ds_read_b128 v[224:227], v139 offset:38912
	ds_read_b128 v[228:231], v139 offset:39936
	global_load_lds_dwordx4 v[236:237], off
	v_lshl_add_u64 v[236:237], s[46:47], 0, v[130:131]
	s_mov_b32 m0, s4
	s_nop 0
	global_load_lds_dwordx4 v[236:237], off
	s_waitcnt vmcnt(8)
	s_waitcnt lgkmcnt(0)
	s_barrier
	v_mfma_f32_16x16x32_bf16 v[124:127], v[140:143], v[200:203], v[124:127]
	v_mfma_f32_16x16x32_bf16 v[120:123], v[164:167], v[200:203], v[120:123]
	v_mfma_f32_16x16x32_bf16 v[116:119], v[140:143], v[208:211], v[116:119]
	v_mfma_f32_16x16x32_bf16 v[108:111], v[164:167], v[208:211], v[108:111]
	v_mfma_f32_16x16x32_bf16 v[100:103], v[140:143], v[216:219], v[100:103]
	v_mfma_f32_16x16x32_bf16 v[92:95], v[164:167], v[216:219], v[92:95]
	v_mfma_f32_16x16x32_bf16 v[84:87], v[140:143], v[224:227], v[84:87]
	v_mfma_f32_16x16x32_bf16 v[76:79], v[164:167], v[224:227], v[76:79]
	v_mfma_f32_16x16x32_bf16 v[124:127], v[160:163], v[204:207], v[124:127]
	v_mfma_f32_16x16x32_bf16 v[120:123], v[168:171], v[204:207], v[120:123]
	v_mfma_f32_16x16x32_bf16 v[116:119], v[160:163], v[212:215], v[116:119]
	v_mfma_f32_16x16x32_bf16 v[108:111], v[168:171], v[212:215], v[108:111]
	v_mfma_f32_16x16x32_bf16 v[100:103], v[160:163], v[220:223], v[100:103]
	v_mfma_f32_16x16x32_bf16 v[92:95], v[168:171], v[220:223], v[92:95]
	v_mfma_f32_16x16x32_bf16 v[84:87], v[160:163], v[228:231], v[84:87]
	v_mfma_f32_16x16x32_bf16 v[76:79], v[168:171], v[228:231], v[76:79]
	v_mfma_f32_16x16x32_bf16 v[112:115], v[172:175], v[200:203], v[112:115]
	v_mfma_f32_16x16x32_bf16 v[104:107], v[192:195], v[200:203], v[104:107]
	v_mfma_f32_16x16x32_bf16 v[96:99], v[172:175], v[208:211], v[96:99]
	v_mfma_f32_16x16x32_bf16 v[88:91], v[192:195], v[208:211], v[88:91]
	v_mfma_f32_16x16x32_bf16 v[80:83], v[172:175], v[216:219], v[80:83]
	v_mfma_f32_16x16x32_bf16 v[72:75], v[192:195], v[216:219], v[72:75]
	v_mfma_f32_16x16x32_bf16 v[68:71], v[172:175], v[224:227], v[68:71]
	v_mfma_f32_16x16x32_bf16 v[64:67], v[192:195], v[224:227], v[64:67]
	v_mfma_f32_16x16x32_bf16 v[112:115], v[176:179], v[204:207], v[112:115]
	v_mfma_f32_16x16x32_bf16 v[104:107], v[196:199], v[204:207], v[104:107]
	v_mfma_f32_16x16x32_bf16 v[96:99], v[176:179], v[212:215], v[96:99]
	v_mfma_f32_16x16x32_bf16 v[88:91], v[196:199], v[212:215], v[88:91]
	v_mfma_f32_16x16x32_bf16 v[80:83], v[176:179], v[220:223], v[80:83]
	v_mfma_f32_16x16x32_bf16 v[72:75], v[196:199], v[220:223], v[72:75]
	v_mfma_f32_16x16x32_bf16 v[68:71], v[176:179], v[228:231], v[68:71]
	v_mfma_f32_16x16x32_bf16 v[64:67], v[196:199], v[228:231], v[64:67]
	s_barrier
; #define PG8_STAGE(bufoff, gbase, voff) do { _Pragma("unroll") for (int _i = 0; _i < 2; ++_i) \
;         __builtin_amdgcn_global_load_lds((const unsigned*)((const char*)(gbase) + (voff)[_i]), (LAS unsigned*)(lds + (bufoff) + ldsw + _i * 8192), 16, 0, 0); } while (0)
; #define PG8_LDA(dst, b, h) do { _Pragma("unroll") for (int m = 0; m < 4; ++m) _Pragma("unroll") for (int k = 0; k < 2; ++k) dst[m][k] = *(const LAS bf16x8*)(lds + PG8_SA(b, h) + aoff + m * 2048 + k * 1024); } while (0)
; #define PG8_MMA(ai, bj, At, Bt) do { __builtin_amdgcn_s_setprio(1); _Pragma("unroll") for (int m = 0; m < 4; ++m) _Pragma("unroll") for (int n = 0; n < 2; ++n) _Pragma("unroll") for (int k = 0; k < 2; ++k) \
;         acc[ai][bj][m][n] = __builtin_amdgcn_mfma_f32_16x16x32_bf16(Bt[n][k], At[m][k], acc[ai][bj][m][n], 0, 0, 0); __builtin_amdgcn_s_setprio(0); } while (0)
; #define PG8_WAIT_V(n) asm volatile("s_waitcnt vmcnt(" #n ")" ::: "memory")
; #define PG8_WAIT_L(n) asm volatile("s_waitcnt lgkmcnt(" #n ")" ::: "memory")
; #define PG8_BAR __builtin_amdgcn_s_barrier()
; #define PG8_SCHED __builtin_amdgcn_sched_barrier(0)
; template <class Epi, class Map>
; __device__ __forceinline__ void gemm_phase(LAS unsigned char* lds, const Gemm g, const Sched<Map>& S, const Epi& E) {
;     ...
;             PG8_LDA(At, 1, 1); PG8_STAGE(PG8_SB(1, 0), b3, voffB); PG8_STAGE(PG8_SB(1, 1), b3 + hstepB, voffB); PG8_STAGE(PG8_SA(1, 0), a3, voffA);
;             PG8_WAIT_V(8); PG8_WAIT_L(0); PG8_BAR; PG8_MMA(1, 0, At, B0); PG8_MMA(1, 1, At, B1); PG8_BAR; PG8_SCHED;
;         }
;         if (wr == 0) PG8_BAR;
	s_mov_b32 m0, s33
	v_lshl_add_u64 v[134:135], v[134:135], 0, s[82:83]
	ds_read_b128 v[200:203], v139 offset:49152
	ds_read_b128 v[204:207], v139 offset:50176
	ds_read_b128 v[208:211], v139 offset:51200
	ds_read_b128 v[212:215], v139 offset:52224
	ds_read_b128 v[216:219], v139 offset:53248
	ds_read_b128 v[220:223], v139 offset:54272
	ds_read_b128 v[224:227], v139 offset:55296
	ds_read_b128 v[228:231], v139 offset:56320
	global_load_lds_dwordx4 v[134:135], off
	v_lshl_add_u64 v[134:135], v[180:181], 0, s[82:83]
	s_mov_b32 m0, s21
	s_nop 0
	global_load_lds_dwordx4 v[134:135], off
	v_lshl_add_u64 v[134:135], s[44:45], 0, v[144:145]
	s_mov_b32 m0, s66
	s_nop 0
	global_load_lds_dwordx4 v[134:135], off
	v_lshl_add_u64 v[134:135], s[44:45], 0, v[128:129]
	s_mov_b32 m0, s65
	s_nop 0
	global_load_lds_dwordx4 v[134:135], off
	v_lshl_add_u64 v[134:135], v[232:233], 0, s[82:83]
	s_mov_b32 m0, s6
	s_nop 0
	global_load_lds_dwordx4 v[134:135], off
	v_lshl_add_u64 v[134:135], v[234:235], 0, s[82:83]
	s_mov_b32 m0, s7
	s_nop 0
	global_load_lds_dwordx4 v[134:135], off
	s_waitcnt vmcnt(8)
	s_waitcnt lgkmcnt(0)
	s_barrier
	v_mfma_f32_16x16x32_bf16 v[60:63], v[140:143], v[200:203], v[60:63]
	v_mfma_f32_16x16x32_bf16 v[56:59], v[164:167], v[200:203], v[56:59]
	v_mfma_f32_16x16x32_bf16 v[52:55], v[140:143], v[208:211], v[52:55]
	v_mfma_f32_16x16x32_bf16 v[44:47], v[164:167], v[208:211], v[44:47]
	v_mfma_f32_16x16x32_bf16 v[36:39], v[140:143], v[216:219], v[36:39]
	v_mfma_f32_16x16x32_bf16 v[28:31], v[164:167], v[216:219], v[28:31]
	v_mfma_f32_16x16x32_bf16 v[20:23], v[140:143], v[224:227], v[20:23]
	v_mfma_f32_16x16x32_bf16 v[12:15], v[164:167], v[224:227], v[12:15]
	v_mfma_f32_16x16x32_bf16 v[60:63], v[160:163], v[204:207], v[60:63]
	v_mfma_f32_16x16x32_bf16 v[56:59], v[168:171], v[204:207], v[56:59]
	v_mfma_f32_16x16x32_bf16 v[52:55], v[160:163], v[212:215], v[52:55]
	v_mfma_f32_16x16x32_bf16 v[44:47], v[168:171], v[212:215], v[44:47]
	v_mfma_f32_16x16x32_bf16 v[36:39], v[160:163], v[220:223], v[36:39]
	v_mfma_f32_16x16x32_bf16 v[28:31], v[168:171], v[220:223], v[28:31]
	v_mfma_f32_16x16x32_bf16 v[20:23], v[160:163], v[228:231], v[20:23]
	v_mfma_f32_16x16x32_bf16 v[12:15], v[168:171], v[228:231], v[12:15]
	v_mfma_f32_16x16x32_bf16 v[48:51], v[172:175], v[200:203], v[48:51]
	v_mfma_f32_16x16x32_bf16 v[40:43], v[192:195], v[200:203], v[40:43]
	v_mfma_f32_16x16x32_bf16 v[32:35], v[172:175], v[208:211], v[32:35]
	v_mfma_f32_16x16x32_bf16 v[24:27], v[192:195], v[208:211], v[24:27]
	v_mfma_f32_16x16x32_bf16 v[16:19], v[172:175], v[216:219], v[16:19]
	v_mfma_f32_16x16x32_bf16 v[8:11], v[192:195], v[216:219], v[8:11]
	v_mfma_f32_16x16x32_bf16 v[4:7], v[172:175], v[224:227], v[4:7]
	v_mfma_f32_16x16x32_bf16 v[0:3], v[192:195], v[224:227], v[0:3]
	v_mfma_f32_16x16x32_bf16 v[48:51], v[176:179], v[204:207], v[48:51]
	v_mfma_f32_16x16x32_bf16 v[40:43], v[196:199], v[204:207], v[40:43]
	v_mfma_f32_16x16x32_bf16 v[32:35], v[176:179], v[212:215], v[32:35]
	v_mfma_f32_16x16x32_bf16 v[24:27], v[196:199], v[212:215], v[24:27]
	v_mfma_f32_16x16x32_bf16 v[16:19], v[176:179], v[220:223], v[16:19]
	v_mfma_f32_16x16x32_bf16 v[8:11], v[196:199], v[220:223], v[8:11]
	v_mfma_f32_16x16x32_bf16 v[4:7], v[176:179], v[228:231], v[4:7]
	v_mfma_f32_16x16x32_bf16 v[0:3], v[196:199], v[228:231], v[0:3]
	s_barrier
	s_andn2_b64 vcc, exec, s[36:37]
	s_mov_b64 s[44:45], -1
	s_mov_b64 s[36:37], 0
	s_mov_b64 s[46:47], 0x100
	s_cbranch_vccz .LBB0_679
	s_and_b64 vcc, exec, s[18:19]
	s_cbranch_vccz .LBB0_682
	s_barrier

; #define PG8_STAGE(bufoff, gbase, voff) do { _Pragma("unroll") for (int _i = 0; _i < 2; ++_i) \
;         __builtin_amdgcn_global_load_lds((const unsigned*)((const char*)(gbase) + (voff)[_i]), (LAS unsigned*)(lds + (bufoff) + ldsw + _i * 8192), 16, 0, 0); } while (0)
; #define PG8_LDA(dst, b, h) do { _Pragma("unroll") for (int m = 0; m < 4; ++m) _Pragma("unroll") for (int k = 0; k < 2; ++k) dst[m][k] = *(const LAS bf16x8*)(lds + PG8_SA(b, h) + aoff + m * 2048 + k * 1024); } while (0)
; #define PG8_LDB(dst, b, h) do { _Pragma("unroll") for (int n = 0; n < 2; ++n) _Pragma("unroll") for (int k = 0; k < 2; ++k) dst[n][k] = *(const LAS bf16x8*)(lds + PG8_SB(b, h) + boff + n * 2048 + k * 1024); } while (0)
; #define PG8_MMA(ai, bj, At, Bt) do { __builtin_amdgcn_s_setprio(1); _Pragma("unroll") for (int m = 0; m < 4; ++m) _Pragma("unroll") for (int n = 0; n < 2; ++n) _Pragma("unroll") for (int k = 0; k < 2; ++k) \
;         acc[ai][bj][m][n] = __builtin_amdgcn_mfma_f32_16x16x32_bf16(Bt[n][k], At[m][k], acc[ai][bj][m][n], 0, 0, 0); __builtin_amdgcn_s_setprio(0); } while (0)
; #define PG8_WAIT_V(n) asm volatile("s_waitcnt vmcnt(" #n ")" ::: "memory")
; #define PG8_WAIT_L(n) asm volatile("s_waitcnt lgkmcnt(" #n ")" ::: "memory")
; #define PG8_BAR __builtin_amdgcn_s_barrier()
; #define PG8_SCHED __builtin_amdgcn_sched_barrier(0)
; template <class Epi, class Map>
; __device__ __forceinline__ void gemm_phase(LAS unsigned char* lds, const Gemm g, const Sched<Map>& S, const Epi& E) {
;     ...
;         for (int t = 0; t < nt; t += 2) {
;             const bool last = (t == nt - 2);
;             const char* a1 = cA + (size_t)(t + 1) * kstep;
;             const char* a2 = last ? nA : cA + (size_t)(t + 2) * kstep; const char* b2 = last ? nB : cB + (size_t)(t + 2) * kstep;
;             const char* a3 = a2 + kstep; const char* b3 = b2 + kstep;
;             PG8_LDB(B0, 0, 0); PG8_LDB(B1, 0, 1); PG8_SCHED; PG8_LDA(At, 0, 0); PG8_STAGE(PG8_SA(1, 1), a1 + hstepA, voffA);
;             PG8_WAIT_V(8); PG8_WAIT_L(0); PG8_BAR; PG8_MMA(0, 0, At, B0); PG8_MMA(0, 1, At, B1); PG8_BAR; PG8_SCHED;
;             PG8_LDA(At, 0, 1); PG8_STAGE(PG8_SB(0, 0), b2, voffB); PG8_STAGE(PG8_SB(0, 1), b2 + hstepB, voffB); PG8_STAGE(PG8_SA(0, 0), a2, voffA);
.LBB0_808:
	s_add_u32 s36, s34, 0xfffe0080
	s_addc_u32 s37, s35, -1
	s_add_i32 s48, 0, 0x10000
	s_cmp_eq_u32 s47, 4
	s_cselect_b32 s45, s21, s37
	s_cselect_b32 s44, s25, s36
	v_add_u32_e32 v161, s48, v159
	s_cselect_b32 s37, s33, s46
	s_cselect_b32 s36, s38, s39
	s_add_i32 s50, 0, 0x14000
	ds_read_b128 v[138:141], v161
	ds_read_b128 v[162:165], v161 offset:1024
	ds_read_b128 v[166:169], v161 offset:2048
	ds_read_b128 v[170:173], v161 offset:3072
	v_add_u32_e32 v161, s50, v159
	ds_read_b128 v[174:177], v161
	ds_read_b128 v[178:181], v161 offset:1024
	ds_read_b128 v[192:195], v161 offset:2048
	ds_read_b128 v[196:199], v161 offset:3072
	v_lshl_add_u64 v[232:233], s[34:35], 0, v[134:135]
	s_add_i32 m0, s1, 0xc000
	ds_read_b128 v[200:203], v160
	ds_read_b128 v[204:207], v160 offset:1024
	ds_read_b128 v[208:211], v160 offset:2048
	ds_read_b128 v[212:215], v160 offset:3072
	ds_read_b128 v[216:219], v160 offset:4096
	ds_read_b128 v[220:223], v160 offset:5120
	ds_read_b128 v[224:227], v160 offset:6144
	ds_read_b128 v[228:231], v160 offset:7168
	global_load_lds_dwordx4 v[232:233], off
	v_lshl_add_u64 v[232:233], s[34:35], 0, v[136:137]
	s_add_i32 m0, s1, 0xe000
	s_nop 0
	global_load_lds_dwordx4 v[232:233], off
	s_waitcnt vmcnt(8)
	s_waitcnt lgkmcnt(0)
	s_barrier
	v_mfma_f32_16x16x32_bf16 v[124:127], v[138:141], v[200:203], v[124:127]
	v_mfma_f32_16x16x32_bf16 v[120:123], v[166:169], v[200:203], v[120:123]
	v_mfma_f32_16x16x32_bf16 v[116:119], v[138:141], v[208:211], v[116:119]
	v_mfma_f32_16x16x32_bf16 v[112:115], v[166:169], v[208:211], v[112:115]
	v_mfma_f32_16x16x32_bf16 v[108:111], v[138:141], v[216:219], v[108:111]
	v_mfma_f32_16x16x32_bf16 v[104:107], v[166:169], v[216:219], v[104:107]
	v_mfma_f32_16x16x32_bf16 v[100:103], v[138:141], v[224:227], v[100:103]
	v_mfma_f32_16x16x32_bf16 v[96:99], v[166:169], v[224:227], v[96:99]
	v_mfma_f32_16x16x32_bf16 v[124:127], v[162:165], v[204:207], v[124:127]
	v_mfma_f32_16x16x32_bf16 v[120:123], v[170:173], v[204:207], v[120:123]
	v_mfma_f32_16x16x32_bf16 v[116:119], v[162:165], v[212:215], v[116:119]
	v_mfma_f32_16x16x32_bf16 v[112:115], v[170:173], v[212:215], v[112:115]
	v_mfma_f32_16x16x32_bf16 v[108:111], v[162:165], v[220:223], v[108:111]
	v_mfma_f32_16x16x32_bf16 v[104:107], v[170:173], v[220:223], v[104:107]
	v_mfma_f32_16x16x32_bf16 v[100:103], v[162:165], v[228:231], v[100:103]
	v_mfma_f32_16x16x32_bf16 v[96:99], v[170:173], v[228:231], v[96:99]
	v_mfma_f32_16x16x32_bf16 v[92:95], v[174:177], v[200:203], v[92:95]
	v_mfma_f32_16x16x32_bf16 v[88:91], v[192:195], v[200:203], v[88:91]
	v_mfma_f32_16x16x32_bf16 v[84:87], v[174:177], v[208:211], v[84:87]
	v_mfma_f32_16x16x32_bf16 v[80:83], v[192:195], v[208:211], v[80:83]
	v_mfma_f32_16x16x32_bf16 v[76:79], v[174:177], v[216:219], v[76:79]
	v_mfma_f32_16x16x32_bf16 v[72:75], v[192:195], v[216:219], v[72:75]
	v_mfma_f32_16x16x32_bf16 v[68:71], v[174:177], v[224:227], v[68:71]
	v_mfma_f32_16x16x32_bf16 v[64:67], v[192:195], v[224:227], v[64:67]
	v_mfma_f32_16x16x32_bf16 v[92:95], v[178:181], v[204:207], v[92:95]
	v_mfma_f32_16x16x32_bf16 v[88:91], v[196:199], v[204:207], v[88:91]
	v_mfma_f32_16x16x32_bf16 v[84:87], v[178:181], v[212:215], v[84:87]
	v_mfma_f32_16x16x32_bf16 v[80:83], v[196:199], v[212:215], v[80:83]
	v_mfma_f32_16x16x32_bf16 v[76:79], v[178:181], v[220:223], v[76:79]
	v_mfma_f32_16x16x32_bf16 v[72:75], v[196:199], v[220:223], v[72:75]
	v_mfma_f32_16x16x32_bf16 v[68:71], v[178:181], v[228:231], v[68:71]
	v_mfma_f32_16x16x32_bf16 v[64:67], v[196:199], v[228:231], v[64:67]
	s_barrier
	s_add_i32 s48, s48, s0
	v_lshl_add_u64 v[232:233], s[36:37], 0, v[144:145]
	s_mov_b32 m0, s48
	ds_read_b128 v[200:203], v160 offset:16384
	ds_read_b128 v[204:207], v160 offset:17408
	ds_read_b128 v[208:211], v160 offset:18432
	ds_read_b128 v[212:215], v160 offset:19456
	ds_read_b128 v[216:219], v160 offset:20480
	ds_read_b128 v[220:223], v160 offset:21504
	ds_read_b128 v[224:227], v160 offset:22528
	ds_read_b128 v[228:231], v160 offset:23552
	global_load_lds_dwordx4 v[232:233], off
	s_add_i32 m0, s48, 0x2000
	s_add_u32 s48, s36, 0x20000
	v_lshl_add_u64 v[234:235], s[36:37], 0, v[128:129]
	s_addc_u32 s49, s37, 0
	s_add_i32 s50, s50, s0
	global_load_lds_dwordx4 v[234:235], off
	v_lshl_add_u64 v[236:237], s[48:49], 0, v[144:145]
	s_mov_b32 m0, s50
	v_lshl_add_u64 v[238:239], s[44:45], 0, v[130:131]
	global_load_lds_dwordx4 v[236:237], off
	v_lshl_add_u64 v[236:237], s[48:49], 0, v[128:129]
	s_add_i32 m0, s50, 0x2000
	s_nop 0
	global_load_lds_dwordx4 v[236:237], off
	v_lshl_add_u64 v[236:237], s[44:45], 0, v[132:133]
	s_mov_b32 m0, s1
	s_nop 0
	global_load_lds_dwordx4 v[236:237], off
	s_mov_b32 m0, s2
	s_nop 0
	global_load_lds_dwordx4 v[238:239], off
	s_waitcnt vmcnt(8)
	s_waitcnt lgkmcnt(0)
	s_barrier
; #define PG8_STAGE(bufoff, gbase, voff) do { _Pragma("unroll") for (int _i = 0; _i < 2; ++_i) \
;         __builtin_amdgcn_global_load_lds((const unsigned*)((const char*)(gbase) + (voff)[_i]), (LAS unsigned*)(lds + (bufoff) + ldsw + _i * 8192), 16, 0, 0); } while (0)
; #define PG8_LDA(dst, b, h) do { _Pragma("unroll") for (int m = 0; m < 4; ++m) _Pragma("unroll") for (int k = 0; k < 2; ++k) dst[m][k] = *(const LAS bf16x8*)(lds + PG8_SA(b, h) + aoff + m * 2048 + k * 1024); } while (0)
; #define PG8_LDB(dst, b, h) do { _Pragma("unroll") for (int n = 0; n < 2; ++n) _Pragma("unroll") for (int k = 0; k < 2; ++k) dst[n][k] = *(const LAS bf16x8*)(lds + PG8_SB(b, h) + boff + n * 2048 + k * 1024); } while (0)
; #define PG8_MMA(ai, bj, At, Bt) do { __builtin_amdgcn_s_setprio(1); _Pragma("unroll") for (int m = 0; m < 4; ++m) _Pragma("unroll") for (int n = 0; n < 2; ++n) _Pragma("unroll") for (int k = 0; k < 2; ++k) \
;         acc[ai][bj][m][n] = __builtin_amdgcn_mfma_f32_16x16x32_bf16(Bt[n][k], At[m][k], acc[ai][bj][m][n], 0, 0, 0); __builtin_amdgcn_s_setprio(0); } while (0)
; #define PG8_WAIT_V(n) asm volatile("s_waitcnt vmcnt(" #n ")" ::: "memory")
; #define PG8_WAIT_L(n) asm volatile("s_waitcnt lgkmcnt(" #n ")" ::: "memory")
; #define PG8_BAR __builtin_amdgcn_s_barrier()
; #define PG8_SCHED __builtin_amdgcn_sched_barrier(0)
; template <class Epi, class Map>
; __device__ __forceinline__ void gemm_phase(LAS unsigned char* lds, const Gemm g, const Sched<Map>& S, const Epi& E) {
;     ...
;             PG8_WAIT_V(8); PG8_WAIT_L(0); PG8_BAR; PG8_MMA(1, 0, At, B0); PG8_MMA(1, 1, At, B1); PG8_BAR; PG8_SCHED;
;             PG8_LDB(B0, 1, 0); PG8_LDB(B1, 1, 1); PG8_SCHED; PG8_LDA(At, 1, 0); PG8_STAGE(PG8_SA(0, 1), a2 + hstepA, voffA);
;             PG8_WAIT_V(8); PG8_WAIT_L(0); PG8_BAR; PG8_MMA(0, 0, At, B0); PG8_MMA(0, 1, At, B1); PG8_BAR; PG8_SCHED;
	v_mfma_f32_16x16x32_bf16 v[60:63], v[138:141], v[200:203], v[60:63]
	v_mfma_f32_16x16x32_bf16 v[56:59], v[166:169], v[200:203], v[56:59]
	v_mfma_f32_16x16x32_bf16 v[52:55], v[138:141], v[208:211], v[52:55]
	v_mfma_f32_16x16x32_bf16 v[48:51], v[166:169], v[208:211], v[48:51]
	v_mfma_f32_16x16x32_bf16 v[44:47], v[138:141], v[216:219], v[44:47]
	v_mfma_f32_16x16x32_bf16 v[40:43], v[166:169], v[216:219], v[40:43]
	v_mfma_f32_16x16x32_bf16 v[36:39], v[138:141], v[224:227], v[36:39]
	v_mfma_f32_16x16x32_bf16 v[32:35], v[166:169], v[224:227], v[32:35]
	v_mfma_f32_16x16x32_bf16 v[60:63], v[162:165], v[204:207], v[60:63]
	v_mfma_f32_16x16x32_bf16 v[56:59], v[170:173], v[204:207], v[56:59]
	v_mfma_f32_16x16x32_bf16 v[52:55], v[162:165], v[212:215], v[52:55]
	v_mfma_f32_16x16x32_bf16 v[48:51], v[170:173], v[212:215], v[48:51]
	v_mfma_f32_16x16x32_bf16 v[44:47], v[162:165], v[220:223], v[44:47]
	v_mfma_f32_16x16x32_bf16 v[40:43], v[170:173], v[220:223], v[40:43]
	v_mfma_f32_16x16x32_bf16 v[36:39], v[162:165], v[228:231], v[36:39]
	v_mfma_f32_16x16x32_bf16 v[32:35], v[170:173], v[228:231], v[32:35]
	v_mfma_f32_16x16x32_bf16 v[28:31], v[174:177], v[200:203], v[28:31]
	v_mfma_f32_16x16x32_bf16 v[24:27], v[192:195], v[200:203], v[24:27]
	v_mfma_f32_16x16x32_bf16 v[20:23], v[174:177], v[208:211], v[20:23]
	v_mfma_f32_16x16x32_bf16 v[16:19], v[192:195], v[208:211], v[16:19]
	v_mfma_f32_16x16x32_bf16 v[12:15], v[174:177], v[216:219], v[12:15]
	v_mfma_f32_16x16x32_bf16 v[8:11], v[192:195], v[216:219], v[8:11]
	v_mfma_f32_16x16x32_bf16 v[4:7], v[174:177], v[224:227], v[4:7]
	v_mfma_f32_16x16x32_bf16 v[0:3], v[192:195], v[224:227], v[0:3]
	v_mfma_f32_16x16x32_bf16 v[28:31], v[178:181], v[204:207], v[28:31]
	v_mfma_f32_16x16x32_bf16 v[24:27], v[196:199], v[204:207], v[24:27]
	v_mfma_f32_16x16x32_bf16 v[20:23], v[178:181], v[212:215], v[20:23]
	v_mfma_f32_16x16x32_bf16 v[16:19], v[196:199], v[212:215], v[16:19]
	v_mfma_f32_16x16x32_bf16 v[12:15], v[178:181], v[220:223], v[12:15]
	v_mfma_f32_16x16x32_bf16 v[8:11], v[196:199], v[220:223], v[8:11]
	v_mfma_f32_16x16x32_bf16 v[4:7], v[178:181], v[228:231], v[4:7]
	v_mfma_f32_16x16x32_bf16 v[0:3], v[196:199], v[228:231], v[0:3]
	s_barrier
	s_add_i32 s48, 0, 0x18000
	v_add_u32_e32 v161, s48, v159
	s_add_i32 s49, 0, 0x1c000
	ds_read_b128 v[138:141], v161
	ds_read_b128 v[162:165], v161 offset:1024
	ds_read_b128 v[166:169], v161 offset:2048
	ds_read_b128 v[170:173], v161 offset:3072
	v_add_u32_e32 v161, s49, v159
	ds_read_b128 v[174:177], v161
	ds_read_b128 v[178:181], v161 offset:1024
	ds_read_b128 v[192:195], v161 offset:2048
	ds_read_b128 v[196:199], v161 offset:3072
	s_add_u32 s44, s44, 0x20000
	s_addc_u32 s45, s45, 0
	s_mov_b32 m0, s3
	v_lshl_add_u64 v[240:241], s[44:45], 0, v[132:133]
	ds_read_b128 v[200:203], v160 offset:32768
	ds_read_b128 v[204:207], v160 offset:33792
	ds_read_b128 v[208:211], v160 offset:34816
	ds_read_b128 v[212:215], v160 offset:35840
	ds_read_b128 v[216:219], v160 offset:36864
	ds_read_b128 v[220:223], v160 offset:37888
	ds_read_b128 v[224:227], v160 offset:38912
	ds_read_b128 v[228:231], v160 offset:39936
	global_load_lds_dwordx4 v[240:241], off
	v_lshl_add_u64 v[240:241], s[44:45], 0, v[130:131]
	s_mov_b32 m0, s4
	s_nop 0
	global_load_lds_dwordx4 v[240:241], off
	s_waitcnt vmcnt(8)
	s_waitcnt lgkmcnt(0)
	s_barrier
	v_mfma_f32_16x16x32_bf16 v[124:127], v[138:141], v[200:203], v[124:127]
	v_mfma_f32_16x16x32_bf16 v[120:123], v[166:169], v[200:203], v[120:123]
	v_mfma_f32_16x16x32_bf16 v[116:119], v[138:141], v[208:211], v[116:119]
	v_mfma_f32_16x16x32_bf16 v[112:115], v[166:169], v[208:211], v[112:115]
	v_mfma_f32_16x16x32_bf16 v[108:111], v[138:141], v[216:219], v[108:111]
	v_mfma_f32_16x16x32_bf16 v[104:107], v[166:169], v[216:219], v[104:107]
	v_mfma_f32_16x16x32_bf16 v[100:103], v[138:141], v[224:227], v[100:103]
	v_mfma_f32_16x16x32_bf16 v[96:99], v[166:169], v[224:227], v[96:99]
	v_mfma_f32_16x16x32_bf16 v[124:127], v[162:165], v[204:207], v[124:127]
	v_mfma_f32_16x16x32_bf16 v[120:123], v[170:173], v[204:207], v[120:123]
	v_mfma_f32_16x16x32_bf16 v[116:119], v[162:165], v[212:215], v[116:119]
	v_mfma_f32_16x16x32_bf16 v[112:115], v[170:173], v[212:215], v[112:115]
	v_mfma_f32_16x16x32_bf16 v[108:111], v[162:165], v[220:223], v[108:111]
	v_mfma_f32_16x16x32_bf16 v[104:107], v[170:173], v[220:223], v[104:107]
	v_mfma_f32_16x16x32_bf16 v[100:103], v[162:165], v[228:231], v[100:103]
	v_mfma_f32_16x16x32_bf16 v[96:99], v[170:173], v[228:231], v[96:99]
	v_mfma_f32_16x16x32_bf16 v[92:95], v[174:177], v[200:203], v[92:95]
	v_mfma_f32_16x16x32_bf16 v[88:91], v[192:195], v[200:203], v[88:91]
	v_mfma_f32_16x16x32_bf16 v[84:87], v[174:177], v[208:211], v[84:87]
	v_mfma_f32_16x16x32_bf16 v[80:83], v[192:195], v[208:211], v[80:83]
	v_mfma_f32_16x16x32_bf16 v[76:79], v[174:177], v[216:219], v[76:79]
	v_mfma_f32_16x16x32_bf16 v[72:75], v[192:195], v[216:219], v[72:75]
	v_mfma_f32_16x16x32_bf16 v[68:71], v[174:177], v[224:227], v[68:71]
	v_mfma_f32_16x16x32_bf16 v[64:67], v[192:195], v[224:227], v[64:67]
	v_mfma_f32_16x16x32_bf16 v[92:95], v[178:181], v[204:207], v[92:95]
	v_mfma_f32_16x16x32_bf16 v[88:91], v[196:199], v[204:207], v[88:91]
	v_mfma_f32_16x16x32_bf16 v[84:87], v[178:181], v[212:215], v[84:87]
	v_mfma_f32_16x16x32_bf16 v[80:83], v[196:199], v[212:215], v[80:83]
	v_mfma_f32_16x16x32_bf16 v[76:79], v[178:181], v[220:223], v[76:79]
	v_mfma_f32_16x16x32_bf16 v[72:75], v[196:199], v[220:223], v[72:75]
	v_mfma_f32_16x16x32_bf16 v[68:71], v[178:181], v[228:231], v[68:71]
	v_mfma_f32_16x16x32_bf16 v[64:67], v[196:199], v[228:231], v[64:67]
	s_barrier
; #define PG8_STAGE(bufoff, gbase, voff) do { _Pragma("unroll") for (int _i = 0; _i < 2; ++_i) \
;         __builtin_amdgcn_global_load_lds((const unsigned*)((const char*)(gbase) + (voff)[_i]), (LAS unsigned*)(lds + (bufoff) + ldsw + _i * 8192), 16, 0, 0); } while (0)
; #define PG8_LDA(dst, b, h) do { _Pragma("unroll") for (int m = 0; m < 4; ++m) _Pragma("unroll") for (int k = 0; k < 2; ++k) dst[m][k] = *(const LAS bf16x8*)(lds + PG8_SA(b, h) + aoff + m * 2048 + k * 1024); } while (0)
; #define PG8_MMA(ai, bj, At, Bt) do { __builtin_amdgcn_s_setprio(1); _Pragma("unroll") for (int m = 0; m < 4; ++m) _Pragma("unroll") for (int n = 0; n < 2; ++n) _Pragma("unroll") for (int k = 0; k < 2; ++k) \
;         acc[ai][bj][m][n] = __builtin_amdgcn_mfma_f32_16x16x32_bf16(Bt[n][k], At[m][k], acc[ai][bj][m][n], 0, 0, 0); __builtin_amdgcn_s_setprio(0); } while (0)
; #define PG8_WAIT_V(n) asm volatile("s_waitcnt vmcnt(" #n ")" ::: "memory")
; #define PG8_WAIT_L(n) asm volatile("s_waitcnt lgkmcnt(" #n ")" ::: "memory")
; #define PG8_BAR __builtin_amdgcn_s_barrier()
; #define PG8_SCHED __builtin_amdgcn_sched_barrier(0)
; template <class Epi, class Map>
; __device__ __forceinline__ void gemm_phase(LAS unsigned char* lds, const Gemm g, const Sched<Map>& S, const Epi& E) {
;     ...
;             PG8_LDA(At, 1, 1); PG8_STAGE(PG8_SB(1, 0), b3, voffB); PG8_STAGE(PG8_SB(1, 1), b3 + hstepB, voffB); PG8_STAGE(PG8_SA(1, 0), a3, voffA);
;             PG8_WAIT_V(8); PG8_WAIT_L(0); PG8_BAR; PG8_MMA(1, 0, At, B0); PG8_MMA(1, 1, At, B1); PG8_BAR; PG8_SCHED;
;         }
;         if (wr == 0) PG8_BAR;
	s_add_i32 s44, s48, s0
	v_lshl_add_u64 v[232:233], v[232:233], 0, s[82:83]
	s_mov_b32 m0, s44
	ds_read_b128 v[200:203], v160 offset:49152
	ds_read_b128 v[204:207], v160 offset:50176
	ds_read_b128 v[208:211], v160 offset:51200
	ds_read_b128 v[212:215], v160 offset:52224
	ds_read_b128 v[216:219], v160 offset:53248
	ds_read_b128 v[220:223], v160 offset:54272
	ds_read_b128 v[224:227], v160 offset:55296
	ds_read_b128 v[228:231], v160 offset:56320
	global_load_lds_dwordx4 v[232:233], off
	s_add_i32 m0, s44, 0x2000
	s_add_u32 s36, s36, 0x20080
	v_lshl_add_u64 v[232:233], v[234:235], 0, s[82:83]
	s_addc_u32 s37, s37, 0
	s_add_i32 s44, s49, s0
	global_load_lds_dwordx4 v[232:233], off
	v_lshl_add_u64 v[232:233], s[36:37], 0, v[144:145]
	s_mov_b32 m0, s44
	s_nop 0
	global_load_lds_dwordx4 v[232:233], off
	v_lshl_add_u64 v[232:233], s[36:37], 0, v[128:129]
	s_add_i32 m0, s44, 0x2000
	s_nop 0
	global_load_lds_dwordx4 v[232:233], off
	v_lshl_add_u64 v[232:233], v[236:237], 0, s[82:83]
	s_mov_b32 m0, s6
	s_nop 0
	global_load_lds_dwordx4 v[232:233], off
	v_lshl_add_u64 v[232:233], v[238:239], 0, s[82:83]
	s_mov_b32 m0, s7
	s_nop 0
	global_load_lds_dwordx4 v[232:233], off
	s_waitcnt vmcnt(8)
	s_waitcnt lgkmcnt(0)
	s_barrier
	v_mfma_f32_16x16x32_bf16 v[60:63], v[138:141], v[200:203], v[60:63]
	v_mfma_f32_16x16x32_bf16 v[56:59], v[166:169], v[200:203], v[56:59]
	v_mfma_f32_16x16x32_bf16 v[52:55], v[138:141], v[208:211], v[52:55]
	v_mfma_f32_16x16x32_bf16 v[48:51], v[166:169], v[208:211], v[48:51]
	v_mfma_f32_16x16x32_bf16 v[44:47], v[138:141], v[216:219], v[44:47]
	v_mfma_f32_16x16x32_bf16 v[40:43], v[166:169], v[216:219], v[40:43]
	v_mfma_f32_16x16x32_bf16 v[36:39], v[138:141], v[224:227], v[36:39]
	v_mfma_f32_16x16x32_bf16 v[32:35], v[166:169], v[224:227], v[32:35]
	v_mfma_f32_16x16x32_bf16 v[60:63], v[162:165], v[204:207], v[60:63]
	v_mfma_f32_16x16x32_bf16 v[56:59], v[170:173], v[204:207], v[56:59]
	v_mfma_f32_16x16x32_bf16 v[52:55], v[162:165], v[212:215], v[52:55]
	v_mfma_f32_16x16x32_bf16 v[48:51], v[170:173], v[212:215], v[48:51]
	v_mfma_f32_16x16x32_bf16 v[44:47], v[162:165], v[220:223], v[44:47]
	v_mfma_f32_16x16x32_bf16 v[40:43], v[170:173], v[220:223], v[40:43]
	v_mfma_f32_16x16x32_bf16 v[36:39], v[162:165], v[228:231], v[36:39]
	v_mfma_f32_16x16x32_bf16 v[32:35], v[170:173], v[228:231], v[32:35]
	v_mfma_f32_16x16x32_bf16 v[28:31], v[174:177], v[200:203], v[28:31]
	v_mfma_f32_16x16x32_bf16 v[24:27], v[192:195], v[200:203], v[24:27]
	v_mfma_f32_16x16x32_bf16 v[20:23], v[174:177], v[208:211], v[20:23]
	v_mfma_f32_16x16x32_bf16 v[16:19], v[192:195], v[208:211], v[16:19]
	v_mfma_f32_16x16x32_bf16 v[12:15], v[174:177], v[216:219], v[12:15]
	v_mfma_f32_16x16x32_bf16 v[8:11], v[192:195], v[216:219], v[8:11]
	v_mfma_f32_16x16x32_bf16 v[4:7], v[174:177], v[224:227], v[4:7]
	v_mfma_f32_16x16x32_bf16 v[0:3], v[192:195], v[224:227], v[0:3]
	v_mfma_f32_16x16x32_bf16 v[28:31], v[178:181], v[204:207], v[28:31]
	v_mfma_f32_16x16x32_bf16 v[24:27], v[196:199], v[204:207], v[24:27]
	v_mfma_f32_16x16x32_bf16 v[20:23], v[178:181], v[212:215], v[20:23]
	v_mfma_f32_16x16x32_bf16 v[16:19], v[196:199], v[212:215], v[16:19]
	v_mfma_f32_16x16x32_bf16 v[12:15], v[178:181], v[220:223], v[12:15]
	v_mfma_f32_16x16x32_bf16 v[8:11], v[196:199], v[220:223], v[8:11]
	v_mfma_f32_16x16x32_bf16 v[4:7], v[178:181], v[228:231], v[4:7]
	v_mfma_f32_16x16x32_bf16 v[0:3], v[196:199], v[228:231], v[0:3]
	s_barrier
	s_add_i32 s47, s47, 2
	s_add_u32 s34, s34, 0x100
	s_addc_u32 s35, s35, 0
	s_add_u32 s39, s39, 0x100
	s_addc_u32 s46, s46, 0
	s_cmp_gt_u32 s47, 5
	s_cbranch_scc0 .LBB0_808
	s_and_b64 vcc, exec, s[18:19]
	s_cbranch_vccz .LBB0_811
	s_barrier

; #define PG8_STAGE(bufoff, gbase, voff) do { _Pragma("unroll") for (int _i = 0; _i < 2; ++_i) \
;         __builtin_amdgcn_global_load_lds((const unsigned*)((const char*)(gbase) + (voff)[_i]), (LAS unsigned*)(lds + (bufoff) + ldsw + _i * 8192), 16, 0, 0); } while (0)
; #define PG8_LDA(dst, b, h) do { _Pragma("unroll") for (int m = 0; m < 4; ++m) _Pragma("unroll") for (int k = 0; k < 2; ++k) dst[m][k] = *(const LAS bf16x8*)(lds + PG8_SA(b, h) + aoff + m * 2048 + k * 1024); } while (0)
; #define PG8_LDB(dst, b, h) do { _Pragma("unroll") for (int n = 0; n < 2; ++n) _Pragma("unroll") for (int k = 0; k < 2; ++k) dst[n][k] = *(const LAS bf16x8*)(lds + PG8_SB(b, h) + boff + n * 2048 + k * 1024); } while (0)
; #define PG8_MMA(ai, bj, At, Bt) do { __builtin_amdgcn_s_setprio(1); _Pragma("unroll") for (int m = 0; m < 4; ++m) _Pragma("unroll") for (int n = 0; n < 2; ++n) _Pragma("unroll") for (int k = 0; k < 2; ++k) \
;         acc[ai][bj][m][n] = __builtin_amdgcn_mfma_f32_16x16x32_bf16(Bt[n][k], At[m][k], acc[ai][bj][m][n], 0, 0, 0); __builtin_amdgcn_s_setprio(0); } while (0)
; #define PG8_WAIT_V(n) asm volatile("s_waitcnt vmcnt(" #n ")" ::: "memory")
; #define PG8_WAIT_L(n) asm volatile("s_waitcnt lgkmcnt(" #n ")" ::: "memory")
; #define PG8_BAR __builtin_amdgcn_s_barrier()
; #define PG8_SCHED __builtin_amdgcn_sched_barrier(0)
; template <class Epi, class Map>
; __device__ __forceinline__ void gemm_phase(LAS unsigned char* lds, const Gemm g, const Sched<Map>& S, const Epi& E) {
;     ...
;         for (int t = 0; t < nt; t += 2) {
;             const bool last = (t == nt - 2);
;             const char* a1 = cA + (size_t)(t + 1) * kstep;
;             const char* a2 = last ? nA : cA + (size_t)(t + 2) * kstep; const char* b2 = last ? nB : cB + (size_t)(t + 2) * kstep;
;             const char* a3 = a2 + kstep; const char* b3 = b2 + kstep;
;             PG8_LDB(B0, 0, 0); PG8_LDB(B1, 0, 1); PG8_SCHED; PG8_LDA(At, 0, 0); PG8_STAGE(PG8_SA(1, 1), a1 + hstepA, voffA);
;             PG8_WAIT_V(8); PG8_WAIT_L(0); PG8_BAR; PG8_MMA(0, 0, At, B0); PG8_MMA(0, 1, At, B1); PG8_BAR; PG8_SCHED;
;             PG8_LDA(At, 0, 1); PG8_STAGE(PG8_SB(0, 0), b2, voffB); PG8_STAGE(PG8_SB(0, 1), b2 + hstepB, voffB); PG8_STAGE(PG8_SA(0, 0), a2, voffA);
;             PG8_WAIT_V(8); PG8_WAIT_L(0); PG8_BAR; PG8_MMA(1, 0, At, B0); PG8_MMA(1, 1, At, B1); PG8_BAR; PG8_SCHED;
.LBB0_880:
	s_add_u32 s9, s18, 0xfff80080
	s_addc_u32 s10, s19, -1
	s_add_i32 s11, 0, 0x10000
	s_cmp_eq_u32 s8, 28
	s_cselect_b32 s25, s2, s10
	s_cselect_b32 s24, s3, s9
	s_cselect_b32 s21, s4, s7
	s_cselect_b32 s20, s5, s6
	s_add_i32 s9, 0, 0x14000
	v_add_u32_e32 v166, s11, v173
	v_add_u32_e32 v170, s9, v173
	ds_read_b128 v[124:127], v166
	ds_read_b128 v[132:135], v166 offset:1024
	ds_read_b128 v[162:165], v166 offset:2048
	ds_read_b128 v[166:169], v166 offset:3072
	ds_read_b128 v[176:179], v170
	ds_read_b128 v[192:195], v170 offset:1024
	ds_read_b128 v[196:199], v170 offset:2048
	ds_read_b128 v[200:203], v170 offset:3072
	v_lshl_add_u64 v[170:171], s[18:19], 0, v[142:143]
	s_add_i32 m0, s29, 0xc000
	ds_read_b128 v[204:207], v174
	ds_read_b128 v[208:211], v174 offset:1024
	ds_read_b128 v[212:215], v174 offset:2048
	ds_read_b128 v[216:219], v174 offset:3072
	ds_read_b128 v[220:223], v174 offset:4096
	ds_read_b128 v[224:227], v174 offset:5120
	ds_read_b128 v[228:231], v174 offset:6144
	ds_read_b128 v[232:235], v174 offset:7168
	global_load_lds_dwordx4 v[170:171], off
	v_lshl_add_u64 v[170:171], s[18:19], 0, v[160:161]
	s_add_i32 m0, s29, 0xe000
	s_nop 0
	global_load_lds_dwordx4 v[170:171], off
	s_waitcnt vmcnt(8)
	s_waitcnt lgkmcnt(0)
	s_barrier
	v_mfma_f32_16x16x32_bf16 v[128:131], v[124:127], v[204:207], v[128:131]
	v_mfma_f32_16x16x32_bf16 v[120:123], v[162:165], v[204:207], v[120:123]
	v_mfma_f32_16x16x32_bf16 v[108:111], v[124:127], v[212:215], v[108:111]
	v_mfma_f32_16x16x32_bf16 v[104:107], v[162:165], v[212:215], v[104:107]
	v_mfma_f32_16x16x32_bf16 v[92:95], v[124:127], v[220:223], v[92:95]
	v_mfma_f32_16x16x32_bf16 v[88:91], v[162:165], v[220:223], v[88:91]
	v_mfma_f32_16x16x32_bf16 v[76:79], v[124:127], v[228:231], v[76:79]
	v_mfma_f32_16x16x32_bf16 v[72:75], v[162:165], v[228:231], v[72:75]
	v_mfma_f32_16x16x32_bf16 v[128:131], v[132:135], v[208:211], v[128:131]
	v_mfma_f32_16x16x32_bf16 v[120:123], v[166:169], v[208:211], v[120:123]
	v_mfma_f32_16x16x32_bf16 v[108:111], v[132:135], v[216:219], v[108:111]
	v_mfma_f32_16x16x32_bf16 v[104:107], v[166:169], v[216:219], v[104:107]
	v_mfma_f32_16x16x32_bf16 v[92:95], v[132:135], v[224:227], v[92:95]
	v_mfma_f32_16x16x32_bf16 v[88:91], v[166:169], v[224:227], v[88:91]
	v_mfma_f32_16x16x32_bf16 v[76:79], v[132:135], v[232:235], v[76:79]
	v_mfma_f32_16x16x32_bf16 v[72:75], v[166:169], v[232:235], v[72:75]
	v_mfma_f32_16x16x32_bf16 v[116:119], v[176:179], v[204:207], v[116:119]
	v_mfma_f32_16x16x32_bf16 v[112:115], v[196:199], v[204:207], v[112:115]
	v_mfma_f32_16x16x32_bf16 v[100:103], v[176:179], v[212:215], v[100:103]
	v_mfma_f32_16x16x32_bf16 v[96:99], v[196:199], v[212:215], v[96:99]
	v_mfma_f32_16x16x32_bf16 v[84:87], v[176:179], v[220:223], v[84:87]
	v_mfma_f32_16x16x32_bf16 v[80:83], v[196:199], v[220:223], v[80:83]
	v_mfma_f32_16x16x32_bf16 v[68:71], v[176:179], v[228:231], v[68:71]
	v_mfma_f32_16x16x32_bf16 v[64:67], v[196:199], v[228:231], v[64:67]
	v_mfma_f32_16x16x32_bf16 v[116:119], v[192:195], v[208:211], v[116:119]
	v_mfma_f32_16x16x32_bf16 v[112:115], v[200:203], v[208:211], v[112:115]
	v_mfma_f32_16x16x32_bf16 v[100:103], v[192:195], v[216:219], v[100:103]
	v_mfma_f32_16x16x32_bf16 v[96:99], v[200:203], v[216:219], v[96:99]
	v_mfma_f32_16x16x32_bf16 v[84:87], v[192:195], v[224:227], v[84:87]
	v_mfma_f32_16x16x32_bf16 v[80:83], v[200:203], v[224:227], v[80:83]
	v_mfma_f32_16x16x32_bf16 v[68:71], v[192:195], v[232:235], v[68:71]
	v_mfma_f32_16x16x32_bf16 v[64:67], v[200:203], v[232:235], v[64:67]
	s_barrier
	s_add_i32 s10, s11, s28
	v_lshl_add_u64 v[170:171], s[20:21], 0, v[144:145]
	s_mov_b32 m0, s10
	ds_read_b128 v[204:207], v174 offset:16384
	ds_read_b128 v[208:211], v174 offset:17408
	ds_read_b128 v[212:215], v174 offset:18432
	ds_read_b128 v[216:219], v174 offset:19456
	ds_read_b128 v[220:223], v174 offset:20480
	ds_read_b128 v[224:227], v174 offset:21504
	ds_read_b128 v[228:231], v174 offset:22528
	ds_read_b128 v[232:235], v174 offset:23552
	global_load_lds_dwordx4 v[170:171], off
	s_add_i32 m0, s10, 0x2000
	s_add_u32 s10, s20, 0x80000
	v_lshl_add_u64 v[180:181], s[20:21], 0, v[136:137]
	s_addc_u32 s11, s21, 0
	s_add_i32 s9, s9, s28
	global_load_lds_dwordx4 v[180:181], off
	v_lshl_add_u64 v[236:237], s[10:11], 0, v[144:145]
	s_mov_b32 m0, s9
	v_lshl_add_u64 v[238:239], s[24:25], 0, v[138:139]
	global_load_lds_dwordx4 v[236:237], off
	v_lshl_add_u64 v[236:237], s[10:11], 0, v[136:137]
	s_add_i32 m0, s9, 0x2000
	s_nop 0
	global_load_lds_dwordx4 v[236:237], off
	v_lshl_add_u64 v[236:237], s[24:25], 0, v[140:141]
	s_mov_b32 m0, s29
	s_nop 0
	global_load_lds_dwordx4 v[236:237], off
	s_mov_b32 m0, s30
	s_nop 0
	global_load_lds_dwordx4 v[238:239], off
	s_waitcnt vmcnt(8)
	s_waitcnt lgkmcnt(0)
	s_barrier
; #define PG8_STAGE(bufoff, gbase, voff) do { _Pragma("unroll") for (int _i = 0; _i < 2; ++_i) \
;         __builtin_amdgcn_global_load_lds((const unsigned*)((const char*)(gbase) + (voff)[_i]), (LAS unsigned*)(lds + (bufoff) + ldsw + _i * 8192), 16, 0, 0); } while (0)
; #define PG8_LDA(dst, b, h) do { _Pragma("unroll") for (int m = 0; m < 4; ++m) _Pragma("unroll") for (int k = 0; k < 2; ++k) dst[m][k] = *(const LAS bf16x8*)(lds + PG8_SA(b, h) + aoff + m * 2048 + k * 1024); } while (0)
; #define PG8_LDB(dst, b, h) do { _Pragma("unroll") for (int n = 0; n < 2; ++n) _Pragma("unroll") for (int k = 0; k < 2; ++k) dst[n][k] = *(const LAS bf16x8*)(lds + PG8_SB(b, h) + boff + n * 2048 + k * 1024); } while (0)
; #define PG8_MMA(ai, bj, At, Bt) do { __builtin_amdgcn_s_setprio(1); _Pragma("unroll") for (int m = 0; m < 4; ++m) _Pragma("unroll") for (int n = 0; n < 2; ++n) _Pragma("unroll") for (int k = 0; k < 2; ++k) \
;         acc[ai][bj][m][n] = __builtin_amdgcn_mfma_f32_16x16x32_bf16(Bt[n][k], At[m][k], acc[ai][bj][m][n], 0, 0, 0); __builtin_amdgcn_s_setprio(0); } while (0)
; #define PG8_WAIT_V(n) asm volatile("s_waitcnt vmcnt(" #n ")" ::: "memory")
; #define PG8_WAIT_L(n) asm volatile("s_waitcnt lgkmcnt(" #n ")" ::: "memory")
; #define PG8_BAR __builtin_amdgcn_s_barrier()
; #define PG8_SCHED __builtin_amdgcn_sched_barrier(0)
; template <class Epi, class Map>
; __device__ __forceinline__ void gemm_phase(LAS unsigned char* lds, const Gemm g, const Sched<Map>& S, const Epi& E) {
;     ...
;             PG8_WAIT_V(8); PG8_WAIT_L(0); PG8_BAR; PG8_MMA(1, 0, At, B0); PG8_MMA(1, 1, At, B1); PG8_BAR; PG8_SCHED;
;             PG8_LDB(B0, 1, 0); PG8_LDB(B1, 1, 1); PG8_SCHED; PG8_LDA(At, 1, 0); PG8_STAGE(PG8_SA(0, 1), a2 + hstepA, voffA);
;             PG8_WAIT_V(8); PG8_WAIT_L(0); PG8_BAR; PG8_MMA(0, 0, At, B0); PG8_MMA(0, 1, At, B1); PG8_BAR; PG8_SCHED;
;             PG8_LDA(At, 1, 1); PG8_STAGE(PG8_SB(1, 0), b3, voffB); PG8_STAGE(PG8_SB(1, 1), b3 + hstepB, voffB); PG8_STAGE(PG8_SA(1, 0), a3, voffA);
	v_mfma_f32_16x16x32_bf16 v[60:63], v[124:127], v[204:207], v[60:63]
	v_mfma_f32_16x16x32_bf16 v[56:59], v[162:165], v[204:207], v[56:59]
	v_mfma_f32_16x16x32_bf16 v[44:47], v[124:127], v[212:215], v[44:47]
	v_mfma_f32_16x16x32_bf16 v[40:43], v[162:165], v[212:215], v[40:43]
	v_mfma_f32_16x16x32_bf16 v[28:31], v[124:127], v[220:223], v[28:31]
	v_mfma_f32_16x16x32_bf16 v[24:27], v[162:165], v[220:223], v[24:27]
	v_mfma_f32_16x16x32_bf16 v[12:15], v[124:127], v[228:231], v[12:15]
	v_mfma_f32_16x16x32_bf16 v[8:11], v[162:165], v[228:231], v[8:11]
	v_mfma_f32_16x16x32_bf16 v[60:63], v[132:135], v[208:211], v[60:63]
	v_mfma_f32_16x16x32_bf16 v[56:59], v[166:169], v[208:211], v[56:59]
	v_mfma_f32_16x16x32_bf16 v[44:47], v[132:135], v[216:219], v[44:47]
	v_mfma_f32_16x16x32_bf16 v[40:43], v[166:169], v[216:219], v[40:43]
	v_mfma_f32_16x16x32_bf16 v[28:31], v[132:135], v[224:227], v[28:31]
	v_mfma_f32_16x16x32_bf16 v[24:27], v[166:169], v[224:227], v[24:27]
	v_mfma_f32_16x16x32_bf16 v[12:15], v[132:135], v[232:235], v[12:15]
	v_mfma_f32_16x16x32_bf16 v[8:11], v[166:169], v[232:235], v[8:11]
	v_mfma_f32_16x16x32_bf16 v[52:55], v[176:179], v[204:207], v[52:55]
	v_mfma_f32_16x16x32_bf16 v[48:51], v[196:199], v[204:207], v[48:51]
	v_mfma_f32_16x16x32_bf16 v[36:39], v[176:179], v[212:215], v[36:39]
	v_mfma_f32_16x16x32_bf16 v[32:35], v[196:199], v[212:215], v[32:35]
	v_mfma_f32_16x16x32_bf16 v[20:23], v[176:179], v[220:223], v[20:23]
	v_mfma_f32_16x16x32_bf16 v[16:19], v[196:199], v[220:223], v[16:19]
	v_mfma_f32_16x16x32_bf16 v[4:7], v[176:179], v[228:231], v[4:7]
	v_mfma_f32_16x16x32_bf16 v[0:3], v[196:199], v[228:231], v[0:3]
	v_mfma_f32_16x16x32_bf16 v[52:55], v[192:195], v[208:211], v[52:55]
	v_mfma_f32_16x16x32_bf16 v[48:51], v[200:203], v[208:211], v[48:51]
	v_mfma_f32_16x16x32_bf16 v[36:39], v[192:195], v[216:219], v[36:39]
	v_mfma_f32_16x16x32_bf16 v[32:35], v[200:203], v[216:219], v[32:35]
	v_mfma_f32_16x16x32_bf16 v[20:23], v[192:195], v[224:227], v[20:23]
	v_mfma_f32_16x16x32_bf16 v[16:19], v[200:203], v[224:227], v[16:19]
	v_mfma_f32_16x16x32_bf16 v[4:7], v[192:195], v[232:235], v[4:7]
	v_mfma_f32_16x16x32_bf16 v[0:3], v[200:203], v[232:235], v[0:3]
	s_barrier
	s_add_i32 s9, 0, 0x18000
	s_add_i32 s12, 0, 0x1c000
	v_add_u32_e32 v166, s9, v173
	v_add_u32_e32 v175, s12, v173
	ds_read_b128 v[124:127], v166
	ds_read_b128 v[132:135], v166 offset:1024
	ds_read_b128 v[162:165], v166 offset:2048
	ds_read_b128 v[166:169], v166 offset:3072
	ds_read_b128 v[176:179], v175
	ds_read_b128 v[192:195], v175 offset:1024
	ds_read_b128 v[196:199], v175 offset:2048
	ds_read_b128 v[200:203], v175 offset:3072
	s_add_u32 s10, s24, 0x80000
	s_addc_u32 s11, s25, 0
	s_mov_b32 m0, s31
	v_lshl_add_u64 v[240:241], s[10:11], 0, v[140:141]
	ds_read_b128 v[204:207], v174 offset:32768
	ds_read_b128 v[208:211], v174 offset:33792
	ds_read_b128 v[212:215], v174 offset:34816
	ds_read_b128 v[216:219], v174 offset:35840
	ds_read_b128 v[220:223], v174 offset:36864
	ds_read_b128 v[224:227], v174 offset:37888
	ds_read_b128 v[228:231], v174 offset:38912
	ds_read_b128 v[232:235], v174 offset:39936
	global_load_lds_dwordx4 v[240:241], off
	v_lshl_add_u64 v[240:241], s[10:11], 0, v[138:139]
	s_mov_b32 m0, s34
	s_nop 0
	global_load_lds_dwordx4 v[240:241], off
	s_waitcnt vmcnt(8)
	s_waitcnt lgkmcnt(0)
	s_barrier
	v_mfma_f32_16x16x32_bf16 v[128:131], v[124:127], v[204:207], v[128:131]
	v_mfma_f32_16x16x32_bf16 v[120:123], v[162:165], v[204:207], v[120:123]
	v_mfma_f32_16x16x32_bf16 v[108:111], v[124:127], v[212:215], v[108:111]
	v_mfma_f32_16x16x32_bf16 v[104:107], v[162:165], v[212:215], v[104:107]
	v_mfma_f32_16x16x32_bf16 v[92:95], v[124:127], v[220:223], v[92:95]
	v_mfma_f32_16x16x32_bf16 v[88:91], v[162:165], v[220:223], v[88:91]
	v_mfma_f32_16x16x32_bf16 v[76:79], v[124:127], v[228:231], v[76:79]
	v_mfma_f32_16x16x32_bf16 v[72:75], v[162:165], v[228:231], v[72:75]
	v_mfma_f32_16x16x32_bf16 v[128:131], v[132:135], v[208:211], v[128:131]
	v_mfma_f32_16x16x32_bf16 v[120:123], v[166:169], v[208:211], v[120:123]
	v_mfma_f32_16x16x32_bf16 v[108:111], v[132:135], v[216:219], v[108:111]
	v_mfma_f32_16x16x32_bf16 v[104:107], v[166:169], v[216:219], v[104:107]
	v_mfma_f32_16x16x32_bf16 v[92:95], v[132:135], v[224:227], v[92:95]
	v_mfma_f32_16x16x32_bf16 v[88:91], v[166:169], v[224:227], v[88:91]
	v_mfma_f32_16x16x32_bf16 v[76:79], v[132:135], v[232:235], v[76:79]
	v_mfma_f32_16x16x32_bf16 v[72:75], v[166:169], v[232:235], v[72:75]
	v_mfma_f32_16x16x32_bf16 v[116:119], v[176:179], v[204:207], v[116:119]
	v_mfma_f32_16x16x32_bf16 v[112:115], v[196:199], v[204:207], v[112:115]
	v_mfma_f32_16x16x32_bf16 v[100:103], v[176:179], v[212:215], v[100:103]
	v_mfma_f32_16x16x32_bf16 v[96:99], v[196:199], v[212:215], v[96:99]
	v_mfma_f32_16x16x32_bf16 v[84:87], v[176:179], v[220:223], v[84:87]
	v_mfma_f32_16x16x32_bf16 v[80:83], v[196:199], v[220:223], v[80:83]
	v_mfma_f32_16x16x32_bf16 v[68:71], v[176:179], v[228:231], v[68:71]
	v_mfma_f32_16x16x32_bf16 v[64:67], v[196:199], v[228:231], v[64:67]
	v_mfma_f32_16x16x32_bf16 v[116:119], v[192:195], v[208:211], v[116:119]
	v_mfma_f32_16x16x32_bf16 v[112:115], v[200:203], v[208:211], v[112:115]
	v_mfma_f32_16x16x32_bf16 v[100:103], v[192:195], v[216:219], v[100:103]
	v_mfma_f32_16x16x32_bf16 v[96:99], v[200:203], v[216:219], v[96:99]
	v_mfma_f32_16x16x32_bf16 v[84:87], v[192:195], v[224:227], v[84:87]
	v_mfma_f32_16x16x32_bf16 v[80:83], v[200:203], v[224:227], v[80:83]
	v_mfma_f32_16x16x32_bf16 v[68:71], v[192:195], v[232:235], v[68:71]
	v_mfma_f32_16x16x32_bf16 v[64:67], v[200:203], v[232:235], v[64:67]
	s_barrier
; #define PG8_STAGE(bufoff, gbase, voff) do { _Pragma("unroll") for (int _i = 0; _i < 2; ++_i) \
;         __builtin_amdgcn_global_load_lds((const unsigned*)((const char*)(gbase) + (voff)[_i]), (LAS unsigned*)(lds + (bufoff) + ldsw + _i * 8192), 16, 0, 0); } while (0)
; #define PG8_LDA(dst, b, h) do { _Pragma("unroll") for (int m = 0; m < 4; ++m) _Pragma("unroll") for (int k = 0; k < 2; ++k) dst[m][k] = *(const LAS bf16x8*)(lds + PG8_SA(b, h) + aoff + m * 2048 + k * 1024); } while (0)
; #define PG8_MMA(ai, bj, At, Bt) do { __builtin_amdgcn_s_setprio(1); _Pragma("unroll") for (int m = 0; m < 4; ++m) _Pragma("unroll") for (int n = 0; n < 2; ++n) _Pragma("unroll") for (int k = 0; k < 2; ++k) \
;         acc[ai][bj][m][n] = __builtin_amdgcn_mfma_f32_16x16x32_bf16(Bt[n][k], At[m][k], acc[ai][bj][m][n], 0, 0, 0); __builtin_amdgcn_s_setprio(0); } while (0)
; #define PG8_WAIT_V(n) asm volatile("s_waitcnt vmcnt(" #n ")" ::: "memory")
; #define PG8_WAIT_L(n) asm volatile("s_waitcnt lgkmcnt(" #n ")" ::: "memory")
; #define PG8_BAR __builtin_amdgcn_s_barrier()
; #define PG8_SCHED __builtin_amdgcn_sched_barrier(0)
; template <class Epi, class Map>
; __device__ __forceinline__ void gemm_phase(LAS unsigned char* lds, const Gemm g, const Sched<Map>& S, const Epi& E) {
;     ...
;             PG8_LDA(At, 1, 1); PG8_STAGE(PG8_SB(1, 0), b3, voffB); PG8_STAGE(PG8_SB(1, 1), b3 + hstepB, voffB); PG8_STAGE(PG8_SA(1, 0), a3, voffA);
;             PG8_WAIT_V(8); PG8_WAIT_L(0); PG8_BAR; PG8_MMA(1, 0, At, B0); PG8_MMA(1, 1, At, B1); PG8_BAR; PG8_SCHED;
;         }
	s_add_i32 s9, s9, s28
	v_lshl_add_u64 v[170:171], v[170:171], 0, s[82:83]
	s_mov_b32 m0, s9
	ds_read_b128 v[204:207], v174 offset:49152
	ds_read_b128 v[208:211], v174 offset:50176
	ds_read_b128 v[212:215], v174 offset:51200
	ds_read_b128 v[216:219], v174 offset:52224
	ds_read_b128 v[220:223], v174 offset:53248
	ds_read_b128 v[224:227], v174 offset:54272
	ds_read_b128 v[228:231], v174 offset:55296
	ds_read_b128 v[232:235], v174 offset:56320
	global_load_lds_dwordx4 v[170:171], off
	s_add_i32 m0, s9, 0x2000
	s_add_u32 s10, s20, 0x80080
	v_lshl_add_u64 v[170:171], v[180:181], 0, s[82:83]
	s_addc_u32 s11, s21, 0
	s_add_i32 s9, s12, s28
	global_load_lds_dwordx4 v[170:171], off
	v_lshl_add_u64 v[170:171], s[10:11], 0, v[144:145]
	s_mov_b32 m0, s9
	s_nop 0
	global_load_lds_dwordx4 v[170:171], off
	v_lshl_add_u64 v[170:171], s[10:11], 0, v[136:137]
	s_add_i32 m0, s9, 0x2000
	s_nop 0
	global_load_lds_dwordx4 v[170:171], off
	v_lshl_add_u64 v[170:171], v[236:237], 0, s[82:83]
	s_mov_b32 m0, s36
	s_nop 0
	global_load_lds_dwordx4 v[170:171], off
	v_lshl_add_u64 v[170:171], v[238:239], 0, s[82:83]
	s_mov_b32 m0, s37
	s_nop 0
	global_load_lds_dwordx4 v[170:171], off
	s_waitcnt vmcnt(8)
	s_waitcnt lgkmcnt(0)
	s_barrier
	v_mfma_f32_16x16x32_bf16 v[60:63], v[124:127], v[204:207], v[60:63]
	v_mfma_f32_16x16x32_bf16 v[56:59], v[162:165], v[204:207], v[56:59]
	v_mfma_f32_16x16x32_bf16 v[44:47], v[124:127], v[212:215], v[44:47]
	v_mfma_f32_16x16x32_bf16 v[40:43], v[162:165], v[212:215], v[40:43]
	v_mfma_f32_16x16x32_bf16 v[28:31], v[124:127], v[220:223], v[28:31]
	v_mfma_f32_16x16x32_bf16 v[24:27], v[162:165], v[220:223], v[24:27]
	v_mfma_f32_16x16x32_bf16 v[12:15], v[124:127], v[228:231], v[12:15]
	v_mfma_f32_16x16x32_bf16 v[8:11], v[162:165], v[228:231], v[8:11]
	v_mfma_f32_16x16x32_bf16 v[60:63], v[132:135], v[208:211], v[60:63]
	v_mfma_f32_16x16x32_bf16 v[56:59], v[166:169], v[208:211], v[56:59]
	v_mfma_f32_16x16x32_bf16 v[44:47], v[132:135], v[216:219], v[44:47]
	v_mfma_f32_16x16x32_bf16 v[40:43], v[166:169], v[216:219], v[40:43]
	v_mfma_f32_16x16x32_bf16 v[28:31], v[132:135], v[224:227], v[28:31]
	v_mfma_f32_16x16x32_bf16 v[24:27], v[166:169], v[224:227], v[24:27]
	v_mfma_f32_16x16x32_bf16 v[12:15], v[132:135], v[232:235], v[12:15]
	v_mfma_f32_16x16x32_bf16 v[8:11], v[166:169], v[232:235], v[8:11]
	v_mfma_f32_16x16x32_bf16 v[52:55], v[176:179], v[204:207], v[52:55]
	v_mfma_f32_16x16x32_bf16 v[48:51], v[196:199], v[204:207], v[48:51]
	v_mfma_f32_16x16x32_bf16 v[36:39], v[176:179], v[212:215], v[36:39]
	v_mfma_f32_16x16x32_bf16 v[32:35], v[196:199], v[212:215], v[32:35]
	v_mfma_f32_16x16x32_bf16 v[20:23], v[176:179], v[220:223], v[20:23]
	v_mfma_f32_16x16x32_bf16 v[16:19], v[196:199], v[220:223], v[16:19]
	v_mfma_f32_16x16x32_bf16 v[4:7], v[176:179], v[228:231], v[4:7]
	v_mfma_f32_16x16x32_bf16 v[0:3], v[196:199], v[228:231], v[0:3]
	v_mfma_f32_16x16x32_bf16 v[52:55], v[192:195], v[208:211], v[52:55]
	v_mfma_f32_16x16x32_bf16 v[48:51], v[200:203], v[208:211], v[48:51]
	v_mfma_f32_16x16x32_bf16 v[36:39], v[192:195], v[216:219], v[36:39]
	v_mfma_f32_16x16x32_bf16 v[32:35], v[200:203], v[216:219], v[32:35]
	v_mfma_f32_16x16x32_bf16 v[20:23], v[192:195], v[224:227], v[20:23]
	v_mfma_f32_16x16x32_bf16 v[16:19], v[200:203], v[224:227], v[16:19]
	v_mfma_f32_16x16x32_bf16 v[4:7], v[192:195], v[232:235], v[4:7]
	v_mfma_f32_16x16x32_bf16 v[0:3], v[200:203], v[232:235], v[0:3]
	s_barrier
	s_add_i32 s8, s8, 2
	s_add_u32 s18, s18, 0x100
	s_addc_u32 s19, s19, 0
	s_add_u32 s6, s6, 0x100
	s_addc_u32 s7, s7, 0
	s_cmp_gt_u32 s8, 29
	s_cbranch_scc0 .LBB0_880
	s_and_b64 vcc, exec, s[44:45]
	s_cbranch_vccz .LBB0_883
	s_barrier

; #define PG8_STAGE(bufoff, gbase, voff) do { _Pragma("unroll") for (int _i = 0; _i < 2; ++_i) \
;         __builtin_amdgcn_global_load_lds((const unsigned*)((const char*)(gbase) + (voff)[_i]), (LAS unsigned*)(lds + (bufoff) + ldsw + _i * 8192), 16, 0, 0); } while (0)
; #define PG8_LDA(dst, b, h) do { _Pragma("unroll") for (int m = 0; m < 4; ++m) _Pragma("unroll") for (int k = 0; k < 2; ++k) dst[m][k] = *(const LAS bf16x8*)(lds + PG8_SA(b, h) + aoff + m * 2048 + k * 1024); } while (0)
; #define PG8_LDB(dst, b, h) do { _Pragma("unroll") for (int n = 0; n < 2; ++n) _Pragma("unroll") for (int k = 0; k < 2; ++k) dst[n][k] = *(const LAS bf16x8*)(lds + PG8_SB(b, h) + boff + n * 2048 + k * 1024); } while (0)
; #define PG8_MMA(ai, bj, At, Bt) do { __builtin_amdgcn_s_setprio(1); _Pragma("unroll") for (int m = 0; m < 4; ++m) _Pragma("unroll") for (int n = 0; n < 2; ++n) _Pragma("unroll") for (int k = 0; k < 2; ++k) \
;         acc[ai][bj][m][n] = __builtin_amdgcn_mfma_f32_16x16x32_bf16(Bt[n][k], At[m][k], acc[ai][bj][m][n], 0, 0, 0); __builtin_amdgcn_s_setprio(0); } while (0)
; #define PG8_WAIT_V(n) asm volatile("s_waitcnt vmcnt(" #n ")" ::: "memory")
; #define PG8_WAIT_L(n) asm volatile("s_waitcnt lgkmcnt(" #n ")" ::: "memory")
; #define PG8_BAR __builtin_amdgcn_s_barrier()
; #define PG8_SCHED __builtin_amdgcn_sched_barrier(0)
; template <class Epi, class Map>
; __device__ __forceinline__ void gemm_phase(LAS unsigned char* lds, const Gemm g, const Sched<Map>& S, const Epi& E) {
;     ...
;         for (int t = 0; t < nt; t += 2) {
;             const bool last = (t == nt - 2);
;             const char* a1 = cA + (size_t)(t + 1) * kstep;
;             const char* a2 = last ? nA : cA + (size_t)(t + 2) * kstep; const char* b2 = last ? nB : cB + (size_t)(t + 2) * kstep;
;             const char* a3 = a2 + kstep; const char* b3 = b2 + kstep;
;             PG8_LDB(B0, 0, 0); PG8_LDB(B1, 0, 1); PG8_SCHED; PG8_LDA(At, 0, 0); PG8_STAGE(PG8_SA(1, 1), a1 + hstepA, voffA);
;             PG8_WAIT_V(8); PG8_WAIT_L(0); PG8_BAR; PG8_MMA(0, 0, At, B0); PG8_MMA(0, 1, At, B1); PG8_BAR; PG8_SCHED;
;             PG8_LDA(At, 0, 1); PG8_STAGE(PG8_SB(0, 0), b2, voffB); PG8_STAGE(PG8_SB(0, 1), b2 + hstepB, voffB); PG8_STAGE(PG8_SA(0, 0), a2, voffA);
;             PG8_WAIT_V(8); PG8_WAIT_L(0); PG8_BAR; PG8_MMA(1, 0, At, B0); PG8_MMA(1, 1, At, B1); PG8_BAR; PG8_SCHED;
.LBB0_952:
	s_add_u32 s40, s36, 0xfff00080
	s_addc_u32 s41, s37, -1
	s_add_i32 s50, 0, 0x10000
	s_cmp_eq_u32 s49, 60
	s_cselect_b32 s43, s33, s41
	s_cselect_b32 s42, s44, s40
	s_cselect_b32 s41, s45, s48
	s_cselect_b32 s40, s46, s47
	s_add_i32 s52, 0, 0x14000
	v_add_u32_e32 v108, s50, v173
	v_add_u32_e32 v170, s52, v173
	ds_read_b128 v[64:67], v108
	ds_read_b128 v[68:71], v108 offset:1024
	ds_read_b128 v[72:75], v108 offset:2048
	ds_read_b128 v[108:111], v108 offset:3072
	ds_read_b128 v[166:169], v170
	ds_read_b128 v[176:179], v170 offset:1024
	ds_read_b128 v[192:195], v170 offset:2048
	ds_read_b128 v[196:199], v170 offset:3072
	v_lshl_add_u64 v[170:171], s[36:37], 0, v[162:163]
	s_add_i32 m0, s1, 0xc000
	ds_read_b128 v[200:203], v174
	ds_read_b128 v[204:207], v174 offset:1024
	ds_read_b128 v[208:211], v174 offset:2048
	ds_read_b128 v[212:215], v174 offset:3072
	ds_read_b128 v[216:219], v174 offset:4096
	ds_read_b128 v[220:223], v174 offset:5120
	ds_read_b128 v[224:227], v174 offset:6144
	ds_read_b128 v[228:231], v174 offset:7168
	global_load_lds_dwordx4 v[170:171], off
	v_lshl_add_u64 v[170:171], s[36:37], 0, v[164:165]
	s_add_i32 m0, s1, 0xe000
	s_nop 0
	global_load_lds_dwordx4 v[170:171], off
	s_waitcnt vmcnt(8)
	s_waitcnt lgkmcnt(0)
	s_barrier
	v_mfma_f32_16x16x32_bf16 v[140:143], v[64:67], v[200:203], v[140:143]
	v_mfma_f32_16x16x32_bf16 v[136:139], v[72:75], v[200:203], v[136:139]
	v_mfma_f32_16x16x32_bf16 v[132:135], v[64:67], v[208:211], v[132:135]
	v_mfma_f32_16x16x32_bf16 v[128:131], v[72:75], v[208:211], v[128:131]
	v_mfma_f32_16x16x32_bf16 v[104:107], v[64:67], v[216:219], v[104:107]
	v_mfma_f32_16x16x32_bf16 v[100:103], v[72:75], v[216:219], v[100:103]
	v_mfma_f32_16x16x32_bf16 v[96:99], v[64:67], v[224:227], v[96:99]
	v_mfma_f32_16x16x32_bf16 v[92:95], v[72:75], v[224:227], v[92:95]
	v_mfma_f32_16x16x32_bf16 v[140:143], v[68:71], v[204:207], v[140:143]
	v_mfma_f32_16x16x32_bf16 v[136:139], v[108:111], v[204:207], v[136:139]
	v_mfma_f32_16x16x32_bf16 v[132:135], v[68:71], v[212:215], v[132:135]
	v_mfma_f32_16x16x32_bf16 v[128:131], v[108:111], v[212:215], v[128:131]
	v_mfma_f32_16x16x32_bf16 v[104:107], v[68:71], v[220:223], v[104:107]
	v_mfma_f32_16x16x32_bf16 v[100:103], v[108:111], v[220:223], v[100:103]
	v_mfma_f32_16x16x32_bf16 v[96:99], v[68:71], v[228:231], v[96:99]
	v_mfma_f32_16x16x32_bf16 v[92:95], v[108:111], v[228:231], v[92:95]
	v_mfma_f32_16x16x32_bf16 v[124:127], v[166:169], v[200:203], v[124:127]
	v_mfma_f32_16x16x32_bf16 v[120:123], v[192:195], v[200:203], v[120:123]
	v_mfma_f32_16x16x32_bf16 v[116:119], v[166:169], v[208:211], v[116:119]
	v_mfma_f32_16x16x32_bf16 v[112:115], v[192:195], v[208:211], v[112:115]
	v_mfma_f32_16x16x32_bf16 v[88:91], v[166:169], v[216:219], v[88:91]
	v_mfma_f32_16x16x32_bf16 v[84:87], v[192:195], v[216:219], v[84:87]
	v_mfma_f32_16x16x32_bf16 v[80:83], v[166:169], v[224:227], v[80:83]
	v_mfma_f32_16x16x32_bf16 v[76:79], v[192:195], v[224:227], v[76:79]
	v_mfma_f32_16x16x32_bf16 v[124:127], v[176:179], v[204:207], v[124:127]
	v_mfma_f32_16x16x32_bf16 v[120:123], v[196:199], v[204:207], v[120:123]
	v_mfma_f32_16x16x32_bf16 v[116:119], v[176:179], v[212:215], v[116:119]
	v_mfma_f32_16x16x32_bf16 v[112:115], v[196:199], v[212:215], v[112:115]
	v_mfma_f32_16x16x32_bf16 v[88:91], v[176:179], v[220:223], v[88:91]
	v_mfma_f32_16x16x32_bf16 v[84:87], v[196:199], v[220:223], v[84:87]
	v_mfma_f32_16x16x32_bf16 v[80:83], v[176:179], v[228:231], v[80:83]
	v_mfma_f32_16x16x32_bf16 v[76:79], v[196:199], v[228:231], v[76:79]
	s_barrier
	s_add_i32 s50, s50, s0
	v_lshl_add_u64 v[170:171], s[40:41], 0, v[144:145]
	s_mov_b32 m0, s50
	ds_read_b128 v[200:203], v174 offset:16384
	ds_read_b128 v[204:207], v174 offset:17408
	ds_read_b128 v[208:211], v174 offset:18432
	ds_read_b128 v[212:215], v174 offset:19456
	ds_read_b128 v[216:219], v174 offset:20480
	ds_read_b128 v[220:223], v174 offset:21504
	ds_read_b128 v[224:227], v174 offset:22528
	ds_read_b128 v[228:231], v174 offset:23552
	global_load_lds_dwordx4 v[170:171], off
	s_add_i32 m0, s50, 0x2000
	s_add_u32 s50, s40, 0x100000
	v_lshl_add_u64 v[180:181], s[40:41], 0, v[160:161]
	s_addc_u32 s51, s41, 0
	s_add_i32 s52, s52, s0
	global_load_lds_dwordx4 v[180:181], off
	v_lshl_add_u64 v[232:233], s[50:51], 0, v[144:145]
	s_mov_b32 m0, s52
	v_lshl_add_u64 v[234:235], s[42:43], 0, v[160:161]
	global_load_lds_dwordx4 v[232:233], off
	v_lshl_add_u64 v[232:233], s[50:51], 0, v[160:161]
	s_add_i32 m0, s52, 0x2000
	s_nop 0
	global_load_lds_dwordx4 v[232:233], off
	v_lshl_add_u64 v[232:233], s[42:43], 0, v[144:145]
	s_mov_b32 m0, s1
	s_nop 0
	global_load_lds_dwordx4 v[232:233], off
	s_mov_b32 m0, s2
	s_nop 0
	global_load_lds_dwordx4 v[234:235], off
	s_waitcnt vmcnt(8)
	s_waitcnt lgkmcnt(0)
	s_barrier
; #define PG8_STAGE(bufoff, gbase, voff) do { _Pragma("unroll") for (int _i = 0; _i < 2; ++_i) \
;         __builtin_amdgcn_global_load_lds((const unsigned*)((const char*)(gbase) + (voff)[_i]), (LAS unsigned*)(lds + (bufoff) + ldsw + _i * 8192), 16, 0, 0); } while (0)
; #define PG8_LDA(dst, b, h) do { _Pragma("unroll") for (int m = 0; m < 4; ++m) _Pragma("unroll") for (int k = 0; k < 2; ++k) dst[m][k] = *(const LAS bf16x8*)(lds + PG8_SA(b, h) + aoff + m * 2048 + k * 1024); } while (0)
; #define PG8_LDB(dst, b, h) do { _Pragma("unroll") for (int n = 0; n < 2; ++n) _Pragma("unroll") for (int k = 0; k < 2; ++k) dst[n][k] = *(const LAS bf16x8*)(lds + PG8_SB(b, h) + boff + n * 2048 + k * 1024); } while (0)
; #define PG8_MMA(ai, bj, At, Bt) do { __builtin_amdgcn_s_setprio(1); _Pragma("unroll") for (int m = 0; m < 4; ++m) _Pragma("unroll") for (int n = 0; n < 2; ++n) _Pragma("unroll") for (int k = 0; k < 2; ++k) \
;         acc[ai][bj][m][n] = __builtin_amdgcn_mfma_f32_16x16x32_bf16(Bt[n][k], At[m][k], acc[ai][bj][m][n], 0, 0, 0); __builtin_amdgcn_s_setprio(0); } while (0)
; #define PG8_WAIT_V(n) asm volatile("s_waitcnt vmcnt(" #n ")" ::: "memory")
; #define PG8_WAIT_L(n) asm volatile("s_waitcnt lgkmcnt(" #n ")" ::: "memory")
; #define PG8_BAR __builtin_amdgcn_s_barrier()
; #define PG8_SCHED __builtin_amdgcn_sched_barrier(0)
; template <class Epi, class Map>
; __device__ __forceinline__ void gemm_phase(LAS unsigned char* lds, const Gemm g, const Sched<Map>& S, const Epi& E) {
;     ...
;             PG8_WAIT_V(8); PG8_WAIT_L(0); PG8_BAR; PG8_MMA(1, 0, At, B0); PG8_MMA(1, 1, At, B1); PG8_BAR; PG8_SCHED;
;             PG8_LDB(B0, 1, 0); PG8_LDB(B1, 1, 1); PG8_SCHED; PG8_LDA(At, 1, 0); PG8_STAGE(PG8_SA(0, 1), a2 + hstepA, voffA);
;             PG8_WAIT_V(8); PG8_WAIT_L(0); PG8_BAR; PG8_MMA(0, 0, At, B0); PG8_MMA(0, 1, At, B1); PG8_BAR; PG8_SCHED;
;             PG8_LDA(At, 1, 1); PG8_STAGE(PG8_SB(1, 0), b3, voffB); PG8_STAGE(PG8_SB(1, 1), b3 + hstepB, voffB); PG8_STAGE(PG8_SA(1, 0), a3, voffA);
	v_mfma_f32_16x16x32_bf16 v[60:63], v[64:67], v[200:203], v[60:63]
	v_mfma_f32_16x16x32_bf16 v[56:59], v[72:75], v[200:203], v[56:59]
	v_mfma_f32_16x16x32_bf16 v[52:55], v[64:67], v[208:211], v[52:55]
	v_mfma_f32_16x16x32_bf16 v[48:51], v[72:75], v[208:211], v[48:51]
	v_mfma_f32_16x16x32_bf16 v[28:31], v[64:67], v[216:219], v[28:31]
	v_mfma_f32_16x16x32_bf16 v[24:27], v[72:75], v[216:219], v[24:27]
	v_mfma_f32_16x16x32_bf16 v[20:23], v[64:67], v[224:227], v[20:23]
	v_mfma_f32_16x16x32_bf16 v[8:11], v[72:75], v[224:227], v[8:11]
	v_mfma_f32_16x16x32_bf16 v[60:63], v[68:71], v[204:207], v[60:63]
	v_mfma_f32_16x16x32_bf16 v[56:59], v[108:111], v[204:207], v[56:59]
	v_mfma_f32_16x16x32_bf16 v[52:55], v[68:71], v[212:215], v[52:55]
	v_mfma_f32_16x16x32_bf16 v[48:51], v[108:111], v[212:215], v[48:51]
	v_mfma_f32_16x16x32_bf16 v[28:31], v[68:71], v[220:223], v[28:31]
	v_mfma_f32_16x16x32_bf16 v[24:27], v[108:111], v[220:223], v[24:27]
	v_mfma_f32_16x16x32_bf16 v[20:23], v[68:71], v[228:231], v[20:23]
	v_mfma_f32_16x16x32_bf16 v[8:11], v[108:111], v[228:231], v[8:11]
	v_mfma_f32_16x16x32_bf16 v[44:47], v[166:169], v[200:203], v[44:47]
	v_mfma_f32_16x16x32_bf16 v[40:43], v[192:195], v[200:203], v[40:43]
	v_mfma_f32_16x16x32_bf16 v[36:39], v[166:169], v[208:211], v[36:39]
	v_mfma_f32_16x16x32_bf16 v[32:35], v[192:195], v[208:211], v[32:35]
	v_mfma_f32_16x16x32_bf16 v[16:19], v[166:169], v[216:219], v[16:19]
	v_mfma_f32_16x16x32_bf16 v[12:15], v[192:195], v[216:219], v[12:15]
	v_mfma_f32_16x16x32_bf16 v[4:7], v[166:169], v[224:227], v[4:7]
	v_mfma_f32_16x16x32_bf16 v[0:3], v[192:195], v[224:227], v[0:3]
	v_mfma_f32_16x16x32_bf16 v[44:47], v[176:179], v[204:207], v[44:47]
	v_mfma_f32_16x16x32_bf16 v[40:43], v[196:199], v[204:207], v[40:43]
	v_mfma_f32_16x16x32_bf16 v[36:39], v[176:179], v[212:215], v[36:39]
	v_mfma_f32_16x16x32_bf16 v[32:35], v[196:199], v[212:215], v[32:35]
	v_mfma_f32_16x16x32_bf16 v[16:19], v[176:179], v[220:223], v[16:19]
	v_mfma_f32_16x16x32_bf16 v[12:15], v[196:199], v[220:223], v[12:15]
	v_mfma_f32_16x16x32_bf16 v[4:7], v[176:179], v[228:231], v[4:7]
	v_mfma_f32_16x16x32_bf16 v[0:3], v[196:199], v[228:231], v[0:3]
	s_barrier
	s_add_i32 s50, 0, 0x18000
	s_add_i32 s51, 0, 0x1c000
	v_add_u32_e32 v108, s50, v173
	v_add_u32_e32 v175, s51, v173
	ds_read_b128 v[64:67], v108
	ds_read_b128 v[68:71], v108 offset:1024
	ds_read_b128 v[72:75], v108 offset:2048
	ds_read_b128 v[108:111], v108 offset:3072
	ds_read_b128 v[166:169], v175
	ds_read_b128 v[176:179], v175 offset:1024
	ds_read_b128 v[192:195], v175 offset:2048
	ds_read_b128 v[196:199], v175 offset:3072
	s_add_u32 s42, s42, 0x100000
	s_addc_u32 s43, s43, 0
	s_mov_b32 m0, s3
	v_lshl_add_u64 v[236:237], s[42:43], 0, v[144:145]
	ds_read_b128 v[200:203], v174 offset:32768
	ds_read_b128 v[204:207], v174 offset:33792
	ds_read_b128 v[208:211], v174 offset:34816
	ds_read_b128 v[212:215], v174 offset:35840
	ds_read_b128 v[216:219], v174 offset:36864
	ds_read_b128 v[220:223], v174 offset:37888
	ds_read_b128 v[224:227], v174 offset:38912
	ds_read_b128 v[228:231], v174 offset:39936
	global_load_lds_dwordx4 v[236:237], off
	v_lshl_add_u64 v[236:237], s[42:43], 0, v[160:161]
	s_mov_b32 m0, s4
	s_nop 0
	global_load_lds_dwordx4 v[236:237], off
	s_waitcnt vmcnt(8)
	s_waitcnt lgkmcnt(0)
	s_barrier
	v_mfma_f32_16x16x32_bf16 v[140:143], v[64:67], v[200:203], v[140:143]
	v_mfma_f32_16x16x32_bf16 v[136:139], v[72:75], v[200:203], v[136:139]
	v_mfma_f32_16x16x32_bf16 v[132:135], v[64:67], v[208:211], v[132:135]
	v_mfma_f32_16x16x32_bf16 v[128:131], v[72:75], v[208:211], v[128:131]
	v_mfma_f32_16x16x32_bf16 v[104:107], v[64:67], v[216:219], v[104:107]
	v_mfma_f32_16x16x32_bf16 v[100:103], v[72:75], v[216:219], v[100:103]
	v_mfma_f32_16x16x32_bf16 v[96:99], v[64:67], v[224:227], v[96:99]
	v_mfma_f32_16x16x32_bf16 v[92:95], v[72:75], v[224:227], v[92:95]
	v_mfma_f32_16x16x32_bf16 v[140:143], v[68:71], v[204:207], v[140:143]
	v_mfma_f32_16x16x32_bf16 v[136:139], v[108:111], v[204:207], v[136:139]
	v_mfma_f32_16x16x32_bf16 v[132:135], v[68:71], v[212:215], v[132:135]
	v_mfma_f32_16x16x32_bf16 v[128:131], v[108:111], v[212:215], v[128:131]
	v_mfma_f32_16x16x32_bf16 v[104:107], v[68:71], v[220:223], v[104:107]
	v_mfma_f32_16x16x32_bf16 v[100:103], v[108:111], v[220:223], v[100:103]
	v_mfma_f32_16x16x32_bf16 v[96:99], v[68:71], v[228:231], v[96:99]
	v_mfma_f32_16x16x32_bf16 v[92:95], v[108:111], v[228:231], v[92:95]
	v_mfma_f32_16x16x32_bf16 v[124:127], v[166:169], v[200:203], v[124:127]
	v_mfma_f32_16x16x32_bf16 v[120:123], v[192:195], v[200:203], v[120:123]
	v_mfma_f32_16x16x32_bf16 v[116:119], v[166:169], v[208:211], v[116:119]
	v_mfma_f32_16x16x32_bf16 v[112:115], v[192:195], v[208:211], v[112:115]
	v_mfma_f32_16x16x32_bf16 v[88:91], v[166:169], v[216:219], v[88:91]
	v_mfma_f32_16x16x32_bf16 v[84:87], v[192:195], v[216:219], v[84:87]
	v_mfma_f32_16x16x32_bf16 v[80:83], v[166:169], v[224:227], v[80:83]
	v_mfma_f32_16x16x32_bf16 v[76:79], v[192:195], v[224:227], v[76:79]
	v_mfma_f32_16x16x32_bf16 v[124:127], v[176:179], v[204:207], v[124:127]
	v_mfma_f32_16x16x32_bf16 v[120:123], v[196:199], v[204:207], v[120:123]
	v_mfma_f32_16x16x32_bf16 v[116:119], v[176:179], v[212:215], v[116:119]
	v_mfma_f32_16x16x32_bf16 v[112:115], v[196:199], v[212:215], v[112:115]
	v_mfma_f32_16x16x32_bf16 v[88:91], v[176:179], v[220:223], v[88:91]
	v_mfma_f32_16x16x32_bf16 v[84:87], v[196:199], v[220:223], v[84:87]
	v_mfma_f32_16x16x32_bf16 v[80:83], v[176:179], v[228:231], v[80:83]
	v_mfma_f32_16x16x32_bf16 v[76:79], v[196:199], v[228:231], v[76:79]
	s_barrier
; #define PG8_STAGE(bufoff, gbase, voff) do { _Pragma("unroll") for (int _i = 0; _i < 2; ++_i) \
;         __builtin_amdgcn_global_load_lds((const unsigned*)((const char*)(gbase) + (voff)[_i]), (LAS unsigned*)(lds + (bufoff) + ldsw + _i * 8192), 16, 0, 0); } while (0)
; #define PG8_LDA(dst, b, h) do { _Pragma("unroll") for (int m = 0; m < 4; ++m) _Pragma("unroll") for (int k = 0; k < 2; ++k) dst[m][k] = *(const LAS bf16x8*)(lds + PG8_SA(b, h) + aoff + m * 2048 + k * 1024); } while (0)
; #define PG8_MMA(ai, bj, At, Bt) do { __builtin_amdgcn_s_setprio(1); _Pragma("unroll") for (int m = 0; m < 4; ++m) _Pragma("unroll") for (int n = 0; n < 2; ++n) _Pragma("unroll") for (int k = 0; k < 2; ++k) \
;         acc[ai][bj][m][n] = __builtin_amdgcn_mfma_f32_16x16x32_bf16(Bt[n][k], At[m][k], acc[ai][bj][m][n], 0, 0, 0); __builtin_amdgcn_s_setprio(0); } while (0)
; #define PG8_WAIT_V(n) asm volatile("s_waitcnt vmcnt(" #n ")" ::: "memory")
; #define PG8_WAIT_L(n) asm volatile("s_waitcnt lgkmcnt(" #n ")" ::: "memory")
; #define PG8_BAR __builtin_amdgcn_s_barrier()
; #define PG8_SCHED __builtin_amdgcn_sched_barrier(0)
; template <class Epi, class Map>
; __device__ __forceinline__ void gemm_phase(LAS unsigned char* lds, const Gemm g, const Sched<Map>& S, const Epi& E) {
;     ...
;             PG8_LDA(At, 1, 1); PG8_STAGE(PG8_SB(1, 0), b3, voffB); PG8_STAGE(PG8_SB(1, 1), b3 + hstepB, voffB); PG8_STAGE(PG8_SA(1, 0), a3, voffA);
;             PG8_WAIT_V(8); PG8_WAIT_L(0); PG8_BAR; PG8_MMA(1, 0, At, B0); PG8_MMA(1, 1, At, B1); PG8_BAR; PG8_SCHED;
;         }
	s_add_i32 s42, s50, s0
	v_lshl_add_u64 v[170:171], v[170:171], 0, s[82:83]
	s_mov_b32 m0, s42
	ds_read_b128 v[200:203], v174 offset:49152
	ds_read_b128 v[204:207], v174 offset:50176
	ds_read_b128 v[208:211], v174 offset:51200
	ds_read_b128 v[212:215], v174 offset:52224
	ds_read_b128 v[216:219], v174 offset:53248
	ds_read_b128 v[220:223], v174 offset:54272
	ds_read_b128 v[224:227], v174 offset:55296
	ds_read_b128 v[228:231], v174 offset:56320
	global_load_lds_dwordx4 v[170:171], off
	s_add_i32 m0, s42, 0x2000
	s_add_u32 s40, s40, 0x100080
	v_lshl_add_u64 v[170:171], v[180:181], 0, s[82:83]
	s_addc_u32 s41, s41, 0
	s_add_i32 s42, s51, s0
	global_load_lds_dwordx4 v[170:171], off
	v_lshl_add_u64 v[170:171], s[40:41], 0, v[144:145]
	s_mov_b32 m0, s42
	s_nop 0
	global_load_lds_dwordx4 v[170:171], off
	v_lshl_add_u64 v[170:171], s[40:41], 0, v[160:161]
	s_add_i32 m0, s42, 0x2000
	s_nop 0
	global_load_lds_dwordx4 v[170:171], off
	v_lshl_add_u64 v[170:171], v[232:233], 0, s[82:83]
	s_mov_b32 m0, s7
	s_nop 0
	global_load_lds_dwordx4 v[170:171], off
	v_lshl_add_u64 v[170:171], v[234:235], 0, s[82:83]
	s_mov_b32 m0, s8
	s_nop 0
	global_load_lds_dwordx4 v[170:171], off
	s_waitcnt vmcnt(8)
	s_waitcnt lgkmcnt(0)
	s_barrier
	v_mfma_f32_16x16x32_bf16 v[60:63], v[64:67], v[200:203], v[60:63]
	v_mfma_f32_16x16x32_bf16 v[56:59], v[72:75], v[200:203], v[56:59]
	v_mfma_f32_16x16x32_bf16 v[52:55], v[64:67], v[208:211], v[52:55]
	v_mfma_f32_16x16x32_bf16 v[48:51], v[72:75], v[208:211], v[48:51]
	v_mfma_f32_16x16x32_bf16 v[28:31], v[64:67], v[216:219], v[28:31]
	v_mfma_f32_16x16x32_bf16 v[24:27], v[72:75], v[216:219], v[24:27]
	v_mfma_f32_16x16x32_bf16 v[20:23], v[64:67], v[224:227], v[20:23]
	v_mfma_f32_16x16x32_bf16 v[8:11], v[72:75], v[224:227], v[8:11]
	v_mfma_f32_16x16x32_bf16 v[60:63], v[68:71], v[204:207], v[60:63]
	v_mfma_f32_16x16x32_bf16 v[56:59], v[108:111], v[204:207], v[56:59]
	v_mfma_f32_16x16x32_bf16 v[52:55], v[68:71], v[212:215], v[52:55]
	v_mfma_f32_16x16x32_bf16 v[48:51], v[108:111], v[212:215], v[48:51]
	v_mfma_f32_16x16x32_bf16 v[28:31], v[68:71], v[220:223], v[28:31]
	v_mfma_f32_16x16x32_bf16 v[24:27], v[108:111], v[220:223], v[24:27]
	v_mfma_f32_16x16x32_bf16 v[20:23], v[68:71], v[228:231], v[20:23]
	v_mfma_f32_16x16x32_bf16 v[8:11], v[108:111], v[228:231], v[8:11]
	v_mfma_f32_16x16x32_bf16 v[44:47], v[166:169], v[200:203], v[44:47]
	v_mfma_f32_16x16x32_bf16 v[40:43], v[192:195], v[200:203], v[40:43]
	v_mfma_f32_16x16x32_bf16 v[36:39], v[166:169], v[208:211], v[36:39]
	v_mfma_f32_16x16x32_bf16 v[32:35], v[192:195], v[208:211], v[32:35]
	v_mfma_f32_16x16x32_bf16 v[16:19], v[166:169], v[216:219], v[16:19]
	v_mfma_f32_16x16x32_bf16 v[12:15], v[192:195], v[216:219], v[12:15]
	v_mfma_f32_16x16x32_bf16 v[4:7], v[166:169], v[224:227], v[4:7]
	v_mfma_f32_16x16x32_bf16 v[0:3], v[192:195], v[224:227], v[0:3]
	v_mfma_f32_16x16x32_bf16 v[44:47], v[176:179], v[204:207], v[44:47]
	v_mfma_f32_16x16x32_bf16 v[40:43], v[196:199], v[204:207], v[40:43]
	v_mfma_f32_16x16x32_bf16 v[36:39], v[176:179], v[212:215], v[36:39]
	v_mfma_f32_16x16x32_bf16 v[32:35], v[196:199], v[212:215], v[32:35]
	v_mfma_f32_16x16x32_bf16 v[16:19], v[176:179], v[220:223], v[16:19]
	v_mfma_f32_16x16x32_bf16 v[12:15], v[196:199], v[220:223], v[12:15]
	v_mfma_f32_16x16x32_bf16 v[4:7], v[176:179], v[228:231], v[4:7]
	v_mfma_f32_16x16x32_bf16 v[0:3], v[196:199], v[228:231], v[0:3]
	s_barrier
	s_add_i32 s49, s49, 2
	s_add_u32 s36, s36, 0x100
	s_addc_u32 s37, s37, 0
	s_add_u32 s47, s47, 0x100
	s_addc_u32 s48, s48, 0
	s_cmp_gt_u32 s49, 61
	s_cbranch_scc0 .LBB0_952
	s_and_b64 vcc, exec, s[28:29]
	s_cbranch_vccz .LBB0_955
	s_barrier

; #define PG8_STAGE(bufoff, gbase, voff) do { _Pragma("unroll") for (int _i = 0; _i < 2; ++_i) \
;         __builtin_amdgcn_global_load_lds((const unsigned*)((const char*)(gbase) + (voff)[_i]), (LAS unsigned*)(lds + (bufoff) + ldsw + _i * 8192), 16, 0, 0); } while (0)
; #define PG8_LDA(dst, b, h) do { _Pragma("unroll") for (int m = 0; m < 4; ++m) _Pragma("unroll") for (int k = 0; k < 2; ++k) dst[m][k] = *(const LAS bf16x8*)(lds + PG8_SA(b, h) + aoff + m * 2048 + k * 1024); } while (0)
; #define PG8_LDB(dst, b, h) do { _Pragma("unroll") for (int n = 0; n < 2; ++n) _Pragma("unroll") for (int k = 0; k < 2; ++k) dst[n][k] = *(const LAS bf16x8*)(lds + PG8_SB(b, h) + boff + n * 2048 + k * 1024); } while (0)
; #define PG8_MMA(ai, bj, At, Bt) do { __builtin_amdgcn_s_setprio(1); _Pragma("unroll") for (int m = 0; m < 4; ++m) _Pragma("unroll") for (int n = 0; n < 2; ++n) _Pragma("unroll") for (int k = 0; k < 2; ++k) \
;         acc[ai][bj][m][n] = __builtin_amdgcn_mfma_f32_16x16x32_bf16(Bt[n][k], At[m][k], acc[ai][bj][m][n], 0, 0, 0); __builtin_amdgcn_s_setprio(0); } while (0)
; #define PG8_WAIT_V(n) asm volatile("s_waitcnt vmcnt(" #n ")" ::: "memory")
; #define PG8_WAIT_L(n) asm volatile("s_waitcnt lgkmcnt(" #n ")" ::: "memory")
; #define PG8_BAR __builtin_amdgcn_s_barrier()
; #define PG8_SCHED __builtin_amdgcn_sched_barrier(0)
; template <class Epi, class Map>
; __device__ __forceinline__ void gemm_phase(LAS unsigned char* lds, const Gemm g, const Sched<Map>& S, const Epi& E) {
;     ...
;         for (int t = 0; t < nt; t += 2) {
;             const bool last = (t == nt - 2);
;             const char* a1 = cA + (size_t)(t + 1) * kstep;
;             const char* a2 = last ? nA : cA + (size_t)(t + 2) * kstep; const char* b2 = last ? nB : cB + (size_t)(t + 2) * kstep;
;             const char* a3 = a2 + kstep; const char* b3 = b2 + kstep;
;             PG8_LDB(B0, 0, 0); PG8_LDB(B1, 0, 1); PG8_SCHED; PG8_LDA(At, 0, 0); PG8_STAGE(PG8_SA(1, 1), a1 + hstepA, voffA);
;             PG8_WAIT_V(8); PG8_WAIT_L(0); PG8_BAR; PG8_MMA(0, 0, At, B0); PG8_MMA(0, 1, At, B1); PG8_BAR; PG8_SCHED;
;             PG8_LDA(At, 0, 1); PG8_STAGE(PG8_SB(0, 0), b2, voffB); PG8_STAGE(PG8_SB(0, 1), b2 + hstepB, voffB); PG8_STAGE(PG8_SA(0, 0), a2, voffA);
;             PG8_WAIT_V(8); PG8_WAIT_L(0); PG8_BAR; PG8_MMA(1, 0, At, B0); PG8_MMA(1, 1, At, B1); PG8_BAR; PG8_SCHED;
.LBB0_1088:
	s_add_u32 s34, s30, 0xfff80080
	s_addc_u32 s35, s31, -1
	s_add_i32 s41, 0, 0x10000
	s_cmp_eq_u32 s40, 28
	s_cselect_b32 s37, s12, s35
	s_cselect_b32 s36, s13, s34
	v_add_u32_e32 v138, s41, v142
	s_cselect_b32 s35, s14, s33
	s_cselect_b32 s34, s15, s21
	s_add_i32 s46, 0, 0x14000
	ds_read_b128 v[160:163], v138
	ds_read_b128 v[164:167], v138 offset:1024
	ds_read_b128 v[168:171], v138 offset:2048
	ds_read_b128 v[172:175], v138 offset:3072
	v_add_u32_e32 v138, s46, v142
	ds_read_b128 v[176:179], v138
	ds_read_b128 v[192:195], v138 offset:1024
	ds_read_b128 v[196:199], v138 offset:2048
	ds_read_b128 v[200:203], v138 offset:3072
	v_lshl_add_u64 v[138:139], s[30:31], 0, v[134:135]
	s_add_i32 m0, s1, 0xc000
	ds_read_b128 v[204:207], v143
	ds_read_b128 v[208:211], v143 offset:1024
	ds_read_b128 v[212:215], v143 offset:2048
	ds_read_b128 v[216:219], v143 offset:3072
	ds_read_b128 v[220:223], v143 offset:4096
	ds_read_b128 v[224:227], v143 offset:5120
	ds_read_b128 v[228:231], v143 offset:6144
	ds_read_b128 v[232:235], v143 offset:7168
	global_load_lds_dwordx4 v[138:139], off
	v_lshl_add_u64 v[138:139], s[30:31], 0, v[136:137]
	s_add_i32 m0, s1, 0xe000
	s_nop 0
	global_load_lds_dwordx4 v[138:139], off
	s_waitcnt vmcnt(8)
	s_waitcnt lgkmcnt(0)
	s_barrier
	v_mfma_f32_16x16x32_bf16 v[124:127], v[160:163], v[204:207], v[124:127]
	v_mfma_f32_16x16x32_bf16 v[120:123], v[168:171], v[204:207], v[120:123]
	v_mfma_f32_16x16x32_bf16 v[108:111], v[160:163], v[212:215], v[108:111]
	v_mfma_f32_16x16x32_bf16 v[104:107], v[168:171], v[212:215], v[104:107]
	v_mfma_f32_16x16x32_bf16 v[92:95], v[160:163], v[220:223], v[92:95]
	v_mfma_f32_16x16x32_bf16 v[88:91], v[168:171], v[220:223], v[88:91]
	v_mfma_f32_16x16x32_bf16 v[76:79], v[160:163], v[228:231], v[76:79]
	v_mfma_f32_16x16x32_bf16 v[72:75], v[168:171], v[228:231], v[72:75]
	v_mfma_f32_16x16x32_bf16 v[124:127], v[164:167], v[208:211], v[124:127]
	v_mfma_f32_16x16x32_bf16 v[120:123], v[172:175], v[208:211], v[120:123]
	v_mfma_f32_16x16x32_bf16 v[108:111], v[164:167], v[216:219], v[108:111]
	v_mfma_f32_16x16x32_bf16 v[104:107], v[172:175], v[216:219], v[104:107]
	v_mfma_f32_16x16x32_bf16 v[92:95], v[164:167], v[224:227], v[92:95]
	v_mfma_f32_16x16x32_bf16 v[88:91], v[172:175], v[224:227], v[88:91]
	v_mfma_f32_16x16x32_bf16 v[76:79], v[164:167], v[232:235], v[76:79]
	v_mfma_f32_16x16x32_bf16 v[72:75], v[172:175], v[232:235], v[72:75]
	v_mfma_f32_16x16x32_bf16 v[116:119], v[176:179], v[204:207], v[116:119]
	v_mfma_f32_16x16x32_bf16 v[112:115], v[196:199], v[204:207], v[112:115]
	v_mfma_f32_16x16x32_bf16 v[100:103], v[176:179], v[212:215], v[100:103]
	v_mfma_f32_16x16x32_bf16 v[96:99], v[196:199], v[212:215], v[96:99]
	v_mfma_f32_16x16x32_bf16 v[84:87], v[176:179], v[220:223], v[84:87]
	v_mfma_f32_16x16x32_bf16 v[80:83], v[196:199], v[220:223], v[80:83]
	v_mfma_f32_16x16x32_bf16 v[68:71], v[176:179], v[228:231], v[68:71]
	v_mfma_f32_16x16x32_bf16 v[64:67], v[196:199], v[228:231], v[64:67]
	v_mfma_f32_16x16x32_bf16 v[116:119], v[192:195], v[208:211], v[116:119]
	v_mfma_f32_16x16x32_bf16 v[112:115], v[200:203], v[208:211], v[112:115]
	v_mfma_f32_16x16x32_bf16 v[100:103], v[192:195], v[216:219], v[100:103]
	v_mfma_f32_16x16x32_bf16 v[96:99], v[200:203], v[216:219], v[96:99]
	v_mfma_f32_16x16x32_bf16 v[84:87], v[192:195], v[224:227], v[84:87]
	v_mfma_f32_16x16x32_bf16 v[80:83], v[200:203], v[224:227], v[80:83]
	v_mfma_f32_16x16x32_bf16 v[68:71], v[192:195], v[232:235], v[68:71]
	v_mfma_f32_16x16x32_bf16 v[64:67], v[200:203], v[232:235], v[64:67]
	s_barrier
	s_add_i32 s41, s41, s0
	v_lshl_add_u64 v[138:139], s[34:35], 0, v[144:145]
	s_mov_b32 m0, s41
	ds_read_b128 v[204:207], v143 offset:16384
	ds_read_b128 v[208:211], v143 offset:17408
	ds_read_b128 v[212:215], v143 offset:18432
	ds_read_b128 v[216:219], v143 offset:19456
	ds_read_b128 v[220:223], v143 offset:20480
	ds_read_b128 v[224:227], v143 offset:21504
	ds_read_b128 v[228:231], v143 offset:22528
	ds_read_b128 v[232:235], v143 offset:23552
	global_load_lds_dwordx4 v[138:139], off
	s_add_i32 m0, s41, 0x2000
	s_add_u32 s44, s34, 0x80000
	v_lshl_add_u64 v[180:181], s[34:35], 0, v[128:129]
	s_addc_u32 s45, s35, 0
	s_add_i32 s41, s46, s0
	global_load_lds_dwordx4 v[180:181], off
	v_lshl_add_u64 v[236:237], s[44:45], 0, v[144:145]
	s_mov_b32 m0, s41
	v_lshl_add_u64 v[238:239], s[36:37], 0, v[130:131]
	global_load_lds_dwordx4 v[236:237], off
	v_lshl_add_u64 v[236:237], s[44:45], 0, v[128:129]
	s_add_i32 m0, s41, 0x2000
	s_nop 0
	global_load_lds_dwordx4 v[236:237], off
	v_lshl_add_u64 v[236:237], s[36:37], 0, v[132:133]
	s_mov_b32 m0, s1
	s_nop 0
	global_load_lds_dwordx4 v[236:237], off
	s_mov_b32 m0, s2
	s_nop 0
	global_load_lds_dwordx4 v[238:239], off
	s_waitcnt vmcnt(8)
	s_waitcnt lgkmcnt(0)
	s_barrier
; #define PG8_STAGE(bufoff, gbase, voff) do { _Pragma("unroll") for (int _i = 0; _i < 2; ++_i) \
;         __builtin_amdgcn_global_load_lds((const unsigned*)((const char*)(gbase) + (voff)[_i]), (LAS unsigned*)(lds + (bufoff) + ldsw + _i * 8192), 16, 0, 0); } while (0)
; #define PG8_LDA(dst, b, h) do { _Pragma("unroll") for (int m = 0; m < 4; ++m) _Pragma("unroll") for (int k = 0; k < 2; ++k) dst[m][k] = *(const LAS bf16x8*)(lds + PG8_SA(b, h) + aoff + m * 2048 + k * 1024); } while (0)
; #define PG8_LDB(dst, b, h) do { _Pragma("unroll") for (int n = 0; n < 2; ++n) _Pragma("unroll") for (int k = 0; k < 2; ++k) dst[n][k] = *(const LAS bf16x8*)(lds + PG8_SB(b, h) + boff + n * 2048 + k * 1024); } while (0)
; #define PG8_MMA(ai, bj, At, Bt) do { __builtin_amdgcn_s_setprio(1); _Pragma("unroll") for (int m = 0; m < 4; ++m) _Pragma("unroll") for (int n = 0; n < 2; ++n) _Pragma("unroll") for (int k = 0; k < 2; ++k) \
;         acc[ai][bj][m][n] = __builtin_amdgcn_mfma_f32_16x16x32_bf16(Bt[n][k], At[m][k], acc[ai][bj][m][n], 0, 0, 0); __builtin_amdgcn_s_setprio(0); } while (0)
; #define PG8_WAIT_V(n) asm volatile("s_waitcnt vmcnt(" #n ")" ::: "memory")
; #define PG8_WAIT_L(n) asm volatile("s_waitcnt lgkmcnt(" #n ")" ::: "memory")
; #define PG8_BAR __builtin_amdgcn_s_barrier()
; #define PG8_SCHED __builtin_amdgcn_sched_barrier(0)
; template <class Epi, class Map>
; __device__ __forceinline__ void gemm_phase(LAS unsigned char* lds, const Gemm g, const Sched<Map>& S, const Epi& E) {
;     ...
;             PG8_WAIT_V(8); PG8_WAIT_L(0); PG8_BAR; PG8_MMA(1, 0, At, B0); PG8_MMA(1, 1, At, B1); PG8_BAR; PG8_SCHED;
;             PG8_LDB(B0, 1, 0); PG8_LDB(B1, 1, 1); PG8_SCHED; PG8_LDA(At, 1, 0); PG8_STAGE(PG8_SA(0, 1), a2 + hstepA, voffA);
;             PG8_WAIT_V(8); PG8_WAIT_L(0); PG8_BAR; PG8_MMA(0, 0, At, B0); PG8_MMA(0, 1, At, B1); PG8_BAR; PG8_SCHED;
;             PG8_LDA(At, 1, 1); PG8_STAGE(PG8_SB(1, 0), b3, voffB); PG8_STAGE(PG8_SB(1, 1), b3 + hstepB, voffB); PG8_STAGE(PG8_SA(1, 0), a3, voffA);
	v_mfma_f32_16x16x32_bf16 v[60:63], v[160:163], v[204:207], v[60:63]
	v_mfma_f32_16x16x32_bf16 v[56:59], v[168:171], v[204:207], v[56:59]
	v_mfma_f32_16x16x32_bf16 v[44:47], v[160:163], v[212:215], v[44:47]
	v_mfma_f32_16x16x32_bf16 v[40:43], v[168:171], v[212:215], v[40:43]
	v_mfma_f32_16x16x32_bf16 v[28:31], v[160:163], v[220:223], v[28:31]
	v_mfma_f32_16x16x32_bf16 v[24:27], v[168:171], v[220:223], v[24:27]
	v_mfma_f32_16x16x32_bf16 v[12:15], v[160:163], v[228:231], v[12:15]
	v_mfma_f32_16x16x32_bf16 v[8:11], v[168:171], v[228:231], v[8:11]
	v_mfma_f32_16x16x32_bf16 v[60:63], v[164:167], v[208:211], v[60:63]
	v_mfma_f32_16x16x32_bf16 v[56:59], v[172:175], v[208:211], v[56:59]
	v_mfma_f32_16x16x32_bf16 v[44:47], v[164:167], v[216:219], v[44:47]
	v_mfma_f32_16x16x32_bf16 v[40:43], v[172:175], v[216:219], v[40:43]
	v_mfma_f32_16x16x32_bf16 v[28:31], v[164:167], v[224:227], v[28:31]
	v_mfma_f32_16x16x32_bf16 v[24:27], v[172:175], v[224:227], v[24:27]
	v_mfma_f32_16x16x32_bf16 v[12:15], v[164:167], v[232:235], v[12:15]
	v_mfma_f32_16x16x32_bf16 v[8:11], v[172:175], v[232:235], v[8:11]
	v_mfma_f32_16x16x32_bf16 v[52:55], v[176:179], v[204:207], v[52:55]
	v_mfma_f32_16x16x32_bf16 v[48:51], v[196:199], v[204:207], v[48:51]
	v_mfma_f32_16x16x32_bf16 v[36:39], v[176:179], v[212:215], v[36:39]
	v_mfma_f32_16x16x32_bf16 v[32:35], v[196:199], v[212:215], v[32:35]
	v_mfma_f32_16x16x32_bf16 v[20:23], v[176:179], v[220:223], v[20:23]
	v_mfma_f32_16x16x32_bf16 v[16:19], v[196:199], v[220:223], v[16:19]
	v_mfma_f32_16x16x32_bf16 v[4:7], v[176:179], v[228:231], v[4:7]
	v_mfma_f32_16x16x32_bf16 v[0:3], v[196:199], v[228:231], v[0:3]
	v_mfma_f32_16x16x32_bf16 v[52:55], v[192:195], v[208:211], v[52:55]
	v_mfma_f32_16x16x32_bf16 v[48:51], v[200:203], v[208:211], v[48:51]
	v_mfma_f32_16x16x32_bf16 v[36:39], v[192:195], v[216:219], v[36:39]
	v_mfma_f32_16x16x32_bf16 v[32:35], v[200:203], v[216:219], v[32:35]
	v_mfma_f32_16x16x32_bf16 v[20:23], v[192:195], v[224:227], v[20:23]
	v_mfma_f32_16x16x32_bf16 v[16:19], v[200:203], v[224:227], v[16:19]
	v_mfma_f32_16x16x32_bf16 v[4:7], v[192:195], v[232:235], v[4:7]
	v_mfma_f32_16x16x32_bf16 v[0:3], v[200:203], v[232:235], v[0:3]
	s_barrier
	s_add_i32 s41, 0, 0x18000
	v_add_u32_e32 v159, s41, v142
	s_add_i32 s44, 0, 0x1c000
	ds_read_b128 v[160:163], v159
	ds_read_b128 v[164:167], v159 offset:1024
	ds_read_b128 v[168:171], v159 offset:2048
	ds_read_b128 v[172:175], v159 offset:3072
	v_add_u32_e32 v159, s44, v142
	ds_read_b128 v[176:179], v159
	ds_read_b128 v[192:195], v159 offset:1024
	ds_read_b128 v[196:199], v159 offset:2048
	ds_read_b128 v[200:203], v159 offset:3072
	s_add_u32 s36, s36, 0x80000
	s_addc_u32 s37, s37, 0
	s_mov_b32 m0, s3
	v_lshl_add_u64 v[240:241], s[36:37], 0, v[132:133]
	ds_read_b128 v[204:207], v143 offset:32768
	ds_read_b128 v[208:211], v143 offset:33792
	ds_read_b128 v[212:215], v143 offset:34816
	ds_read_b128 v[216:219], v143 offset:35840
	ds_read_b128 v[220:223], v143 offset:36864
	ds_read_b128 v[224:227], v143 offset:37888
	ds_read_b128 v[228:231], v143 offset:38912
	ds_read_b128 v[232:235], v143 offset:39936
	global_load_lds_dwordx4 v[240:241], off
	v_lshl_add_u64 v[240:241], s[36:37], 0, v[130:131]
	s_mov_b32 m0, s4
	s_nop 0
	global_load_lds_dwordx4 v[240:241], off
	s_waitcnt vmcnt(8)
	s_waitcnt lgkmcnt(0)
	s_barrier
	v_mfma_f32_16x16x32_bf16 v[124:127], v[160:163], v[204:207], v[124:127]
	v_mfma_f32_16x16x32_bf16 v[120:123], v[168:171], v[204:207], v[120:123]
	v_mfma_f32_16x16x32_bf16 v[108:111], v[160:163], v[212:215], v[108:111]
	v_mfma_f32_16x16x32_bf16 v[104:107], v[168:171], v[212:215], v[104:107]
	v_mfma_f32_16x16x32_bf16 v[92:95], v[160:163], v[220:223], v[92:95]
	v_mfma_f32_16x16x32_bf16 v[88:91], v[168:171], v[220:223], v[88:91]
	v_mfma_f32_16x16x32_bf16 v[76:79], v[160:163], v[228:231], v[76:79]
	v_mfma_f32_16x16x32_bf16 v[72:75], v[168:171], v[228:231], v[72:75]
	v_mfma_f32_16x16x32_bf16 v[124:127], v[164:167], v[208:211], v[124:127]
	v_mfma_f32_16x16x32_bf16 v[120:123], v[172:175], v[208:211], v[120:123]
	v_mfma_f32_16x16x32_bf16 v[108:111], v[164:167], v[216:219], v[108:111]
	v_mfma_f32_16x16x32_bf16 v[104:107], v[172:175], v[216:219], v[104:107]
	v_mfma_f32_16x16x32_bf16 v[92:95], v[164:167], v[224:227], v[92:95]
	v_mfma_f32_16x16x32_bf16 v[88:91], v[172:175], v[224:227], v[88:91]
	v_mfma_f32_16x16x32_bf16 v[76:79], v[164:167], v[232:235], v[76:79]
	v_mfma_f32_16x16x32_bf16 v[72:75], v[172:175], v[232:235], v[72:75]
	v_mfma_f32_16x16x32_bf16 v[116:119], v[176:179], v[204:207], v[116:119]
	v_mfma_f32_16x16x32_bf16 v[112:115], v[196:199], v[204:207], v[112:115]
	v_mfma_f32_16x16x32_bf16 v[100:103], v[176:179], v[212:215], v[100:103]
	v_mfma_f32_16x16x32_bf16 v[96:99], v[196:199], v[212:215], v[96:99]
	v_mfma_f32_16x16x32_bf16 v[84:87], v[176:179], v[220:223], v[84:87]
	v_mfma_f32_16x16x32_bf16 v[80:83], v[196:199], v[220:223], v[80:83]
	v_mfma_f32_16x16x32_bf16 v[68:71], v[176:179], v[228:231], v[68:71]
	v_mfma_f32_16x16x32_bf16 v[64:67], v[196:199], v[228:231], v[64:67]
	v_mfma_f32_16x16x32_bf16 v[116:119], v[192:195], v[208:211], v[116:119]
	v_mfma_f32_16x16x32_bf16 v[112:115], v[200:203], v[208:211], v[112:115]
	v_mfma_f32_16x16x32_bf16 v[100:103], v[192:195], v[216:219], v[100:103]
	v_mfma_f32_16x16x32_bf16 v[96:99], v[200:203], v[216:219], v[96:99]
	v_mfma_f32_16x16x32_bf16 v[84:87], v[192:195], v[224:227], v[84:87]
	v_mfma_f32_16x16x32_bf16 v[80:83], v[200:203], v[224:227], v[80:83]
	v_mfma_f32_16x16x32_bf16 v[68:71], v[192:195], v[232:235], v[68:71]
	v_mfma_f32_16x16x32_bf16 v[64:67], v[200:203], v[232:235], v[64:67]
	s_barrier
; #define PG8_STAGE(bufoff, gbase, voff) do { _Pragma("unroll") for (int _i = 0; _i < 2; ++_i) \
;         __builtin_amdgcn_global_load_lds((const unsigned*)((const char*)(gbase) + (voff)[_i]), (LAS unsigned*)(lds + (bufoff) + ldsw + _i * 8192), 16, 0, 0); } while (0)
; #define PG8_LDA(dst, b, h) do { _Pragma("unroll") for (int m = 0; m < 4; ++m) _Pragma("unroll") for (int k = 0; k < 2; ++k) dst[m][k] = *(const LAS bf16x8*)(lds + PG8_SA(b, h) + aoff + m * 2048 + k * 1024); } while (0)
; #define PG8_MMA(ai, bj, At, Bt) do { __builtin_amdgcn_s_setprio(1); _Pragma("unroll") for (int m = 0; m < 4; ++m) _Pragma("unroll") for (int n = 0; n < 2; ++n) _Pragma("unroll") for (int k = 0; k < 2; ++k) \
;         acc[ai][bj][m][n] = __builtin_amdgcn_mfma_f32_16x16x32_bf16(Bt[n][k], At[m][k], acc[ai][bj][m][n], 0, 0, 0); __builtin_amdgcn_s_setprio(0); } while (0)
; #define PG8_WAIT_V(n) asm volatile("s_waitcnt vmcnt(" #n ")" ::: "memory")
; #define PG8_WAIT_L(n) asm volatile("s_waitcnt lgkmcnt(" #n ")" ::: "memory")
; #define PG8_BAR __builtin_amdgcn_s_barrier()
; #define PG8_SCHED __builtin_amdgcn_sched_barrier(0)
; template <class Epi, class Map>
; __device__ __forceinline__ void gemm_phase(LAS unsigned char* lds, const Gemm g, const Sched<Map>& S, const Epi& E) {
;     ...
;             PG8_LDA(At, 1, 1); PG8_STAGE(PG8_SB(1, 0), b3, voffB); PG8_STAGE(PG8_SB(1, 1), b3 + hstepB, voffB); PG8_STAGE(PG8_SA(1, 0), a3, voffA);
;             PG8_WAIT_V(8); PG8_WAIT_L(0); PG8_BAR; PG8_MMA(1, 0, At, B0); PG8_MMA(1, 1, At, B1); PG8_BAR; PG8_SCHED;
;         }
	s_add_i32 s36, s41, s0
	v_lshl_add_u64 v[138:139], v[138:139], 0, s[82:83]
	s_mov_b32 m0, s36
	ds_read_b128 v[204:207], v143 offset:49152
	ds_read_b128 v[208:211], v143 offset:50176
	ds_read_b128 v[212:215], v143 offset:51200
	ds_read_b128 v[216:219], v143 offset:52224
	ds_read_b128 v[220:223], v143 offset:53248
	ds_read_b128 v[224:227], v143 offset:54272
	ds_read_b128 v[228:231], v143 offset:55296
	ds_read_b128 v[232:235], v143 offset:56320
	global_load_lds_dwordx4 v[138:139], off
	s_add_i32 m0, s36, 0x2000
	s_add_u32 s34, s34, 0x80080
	v_lshl_add_u64 v[138:139], v[180:181], 0, s[82:83]
	s_addc_u32 s35, s35, 0
	s_add_i32 s36, s44, s0
	global_load_lds_dwordx4 v[138:139], off
	v_lshl_add_u64 v[138:139], s[34:35], 0, v[144:145]
	s_mov_b32 m0, s36
	s_nop 0
	global_load_lds_dwordx4 v[138:139], off
	v_lshl_add_u64 v[138:139], s[34:35], 0, v[128:129]
	s_add_i32 m0, s36, 0x2000
	s_nop 0
	global_load_lds_dwordx4 v[138:139], off
	v_lshl_add_u64 v[138:139], v[236:237], 0, s[82:83]
	s_mov_b32 m0, s6
	s_nop 0
	global_load_lds_dwordx4 v[138:139], off
	v_lshl_add_u64 v[138:139], v[238:239], 0, s[82:83]
	s_mov_b32 m0, s7
	s_nop 0
	global_load_lds_dwordx4 v[138:139], off
	s_waitcnt vmcnt(8)
	s_waitcnt lgkmcnt(0)
	s_barrier
	v_mfma_f32_16x16x32_bf16 v[60:63], v[160:163], v[204:207], v[60:63]
	v_mfma_f32_16x16x32_bf16 v[56:59], v[168:171], v[204:207], v[56:59]
	v_mfma_f32_16x16x32_bf16 v[44:47], v[160:163], v[212:215], v[44:47]
	v_mfma_f32_16x16x32_bf16 v[40:43], v[168:171], v[212:215], v[40:43]
	v_mfma_f32_16x16x32_bf16 v[28:31], v[160:163], v[220:223], v[28:31]
	v_mfma_f32_16x16x32_bf16 v[24:27], v[168:171], v[220:223], v[24:27]
	v_mfma_f32_16x16x32_bf16 v[12:15], v[160:163], v[228:231], v[12:15]
	v_mfma_f32_16x16x32_bf16 v[8:11], v[168:171], v[228:231], v[8:11]
	v_mfma_f32_16x16x32_bf16 v[60:63], v[164:167], v[208:211], v[60:63]
	v_mfma_f32_16x16x32_bf16 v[56:59], v[172:175], v[208:211], v[56:59]
	v_mfma_f32_16x16x32_bf16 v[44:47], v[164:167], v[216:219], v[44:47]
	v_mfma_f32_16x16x32_bf16 v[40:43], v[172:175], v[216:219], v[40:43]
	v_mfma_f32_16x16x32_bf16 v[28:31], v[164:167], v[224:227], v[28:31]
	v_mfma_f32_16x16x32_bf16 v[24:27], v[172:175], v[224:227], v[24:27]
	v_mfma_f32_16x16x32_bf16 v[12:15], v[164:167], v[232:235], v[12:15]
	v_mfma_f32_16x16x32_bf16 v[8:11], v[172:175], v[232:235], v[8:11]
	v_mfma_f32_16x16x32_bf16 v[52:55], v[176:179], v[204:207], v[52:55]
	v_mfma_f32_16x16x32_bf16 v[48:51], v[196:199], v[204:207], v[48:51]
	v_mfma_f32_16x16x32_bf16 v[36:39], v[176:179], v[212:215], v[36:39]
	v_mfma_f32_16x16x32_bf16 v[32:35], v[196:199], v[212:215], v[32:35]
	v_mfma_f32_16x16x32_bf16 v[20:23], v[176:179], v[220:223], v[20:23]
	v_mfma_f32_16x16x32_bf16 v[16:19], v[196:199], v[220:223], v[16:19]
	v_mfma_f32_16x16x32_bf16 v[4:7], v[176:179], v[228:231], v[4:7]
	v_mfma_f32_16x16x32_bf16 v[0:3], v[196:199], v[228:231], v[0:3]
	v_mfma_f32_16x16x32_bf16 v[52:55], v[192:195], v[208:211], v[52:55]
	v_mfma_f32_16x16x32_bf16 v[48:51], v[200:203], v[208:211], v[48:51]
	v_mfma_f32_16x16x32_bf16 v[36:39], v[192:195], v[216:219], v[36:39]
	v_mfma_f32_16x16x32_bf16 v[32:35], v[200:203], v[216:219], v[32:35]
	v_mfma_f32_16x16x32_bf16 v[20:23], v[192:195], v[224:227], v[20:23]
	v_mfma_f32_16x16x32_bf16 v[16:19], v[200:203], v[224:227], v[16:19]
	v_mfma_f32_16x16x32_bf16 v[4:7], v[192:195], v[232:235], v[4:7]
	v_mfma_f32_16x16x32_bf16 v[0:3], v[200:203], v[232:235], v[0:3]
	s_barrier
	s_add_i32 s40, s40, 2
	s_add_u32 s30, s30, 0x100
	s_addc_u32 s31, s31, 0
	s_add_u32 s21, s21, 0x100
	s_addc_u32 s33, s33, 0
	s_cmp_gt_u32 s40, 29
	s_cbranch_scc0 .LBB0_1088
	s_and_b64 vcc, exec, s[18:19]
	s_cbranch_vccz .LBB0_1091
	s_barrier

; #define PG8_STAGE(bufoff, gbase, voff) do { _Pragma("unroll") for (int _i = 0; _i < 2; ++_i) \
;         __builtin_amdgcn_global_load_lds((const unsigned*)((const char*)(gbase) + (voff)[_i]), (LAS unsigned*)(lds + (bufoff) + ldsw + _i * 8192), 16, 0, 0); } while (0)
; #define PG8_LDA(dst, b, h) do { _Pragma("unroll") for (int m = 0; m < 4; ++m) _Pragma("unroll") for (int k = 0; k < 2; ++k) dst[m][k] = *(const LAS bf16x8*)(lds + PG8_SA(b, h) + aoff + m * 2048 + k * 1024); } while (0)
; #define PG8_LDB(dst, b, h) do { _Pragma("unroll") for (int n = 0; n < 2; ++n) _Pragma("unroll") for (int k = 0; k < 2; ++k) dst[n][k] = *(const LAS bf16x8*)(lds + PG8_SB(b, h) + boff + n * 2048 + k * 1024); } while (0)
; #define PG8_MMA(ai, bj, At, Bt) do { __builtin_amdgcn_s_setprio(1); _Pragma("unroll") for (int m = 0; m < 4; ++m) _Pragma("unroll") for (int n = 0; n < 2; ++n) _Pragma("unroll") for (int k = 0; k < 2; ++k) \
;         acc[ai][bj][m][n] = __builtin_amdgcn_mfma_f32_16x16x32_bf16(Bt[n][k], At[m][k], acc[ai][bj][m][n], 0, 0, 0); __builtin_amdgcn_s_setprio(0); } while (0)
; #define PG8_WAIT_V(n) asm volatile("s_waitcnt vmcnt(" #n ")" ::: "memory")
; #define PG8_WAIT_L(n) asm volatile("s_waitcnt lgkmcnt(" #n ")" ::: "memory")
; #define PG8_BAR __builtin_amdgcn_s_barrier()
; #define PG8_SCHED __builtin_amdgcn_sched_barrier(0)
; template <class Epi, class Map>
; __device__ __forceinline__ void gemm_phase(LAS unsigned char* lds, const Gemm g, const Sched<Map>& S, const Epi& E) {
;     ...
;         for (int t = 0; t < nt; t += 2) {
;             const bool last = (t == nt - 2);
;             const char* a1 = cA + (size_t)(t + 1) * kstep;
;             const char* a2 = last ? nA : cA + (size_t)(t + 2) * kstep; const char* b2 = last ? nB : cB + (size_t)(t + 2) * kstep;
;             const char* a3 = a2 + kstep; const char* b3 = b2 + kstep;
;             PG8_LDB(B0, 0, 0); PG8_LDB(B1, 0, 1); PG8_SCHED; PG8_LDA(At, 0, 0); PG8_STAGE(PG8_SA(1, 1), a1 + hstepA, voffA);
;             PG8_WAIT_V(8); PG8_WAIT_L(0); PG8_BAR; PG8_MMA(0, 0, At, B0); PG8_MMA(0, 1, At, B1); PG8_BAR; PG8_SCHED;
;             PG8_LDA(At, 0, 1); PG8_STAGE(PG8_SB(0, 0), b2, voffB); PG8_STAGE(PG8_SB(0, 1), b2 + hstepB, voffB); PG8_STAGE(PG8_SA(0, 0), a2, voffA);
;             PG8_WAIT_V(8); PG8_WAIT_L(0); PG8_BAR; PG8_MMA(1, 0, At, B0); PG8_MMA(1, 1, At, B1); PG8_BAR; PG8_SCHED;
.LBB0_1161:
	s_add_u32 s30, s28, 0xffe00080
	s_addc_u32 s31, s29, -1
	s_add_i32 s50, 0, 0x10000
	s_cmpk_eq_i32 s49, 0x7c
	s_cselect_b32 s35, s37, s31
	s_cselect_b32 s34, s44, s30
	s_cselect_b32 s31, s45, s48
	s_cselect_b32 s30, s46, s47
	s_add_i32 s52, 0, 0x14000
	v_add_u32_e32 v116, s50, v173
	v_add_u32_e32 v170, s52, v173
	ds_read_b128 v[104:107], v116
	ds_read_b128 v[108:111], v116 offset:1024
	ds_read_b128 v[112:115], v116 offset:2048
	ds_read_b128 v[116:119], v116 offset:3072
	ds_read_b128 v[176:179], v170
	ds_read_b128 v[192:195], v170 offset:1024
	ds_read_b128 v[196:199], v170 offset:2048
	ds_read_b128 v[200:203], v170 offset:3072
	v_lshl_add_u64 v[170:171], s[28:29], 0, v[166:167]
	s_add_i32 m0, s3, 0xc000
	ds_read_b128 v[204:207], v174
	ds_read_b128 v[208:211], v174 offset:1024
	ds_read_b128 v[212:215], v174 offset:2048
	ds_read_b128 v[216:219], v174 offset:3072
	ds_read_b128 v[220:223], v174 offset:4096
	ds_read_b128 v[224:227], v174 offset:5120
	ds_read_b128 v[228:231], v174 offset:6144
	ds_read_b128 v[232:235], v174 offset:7168
	global_load_lds_dwordx4 v[170:171], off
	v_lshl_add_u64 v[170:171], s[28:29], 0, v[168:169]
	s_add_i32 m0, s3, 0xe000
	s_nop 0
	global_load_lds_dwordx4 v[170:171], off
	s_waitcnt vmcnt(8)
	s_waitcnt lgkmcnt(0)
	s_barrier
	v_mfma_f32_16x16x32_bf16 v[140:143], v[104:107], v[204:207], v[140:143]
	v_mfma_f32_16x16x32_bf16 v[136:139], v[112:115], v[204:207], v[136:139]
	v_mfma_f32_16x16x32_bf16 v[132:135], v[104:107], v[212:215], v[132:135]
	v_mfma_f32_16x16x32_bf16 v[128:131], v[112:115], v[212:215], v[128:131]
	v_mfma_f32_16x16x32_bf16 v[100:103], v[104:107], v[220:223], v[100:103]
	v_mfma_f32_16x16x32_bf16 v[96:99], v[112:115], v[220:223], v[96:99]
	v_mfma_f32_16x16x32_bf16 v[76:79], v[104:107], v[228:231], v[76:79]
	v_mfma_f32_16x16x32_bf16 v[72:75], v[112:115], v[228:231], v[72:75]
	v_mfma_f32_16x16x32_bf16 v[140:143], v[108:111], v[208:211], v[140:143]
	v_mfma_f32_16x16x32_bf16 v[136:139], v[116:119], v[208:211], v[136:139]
	v_mfma_f32_16x16x32_bf16 v[132:135], v[108:111], v[216:219], v[132:135]
	v_mfma_f32_16x16x32_bf16 v[128:131], v[116:119], v[216:219], v[128:131]
	v_mfma_f32_16x16x32_bf16 v[100:103], v[108:111], v[224:227], v[100:103]
	v_mfma_f32_16x16x32_bf16 v[96:99], v[116:119], v[224:227], v[96:99]
	v_mfma_f32_16x16x32_bf16 v[76:79], v[108:111], v[232:235], v[76:79]
	v_mfma_f32_16x16x32_bf16 v[72:75], v[116:119], v[232:235], v[72:75]
	v_mfma_f32_16x16x32_bf16 v[124:127], v[176:179], v[204:207], v[124:127]
	v_mfma_f32_16x16x32_bf16 v[120:123], v[196:199], v[204:207], v[120:123]
	v_mfma_f32_16x16x32_bf16 v[92:95], v[176:179], v[212:215], v[92:95]
	v_mfma_f32_16x16x32_bf16 v[88:91], v[196:199], v[212:215], v[88:91]
	v_mfma_f32_16x16x32_bf16 v[84:87], v[176:179], v[220:223], v[84:87]
	v_mfma_f32_16x16x32_bf16 v[80:83], v[196:199], v[220:223], v[80:83]
	v_mfma_f32_16x16x32_bf16 v[68:71], v[176:179], v[228:231], v[68:71]
	v_mfma_f32_16x16x32_bf16 v[64:67], v[196:199], v[228:231], v[64:67]
	v_mfma_f32_16x16x32_bf16 v[124:127], v[192:195], v[208:211], v[124:127]
	v_mfma_f32_16x16x32_bf16 v[120:123], v[200:203], v[208:211], v[120:123]
	v_mfma_f32_16x16x32_bf16 v[92:95], v[192:195], v[216:219], v[92:95]
	v_mfma_f32_16x16x32_bf16 v[88:91], v[200:203], v[216:219], v[88:91]
	v_mfma_f32_16x16x32_bf16 v[84:87], v[192:195], v[224:227], v[84:87]
	v_mfma_f32_16x16x32_bf16 v[80:83], v[200:203], v[224:227], v[80:83]
	v_mfma_f32_16x16x32_bf16 v[68:71], v[192:195], v[232:235], v[68:71]
	v_mfma_f32_16x16x32_bf16 v[64:67], v[200:203], v[232:235], v[64:67]
	s_barrier
	s_add_i32 s50, s50, s2
	v_lshl_add_u64 v[170:171], s[30:31], 0, v[144:145]
	s_mov_b32 m0, s50
	ds_read_b128 v[204:207], v174 offset:16384
	ds_read_b128 v[208:211], v174 offset:17408
	ds_read_b128 v[212:215], v174 offset:18432
	ds_read_b128 v[216:219], v174 offset:19456
	ds_read_b128 v[220:223], v174 offset:20480
	ds_read_b128 v[224:227], v174 offset:21504
	ds_read_b128 v[228:231], v174 offset:22528
	ds_read_b128 v[232:235], v174 offset:23552
	global_load_lds_dwordx4 v[170:171], off
	s_add_i32 m0, s50, 0x2000
	s_add_u32 s50, s30, 0x200000
	v_lshl_add_u64 v[180:181], s[30:31], 0, v[160:161]
	s_addc_u32 s51, s31, 0
	s_add_i32 s52, s52, s2
	global_load_lds_dwordx4 v[180:181], off
	v_lshl_add_u64 v[236:237], s[50:51], 0, v[144:145]
	s_mov_b32 m0, s52
	v_lshl_add_u64 v[238:239], s[34:35], 0, v[162:163]
	global_load_lds_dwordx4 v[236:237], off
	v_lshl_add_u64 v[236:237], s[50:51], 0, v[160:161]
	s_add_i32 m0, s52, 0x2000
	s_nop 0
	global_load_lds_dwordx4 v[236:237], off
	v_lshl_add_u64 v[236:237], s[34:35], 0, v[164:165]
	s_mov_b32 m0, s3
	s_nop 0
	global_load_lds_dwordx4 v[236:237], off
	s_mov_b32 m0, s4
	s_nop 0
	global_load_lds_dwordx4 v[238:239], off
	s_waitcnt vmcnt(8)
	s_waitcnt lgkmcnt(0)
	s_barrier
; #define PG8_STAGE(bufoff, gbase, voff) do { _Pragma("unroll") for (int _i = 0; _i < 2; ++_i) \
;         __builtin_amdgcn_global_load_lds((const unsigned*)((const char*)(gbase) + (voff)[_i]), (LAS unsigned*)(lds + (bufoff) + ldsw + _i * 8192), 16, 0, 0); } while (0)
; #define PG8_LDA(dst, b, h) do { _Pragma("unroll") for (int m = 0; m < 4; ++m) _Pragma("unroll") for (int k = 0; k < 2; ++k) dst[m][k] = *(const LAS bf16x8*)(lds + PG8_SA(b, h) + aoff + m * 2048 + k * 1024); } while (0)
; #define PG8_LDB(dst, b, h) do { _Pragma("unroll") for (int n = 0; n < 2; ++n) _Pragma("unroll") for (int k = 0; k < 2; ++k) dst[n][k] = *(const LAS bf16x8*)(lds + PG8_SB(b, h) + boff + n * 2048 + k * 1024); } while (0)
; #define PG8_MMA(ai, bj, At, Bt) do { __builtin_amdgcn_s_setprio(1); _Pragma("unroll") for (int m = 0; m < 4; ++m) _Pragma("unroll") for (int n = 0; n < 2; ++n) _Pragma("unroll") for (int k = 0; k < 2; ++k) \
;         acc[ai][bj][m][n] = __builtin_amdgcn_mfma_f32_16x16x32_bf16(Bt[n][k], At[m][k], acc[ai][bj][m][n], 0, 0, 0); __builtin_amdgcn_s_setprio(0); } while (0)
; #define PG8_WAIT_V(n) asm volatile("s_waitcnt vmcnt(" #n ")" ::: "memory")
; #define PG8_WAIT_L(n) asm volatile("s_waitcnt lgkmcnt(" #n ")" ::: "memory")
; #define PG8_BAR __builtin_amdgcn_s_barrier()
; #define PG8_SCHED __builtin_amdgcn_sched_barrier(0)
; template <class Epi, class Map>
; __device__ __forceinline__ void gemm_phase(LAS unsigned char* lds, const Gemm g, const Sched<Map>& S, const Epi& E) {
;     ...
;             PG8_WAIT_V(8); PG8_WAIT_L(0); PG8_BAR; PG8_MMA(1, 0, At, B0); PG8_MMA(1, 1, At, B1); PG8_BAR; PG8_SCHED;
;             PG8_LDB(B0, 1, 0); PG8_LDB(B1, 1, 1); PG8_SCHED; PG8_LDA(At, 1, 0); PG8_STAGE(PG8_SA(0, 1), a2 + hstepA, voffA);
;             PG8_WAIT_V(8); PG8_WAIT_L(0); PG8_BAR; PG8_MMA(0, 0, At, B0); PG8_MMA(0, 1, At, B1); PG8_BAR; PG8_SCHED;
;             PG8_LDA(At, 1, 1); PG8_STAGE(PG8_SB(1, 0), b3, voffB); PG8_STAGE(PG8_SB(1, 1), b3 + hstepB, voffB); PG8_STAGE(PG8_SA(1, 0), a3, voffA);
	v_mfma_f32_16x16x32_bf16 v[60:63], v[104:107], v[204:207], v[60:63]
	v_mfma_f32_16x16x32_bf16 v[56:59], v[112:115], v[204:207], v[56:59]
	v_mfma_f32_16x16x32_bf16 v[48:51], v[104:107], v[212:215], v[48:51]
	v_mfma_f32_16x16x32_bf16 v[40:43], v[112:115], v[212:215], v[40:43]
	v_mfma_f32_16x16x32_bf16 v[32:35], v[104:107], v[220:223], v[32:35]
	v_mfma_f32_16x16x32_bf16 v[24:27], v[112:115], v[220:223], v[24:27]
	v_mfma_f32_16x16x32_bf16 v[16:19], v[104:107], v[228:231], v[16:19]
	v_mfma_f32_16x16x32_bf16 v[8:11], v[112:115], v[228:231], v[8:11]
	v_mfma_f32_16x16x32_bf16 v[60:63], v[108:111], v[208:211], v[60:63]
	v_mfma_f32_16x16x32_bf16 v[56:59], v[116:119], v[208:211], v[56:59]
	v_mfma_f32_16x16x32_bf16 v[48:51], v[108:111], v[216:219], v[48:51]
	v_mfma_f32_16x16x32_bf16 v[40:43], v[116:119], v[216:219], v[40:43]
	v_mfma_f32_16x16x32_bf16 v[32:35], v[108:111], v[224:227], v[32:35]
	v_mfma_f32_16x16x32_bf16 v[24:27], v[116:119], v[224:227], v[24:27]
	v_mfma_f32_16x16x32_bf16 v[16:19], v[108:111], v[232:235], v[16:19]
	v_mfma_f32_16x16x32_bf16 v[8:11], v[116:119], v[232:235], v[8:11]
	v_mfma_f32_16x16x32_bf16 v[52:55], v[176:179], v[204:207], v[52:55]
	v_mfma_f32_16x16x32_bf16 v[44:47], v[196:199], v[204:207], v[44:47]
	v_mfma_f32_16x16x32_bf16 v[36:39], v[176:179], v[212:215], v[36:39]
	v_mfma_f32_16x16x32_bf16 v[28:31], v[196:199], v[212:215], v[28:31]
	v_mfma_f32_16x16x32_bf16 v[20:23], v[176:179], v[220:223], v[20:23]
	v_mfma_f32_16x16x32_bf16 v[12:15], v[196:199], v[220:223], v[12:15]
	v_mfma_f32_16x16x32_bf16 v[4:7], v[176:179], v[228:231], v[4:7]
	v_mfma_f32_16x16x32_bf16 v[0:3], v[196:199], v[228:231], v[0:3]
	v_mfma_f32_16x16x32_bf16 v[52:55], v[192:195], v[208:211], v[52:55]
	v_mfma_f32_16x16x32_bf16 v[44:47], v[200:203], v[208:211], v[44:47]
	v_mfma_f32_16x16x32_bf16 v[36:39], v[192:195], v[216:219], v[36:39]
	v_mfma_f32_16x16x32_bf16 v[28:31], v[200:203], v[216:219], v[28:31]
	v_mfma_f32_16x16x32_bf16 v[20:23], v[192:195], v[224:227], v[20:23]
	v_mfma_f32_16x16x32_bf16 v[12:15], v[200:203], v[224:227], v[12:15]
	v_mfma_f32_16x16x32_bf16 v[4:7], v[192:195], v[232:235], v[4:7]
	v_mfma_f32_16x16x32_bf16 v[0:3], v[200:203], v[232:235], v[0:3]
	s_barrier
	s_add_i32 s50, 0, 0x18000
	s_add_i32 s51, 0, 0x1c000
	v_add_u32_e32 v116, s50, v173
	v_add_u32_e32 v175, s51, v173
	ds_read_b128 v[104:107], v116
	ds_read_b128 v[108:111], v116 offset:1024
	ds_read_b128 v[112:115], v116 offset:2048
	ds_read_b128 v[116:119], v116 offset:3072
	ds_read_b128 v[176:179], v175
	ds_read_b128 v[192:195], v175 offset:1024
	ds_read_b128 v[196:199], v175 offset:2048
	ds_read_b128 v[200:203], v175 offset:3072
	s_add_u32 s34, s34, 0x200000
	s_addc_u32 s35, s35, 0
	s_mov_b32 m0, s5
	v_lshl_add_u64 v[240:241], s[34:35], 0, v[164:165]
	ds_read_b128 v[204:207], v174 offset:32768
	ds_read_b128 v[208:211], v174 offset:33792
	ds_read_b128 v[212:215], v174 offset:34816
	ds_read_b128 v[216:219], v174 offset:35840
	ds_read_b128 v[220:223], v174 offset:36864
	ds_read_b128 v[224:227], v174 offset:37888
	ds_read_b128 v[228:231], v174 offset:38912
	ds_read_b128 v[232:235], v174 offset:39936
	global_load_lds_dwordx4 v[240:241], off
	v_lshl_add_u64 v[240:241], s[34:35], 0, v[162:163]
	s_mov_b32 m0, s6
	s_nop 0
	global_load_lds_dwordx4 v[240:241], off
	s_waitcnt vmcnt(8)
	s_waitcnt lgkmcnt(0)
	s_barrier
	v_mfma_f32_16x16x32_bf16 v[140:143], v[104:107], v[204:207], v[140:143]
	v_mfma_f32_16x16x32_bf16 v[136:139], v[112:115], v[204:207], v[136:139]
	v_mfma_f32_16x16x32_bf16 v[132:135], v[104:107], v[212:215], v[132:135]
	v_mfma_f32_16x16x32_bf16 v[128:131], v[112:115], v[212:215], v[128:131]
	v_mfma_f32_16x16x32_bf16 v[100:103], v[104:107], v[220:223], v[100:103]
	v_mfma_f32_16x16x32_bf16 v[96:99], v[112:115], v[220:223], v[96:99]
	v_mfma_f32_16x16x32_bf16 v[76:79], v[104:107], v[228:231], v[76:79]
	v_mfma_f32_16x16x32_bf16 v[72:75], v[112:115], v[228:231], v[72:75]
	v_mfma_f32_16x16x32_bf16 v[140:143], v[108:111], v[208:211], v[140:143]
	v_mfma_f32_16x16x32_bf16 v[136:139], v[116:119], v[208:211], v[136:139]
	v_mfma_f32_16x16x32_bf16 v[132:135], v[108:111], v[216:219], v[132:135]
	v_mfma_f32_16x16x32_bf16 v[128:131], v[116:119], v[216:219], v[128:131]
	v_mfma_f32_16x16x32_bf16 v[100:103], v[108:111], v[224:227], v[100:103]
	v_mfma_f32_16x16x32_bf16 v[96:99], v[116:119], v[224:227], v[96:99]
	v_mfma_f32_16x16x32_bf16 v[76:79], v[108:111], v[232:235], v[76:79]
	v_mfma_f32_16x16x32_bf16 v[72:75], v[116:119], v[232:235], v[72:75]
	v_mfma_f32_16x16x32_bf16 v[124:127], v[176:179], v[204:207], v[124:127]
	v_mfma_f32_16x16x32_bf16 v[120:123], v[196:199], v[204:207], v[120:123]
	v_mfma_f32_16x16x32_bf16 v[92:95], v[176:179], v[212:215], v[92:95]
	v_mfma_f32_16x16x32_bf16 v[88:91], v[196:199], v[212:215], v[88:91]
	v_mfma_f32_16x16x32_bf16 v[84:87], v[176:179], v[220:223], v[84:87]
	v_mfma_f32_16x16x32_bf16 v[80:83], v[196:199], v[220:223], v[80:83]
	v_mfma_f32_16x16x32_bf16 v[68:71], v[176:179], v[228:231], v[68:71]
	v_mfma_f32_16x16x32_bf16 v[64:67], v[196:199], v[228:231], v[64:67]
	v_mfma_f32_16x16x32_bf16 v[124:127], v[192:195], v[208:211], v[124:127]
	v_mfma_f32_16x16x32_bf16 v[120:123], v[200:203], v[208:211], v[120:123]
	v_mfma_f32_16x16x32_bf16 v[92:95], v[192:195], v[216:219], v[92:95]
	v_mfma_f32_16x16x32_bf16 v[88:91], v[200:203], v[216:219], v[88:91]
	v_mfma_f32_16x16x32_bf16 v[84:87], v[192:195], v[224:227], v[84:87]
	v_mfma_f32_16x16x32_bf16 v[80:83], v[200:203], v[224:227], v[80:83]
	v_mfma_f32_16x16x32_bf16 v[68:71], v[192:195], v[232:235], v[68:71]
	v_mfma_f32_16x16x32_bf16 v[64:67], v[200:203], v[232:235], v[64:67]
	s_barrier
; #define PG8_STAGE(bufoff, gbase, voff) do { _Pragma("unroll") for (int _i = 0; _i < 2; ++_i) \
;         __builtin_amdgcn_global_load_lds((const unsigned*)((const char*)(gbase) + (voff)[_i]), (LAS unsigned*)(lds + (bufoff) + ldsw + _i * 8192), 16, 0, 0); } while (0)
; #define PG8_LDA(dst, b, h) do { _Pragma("unroll") for (int m = 0; m < 4; ++m) _Pragma("unroll") for (int k = 0; k < 2; ++k) dst[m][k] = *(const LAS bf16x8*)(lds + PG8_SA(b, h) + aoff + m * 2048 + k * 1024); } while (0)
; #define PG8_MMA(ai, bj, At, Bt) do { __builtin_amdgcn_s_setprio(1); _Pragma("unroll") for (int m = 0; m < 4; ++m) _Pragma("unroll") for (int n = 0; n < 2; ++n) _Pragma("unroll") for (int k = 0; k < 2; ++k) \
;         acc[ai][bj][m][n] = __builtin_amdgcn_mfma_f32_16x16x32_bf16(Bt[n][k], At[m][k], acc[ai][bj][m][n], 0, 0, 0); __builtin_amdgcn_s_setprio(0); } while (0)
; #define PG8_WAIT_V(n) asm volatile("s_waitcnt vmcnt(" #n ")" ::: "memory")
; #define PG8_WAIT_L(n) asm volatile("s_waitcnt lgkmcnt(" #n ")" ::: "memory")
; #define PG8_BAR __builtin_amdgcn_s_barrier()
; #define PG8_SCHED __builtin_amdgcn_sched_barrier(0)
; template <class Epi, class Map>
; __device__ __forceinline__ void gemm_phase(LAS unsigned char* lds, const Gemm g, const Sched<Map>& S, const Epi& E) {
;     ...
;             PG8_LDA(At, 1, 1); PG8_STAGE(PG8_SB(1, 0), b3, voffB); PG8_STAGE(PG8_SB(1, 1), b3 + hstepB, voffB); PG8_STAGE(PG8_SA(1, 0), a3, voffA);
;             PG8_WAIT_V(8); PG8_WAIT_L(0); PG8_BAR; PG8_MMA(1, 0, At, B0); PG8_MMA(1, 1, At, B1); PG8_BAR; PG8_SCHED;
;         }
	s_add_i32 s34, s50, s2
	v_lshl_add_u64 v[170:171], v[170:171], 0, s[82:83]
	s_mov_b32 m0, s34
	ds_read_b128 v[204:207], v174 offset:49152
	ds_read_b128 v[208:211], v174 offset:50176
	ds_read_b128 v[212:215], v174 offset:51200
	ds_read_b128 v[216:219], v174 offset:52224
	ds_read_b128 v[220:223], v174 offset:53248
	ds_read_b128 v[224:227], v174 offset:54272
	ds_read_b128 v[228:231], v174 offset:55296
	ds_read_b128 v[232:235], v174 offset:56320
	global_load_lds_dwordx4 v[170:171], off
	s_add_i32 m0, s34, 0x2000
	s_add_u32 s30, s30, 0x200080
	v_lshl_add_u64 v[170:171], v[180:181], 0, s[82:83]
	s_addc_u32 s31, s31, 0
	s_add_i32 s34, s51, s2
	global_load_lds_dwordx4 v[170:171], off
	v_lshl_add_u64 v[170:171], s[30:31], 0, v[144:145]
	s_mov_b32 m0, s34
	s_nop 0
	global_load_lds_dwordx4 v[170:171], off
	v_lshl_add_u64 v[170:171], s[30:31], 0, v[160:161]
	s_add_i32 m0, s34, 0x2000
	s_nop 0
	global_load_lds_dwordx4 v[170:171], off
	v_lshl_add_u64 v[170:171], v[236:237], 0, s[82:83]
	s_mov_b32 m0, s9
	s_nop 0
	global_load_lds_dwordx4 v[170:171], off
	v_lshl_add_u64 v[170:171], v[238:239], 0, s[82:83]
	s_mov_b32 m0, s10
	s_nop 0
	global_load_lds_dwordx4 v[170:171], off
	s_waitcnt vmcnt(8)
	s_waitcnt lgkmcnt(0)
	s_barrier
	v_mfma_f32_16x16x32_bf16 v[60:63], v[104:107], v[204:207], v[60:63]
	v_mfma_f32_16x16x32_bf16 v[56:59], v[112:115], v[204:207], v[56:59]
	v_mfma_f32_16x16x32_bf16 v[48:51], v[104:107], v[212:215], v[48:51]
	v_mfma_f32_16x16x32_bf16 v[40:43], v[112:115], v[212:215], v[40:43]
	v_mfma_f32_16x16x32_bf16 v[32:35], v[104:107], v[220:223], v[32:35]
	v_mfma_f32_16x16x32_bf16 v[24:27], v[112:115], v[220:223], v[24:27]
	v_mfma_f32_16x16x32_bf16 v[16:19], v[104:107], v[228:231], v[16:19]
	v_mfma_f32_16x16x32_bf16 v[8:11], v[112:115], v[228:231], v[8:11]
	v_mfma_f32_16x16x32_bf16 v[60:63], v[108:111], v[208:211], v[60:63]
	v_mfma_f32_16x16x32_bf16 v[56:59], v[116:119], v[208:211], v[56:59]
	v_mfma_f32_16x16x32_bf16 v[48:51], v[108:111], v[216:219], v[48:51]
	v_mfma_f32_16x16x32_bf16 v[40:43], v[116:119], v[216:219], v[40:43]
	v_mfma_f32_16x16x32_bf16 v[32:35], v[108:111], v[224:227], v[32:35]
	v_mfma_f32_16x16x32_bf16 v[24:27], v[116:119], v[224:227], v[24:27]
	v_mfma_f32_16x16x32_bf16 v[16:19], v[108:111], v[232:235], v[16:19]
	v_mfma_f32_16x16x32_bf16 v[8:11], v[116:119], v[232:235], v[8:11]
	v_mfma_f32_16x16x32_bf16 v[52:55], v[176:179], v[204:207], v[52:55]
	v_mfma_f32_16x16x32_bf16 v[44:47], v[196:199], v[204:207], v[44:47]
	v_mfma_f32_16x16x32_bf16 v[36:39], v[176:179], v[212:215], v[36:39]
	v_mfma_f32_16x16x32_bf16 v[28:31], v[196:199], v[212:215], v[28:31]
	v_mfma_f32_16x16x32_bf16 v[20:23], v[176:179], v[220:223], v[20:23]
	v_mfma_f32_16x16x32_bf16 v[12:15], v[196:199], v[220:223], v[12:15]
	v_mfma_f32_16x16x32_bf16 v[4:7], v[176:179], v[228:231], v[4:7]
	v_mfma_f32_16x16x32_bf16 v[0:3], v[196:199], v[228:231], v[0:3]
	v_mfma_f32_16x16x32_bf16 v[52:55], v[192:195], v[208:211], v[52:55]
	v_mfma_f32_16x16x32_bf16 v[44:47], v[200:203], v[208:211], v[44:47]
	v_mfma_f32_16x16x32_bf16 v[36:39], v[192:195], v[216:219], v[36:39]
	v_mfma_f32_16x16x32_bf16 v[28:31], v[200:203], v[216:219], v[28:31]
	v_mfma_f32_16x16x32_bf16 v[20:23], v[192:195], v[224:227], v[20:23]
	v_mfma_f32_16x16x32_bf16 v[12:15], v[200:203], v[224:227], v[12:15]
	v_mfma_f32_16x16x32_bf16 v[4:7], v[192:195], v[232:235], v[4:7]
	v_mfma_f32_16x16x32_bf16 v[0:3], v[200:203], v[232:235], v[0:3]
	s_barrier
	s_add_i32 s49, s49, 2
	s_add_u32 s28, s28, 0x100
	s_addc_u32 s29, s29, 0
	s_add_u32 s47, s47, 0x100
	s_addc_u32 s48, s48, 0
	s_cmpk_gt_u32 s49, 0x7d
	s_cbranch_scc0 .LBB0_1161
	s_and_b64 vcc, exec, s[18:19]
	s_cbranch_vccz .LBB0_1164
	s_barrier

; #define PG8_STAGE(bufoff, gbase, voff) do { _Pragma("unroll") for (int _i = 0; _i < 2; ++_i) \
;         __builtin_amdgcn_global_load_lds((const unsigned*)((const char*)(gbase) + (voff)[_i]), (LAS unsigned*)(lds + (bufoff) + ldsw + _i * 8192), 16, 0, 0); } while (0)
; #define PG8_LDA(dst, b, h) do { _Pragma("unroll") for (int m = 0; m < 4; ++m) _Pragma("unroll") for (int k = 0; k < 2; ++k) dst[m][k] = *(const LAS bf16x8*)(lds + PG8_SA(b, h) + aoff + m * 2048 + k * 1024); } while (0)
; #define PG8_LDB(dst, b, h) do { _Pragma("unroll") for (int n = 0; n < 2; ++n) _Pragma("unroll") for (int k = 0; k < 2; ++k) dst[n][k] = *(const LAS bf16x8*)(lds + PG8_SB(b, h) + boff + n * 2048 + k * 1024); } while (0)
; #define PG8_MMA(ai, bj, At, Bt) do { __builtin_amdgcn_s_setprio(1); _Pragma("unroll") for (int m = 0; m < 4; ++m) _Pragma("unroll") for (int n = 0; n < 2; ++n) _Pragma("unroll") for (int k = 0; k < 2; ++k) \
;         acc[ai][bj][m][n] = __builtin_amdgcn_mfma_f32_16x16x32_bf16(Bt[n][k], At[m][k], acc[ai][bj][m][n], 0, 0, 0); __builtin_amdgcn_s_setprio(0); } while (0)
; #define PG8_WAIT_V(n) asm volatile("s_waitcnt vmcnt(" #n ")" ::: "memory")
; #define PG8_WAIT_L(n) asm volatile("s_waitcnt lgkmcnt(" #n ")" ::: "memory")
; #define PG8_BAR __builtin_amdgcn_s_barrier()
; #define PG8_SCHED __builtin_amdgcn_sched_barrier(0)
; template <class Epi, class Map>
; __device__ __forceinline__ void gemm_phase(LAS unsigned char* lds, const Gemm g, const Sched<Map>& S, const Epi& E) {
;     ...
;         for (int t = 0; t < nt; t += 2) {
;             const bool last = (t == nt - 2);
;             const char* a1 = cA + (size_t)(t + 1) * kstep;
;             const char* a2 = last ? nA : cA + (size_t)(t + 2) * kstep; const char* b2 = last ? nB : cB + (size_t)(t + 2) * kstep;
;             const char* a3 = a2 + kstep; const char* b3 = b2 + kstep;
;             PG8_LDB(B0, 0, 0); PG8_LDB(B1, 0, 1); PG8_SCHED; PG8_LDA(At, 0, 0); PG8_STAGE(PG8_SA(1, 1), a1 + hstepA, voffA);
;             PG8_WAIT_V(8); PG8_WAIT_L(0); PG8_BAR; PG8_MMA(0, 0, At, B0); PG8_MMA(0, 1, At, B1); PG8_BAR; PG8_SCHED;
;             PG8_LDA(At, 0, 1); PG8_STAGE(PG8_SB(0, 0), b2, voffB); PG8_STAGE(PG8_SB(0, 1), b2 + hstepB, voffB); PG8_STAGE(PG8_SA(0, 0), a2, voffA);
;             PG8_WAIT_V(8); PG8_WAIT_L(0); PG8_BAR; PG8_MMA(1, 0, At, B0); PG8_MMA(1, 1, At, B1); PG8_BAR; PG8_SCHED;
.LBB0_1183:
	s_add_u32 s30, s28, 0xffe00080
	s_addc_u32 s31, s29, -1
	s_add_i32 s48, 0, 0x10000
	s_cmpk_eq_i32 s47, 0x7c
	s_cselect_b32 s35, s37, s31
	s_cselect_b32 s34, s40, s30
	s_cselect_b32 s31, s41, s46
	s_cselect_b32 s30, s44, s45
	s_add_i32 s50, 0, 0x14000
	v_add_u32_e32 v108, s48, v173
	v_add_u32_e32 v170, s50, v173
	ds_read_b128 v[64:67], v108
	ds_read_b128 v[68:71], v108 offset:1024
	ds_read_b128 v[72:75], v108 offset:2048
	ds_read_b128 v[108:111], v108 offset:3072
	ds_read_b128 v[166:169], v170
	ds_read_b128 v[176:179], v170 offset:1024
	ds_read_b128 v[192:195], v170 offset:2048
	ds_read_b128 v[196:199], v170 offset:3072
	v_lshl_add_u64 v[170:171], s[28:29], 0, v[162:163]
	s_add_i32 m0, s3, 0xc000
	ds_read_b128 v[200:203], v174
	ds_read_b128 v[204:207], v174 offset:1024
	ds_read_b128 v[208:211], v174 offset:2048
	ds_read_b128 v[212:215], v174 offset:3072
	ds_read_b128 v[216:219], v174 offset:4096
	ds_read_b128 v[220:223], v174 offset:5120
	ds_read_b128 v[224:227], v174 offset:6144
	ds_read_b128 v[228:231], v174 offset:7168
	global_load_lds_dwordx4 v[170:171], off
	v_lshl_add_u64 v[170:171], s[28:29], 0, v[164:165]
	s_add_i32 m0, s3, 0xe000
	s_nop 0
	global_load_lds_dwordx4 v[170:171], off
	s_waitcnt vmcnt(8)
	s_waitcnt lgkmcnt(0)
	s_barrier
	v_mfma_f32_16x16x32_bf16 v[140:143], v[64:67], v[200:203], v[140:143]
	v_mfma_f32_16x16x32_bf16 v[136:139], v[72:75], v[200:203], v[136:139]
	v_mfma_f32_16x16x32_bf16 v[132:135], v[64:67], v[208:211], v[132:135]
	v_mfma_f32_16x16x32_bf16 v[128:131], v[72:75], v[208:211], v[128:131]
	v_mfma_f32_16x16x32_bf16 v[104:107], v[64:67], v[216:219], v[104:107]
	v_mfma_f32_16x16x32_bf16 v[100:103], v[72:75], v[216:219], v[100:103]
	v_mfma_f32_16x16x32_bf16 v[96:99], v[64:67], v[224:227], v[96:99]
	v_mfma_f32_16x16x32_bf16 v[92:95], v[72:75], v[224:227], v[92:95]
	v_mfma_f32_16x16x32_bf16 v[140:143], v[68:71], v[204:207], v[140:143]
	v_mfma_f32_16x16x32_bf16 v[136:139], v[108:111], v[204:207], v[136:139]
	v_mfma_f32_16x16x32_bf16 v[132:135], v[68:71], v[212:215], v[132:135]
	v_mfma_f32_16x16x32_bf16 v[128:131], v[108:111], v[212:215], v[128:131]
	v_mfma_f32_16x16x32_bf16 v[104:107], v[68:71], v[220:223], v[104:107]
	v_mfma_f32_16x16x32_bf16 v[100:103], v[108:111], v[220:223], v[100:103]
	v_mfma_f32_16x16x32_bf16 v[96:99], v[68:71], v[228:231], v[96:99]
	v_mfma_f32_16x16x32_bf16 v[92:95], v[108:111], v[228:231], v[92:95]
	v_mfma_f32_16x16x32_bf16 v[124:127], v[166:169], v[200:203], v[124:127]
	v_mfma_f32_16x16x32_bf16 v[120:123], v[192:195], v[200:203], v[120:123]
	v_mfma_f32_16x16x32_bf16 v[116:119], v[166:169], v[208:211], v[116:119]
	v_mfma_f32_16x16x32_bf16 v[112:115], v[192:195], v[208:211], v[112:115]
	v_mfma_f32_16x16x32_bf16 v[88:91], v[166:169], v[216:219], v[88:91]
	v_mfma_f32_16x16x32_bf16 v[84:87], v[192:195], v[216:219], v[84:87]
	v_mfma_f32_16x16x32_bf16 v[80:83], v[166:169], v[224:227], v[80:83]
	v_mfma_f32_16x16x32_bf16 v[76:79], v[192:195], v[224:227], v[76:79]
	v_mfma_f32_16x16x32_bf16 v[124:127], v[176:179], v[204:207], v[124:127]
	v_mfma_f32_16x16x32_bf16 v[120:123], v[196:199], v[204:207], v[120:123]
	v_mfma_f32_16x16x32_bf16 v[116:119], v[176:179], v[212:215], v[116:119]
	v_mfma_f32_16x16x32_bf16 v[112:115], v[196:199], v[212:215], v[112:115]
	v_mfma_f32_16x16x32_bf16 v[88:91], v[176:179], v[220:223], v[88:91]
	v_mfma_f32_16x16x32_bf16 v[84:87], v[196:199], v[220:223], v[84:87]
	v_mfma_f32_16x16x32_bf16 v[80:83], v[176:179], v[228:231], v[80:83]
	v_mfma_f32_16x16x32_bf16 v[76:79], v[196:199], v[228:231], v[76:79]
	s_barrier
	s_add_i32 s48, s48, s2
	v_lshl_add_u64 v[170:171], s[30:31], 0, v[144:145]
	s_mov_b32 m0, s48
	ds_read_b128 v[200:203], v174 offset:16384
	ds_read_b128 v[204:207], v174 offset:17408
	ds_read_b128 v[208:211], v174 offset:18432
	ds_read_b128 v[212:215], v174 offset:19456
	ds_read_b128 v[216:219], v174 offset:20480
	ds_read_b128 v[220:223], v174 offset:21504
	ds_read_b128 v[224:227], v174 offset:22528
	ds_read_b128 v[228:231], v174 offset:23552
	global_load_lds_dwordx4 v[170:171], off
	s_add_i32 m0, s48, 0x2000
	s_add_u32 s48, s30, 0x200000
	v_lshl_add_u64 v[180:181], s[30:31], 0, v[160:161]
	s_addc_u32 s49, s31, 0
	s_add_i32 s50, s50, s2
	global_load_lds_dwordx4 v[180:181], off
	v_lshl_add_u64 v[232:233], s[48:49], 0, v[144:145]
	s_mov_b32 m0, s50
	v_lshl_add_u64 v[234:235], s[34:35], 0, v[160:161]
	global_load_lds_dwordx4 v[232:233], off
	v_lshl_add_u64 v[232:233], s[48:49], 0, v[160:161]
	s_add_i32 m0, s50, 0x2000
	s_nop 0
	global_load_lds_dwordx4 v[232:233], off
	v_lshl_add_u64 v[232:233], s[34:35], 0, v[144:145]
	s_mov_b32 m0, s3
	s_nop 0
	global_load_lds_dwordx4 v[232:233], off
	s_mov_b32 m0, s4
	s_nop 0
	global_load_lds_dwordx4 v[234:235], off
	s_waitcnt vmcnt(8)
	s_waitcnt lgkmcnt(0)
	s_barrier
; #define PG8_STAGE(bufoff, gbase, voff) do { _Pragma("unroll") for (int _i = 0; _i < 2; ++_i) \
;         __builtin_amdgcn_global_load_lds((const unsigned*)((const char*)(gbase) + (voff)[_i]), (LAS unsigned*)(lds + (bufoff) + ldsw + _i * 8192), 16, 0, 0); } while (0)
; #define PG8_LDA(dst, b, h) do { _Pragma("unroll") for (int m = 0; m < 4; ++m) _Pragma("unroll") for (int k = 0; k < 2; ++k) dst[m][k] = *(const LAS bf16x8*)(lds + PG8_SA(b, h) + aoff + m * 2048 + k * 1024); } while (0)
; #define PG8_LDB(dst, b, h) do { _Pragma("unroll") for (int n = 0; n < 2; ++n) _Pragma("unroll") for (int k = 0; k < 2; ++k) dst[n][k] = *(const LAS bf16x8*)(lds + PG8_SB(b, h) + boff + n * 2048 + k * 1024); } while (0)
; #define PG8_MMA(ai, bj, At, Bt) do { __builtin_amdgcn_s_setprio(1); _Pragma("unroll") for (int m = 0; m < 4; ++m) _Pragma("unroll") for (int n = 0; n < 2; ++n) _Pragma("unroll") for (int k = 0; k < 2; ++k) \
;         acc[ai][bj][m][n] = __builtin_amdgcn_mfma_f32_16x16x32_bf16(Bt[n][k], At[m][k], acc[ai][bj][m][n], 0, 0, 0); __builtin_amdgcn_s_setprio(0); } while (0)
; #define PG8_WAIT_V(n) asm volatile("s_waitcnt vmcnt(" #n ")" ::: "memory")
; #define PG8_WAIT_L(n) asm volatile("s_waitcnt lgkmcnt(" #n ")" ::: "memory")
; #define PG8_BAR __builtin_amdgcn_s_barrier()
; #define PG8_SCHED __builtin_amdgcn_sched_barrier(0)
; template <class Epi, class Map>
; __device__ __forceinline__ void gemm_phase(LAS unsigned char* lds, const Gemm g, const Sched<Map>& S, const Epi& E) {
;     ...
;             PG8_WAIT_V(8); PG8_WAIT_L(0); PG8_BAR; PG8_MMA(1, 0, At, B0); PG8_MMA(1, 1, At, B1); PG8_BAR; PG8_SCHED;
;             PG8_LDB(B0, 1, 0); PG8_LDB(B1, 1, 1); PG8_SCHED; PG8_LDA(At, 1, 0); PG8_STAGE(PG8_SA(0, 1), a2 + hstepA, voffA);
;             PG8_WAIT_V(8); PG8_WAIT_L(0); PG8_BAR; PG8_MMA(0, 0, At, B0); PG8_MMA(0, 1, At, B1); PG8_BAR; PG8_SCHED;
;             PG8_LDA(At, 1, 1); PG8_STAGE(PG8_SB(1, 0), b3, voffB); PG8_STAGE(PG8_SB(1, 1), b3 + hstepB, voffB); PG8_STAGE(PG8_SA(1, 0), a3, voffA);
	v_mfma_f32_16x16x32_bf16 v[60:63], v[64:67], v[200:203], v[60:63]
	v_mfma_f32_16x16x32_bf16 v[56:59], v[72:75], v[200:203], v[56:59]
	v_mfma_f32_16x16x32_bf16 v[52:55], v[64:67], v[208:211], v[52:55]
	v_mfma_f32_16x16x32_bf16 v[48:51], v[72:75], v[208:211], v[48:51]
	v_mfma_f32_16x16x32_bf16 v[28:31], v[64:67], v[216:219], v[28:31]
	v_mfma_f32_16x16x32_bf16 v[24:27], v[72:75], v[216:219], v[24:27]
	v_mfma_f32_16x16x32_bf16 v[20:23], v[64:67], v[224:227], v[20:23]
	v_mfma_f32_16x16x32_bf16 v[8:11], v[72:75], v[224:227], v[8:11]
	v_mfma_f32_16x16x32_bf16 v[60:63], v[68:71], v[204:207], v[60:63]
	v_mfma_f32_16x16x32_bf16 v[56:59], v[108:111], v[204:207], v[56:59]
	v_mfma_f32_16x16x32_bf16 v[52:55], v[68:71], v[212:215], v[52:55]
	v_mfma_f32_16x16x32_bf16 v[48:51], v[108:111], v[212:215], v[48:51]
	v_mfma_f32_16x16x32_bf16 v[28:31], v[68:71], v[220:223], v[28:31]
	v_mfma_f32_16x16x32_bf16 v[24:27], v[108:111], v[220:223], v[24:27]
	v_mfma_f32_16x16x32_bf16 v[20:23], v[68:71], v[228:231], v[20:23]
	v_mfma_f32_16x16x32_bf16 v[8:11], v[108:111], v[228:231], v[8:11]
	v_mfma_f32_16x16x32_bf16 v[44:47], v[166:169], v[200:203], v[44:47]
	v_mfma_f32_16x16x32_bf16 v[40:43], v[192:195], v[200:203], v[40:43]
	v_mfma_f32_16x16x32_bf16 v[36:39], v[166:169], v[208:211], v[36:39]
	v_mfma_f32_16x16x32_bf16 v[32:35], v[192:195], v[208:211], v[32:35]
	v_mfma_f32_16x16x32_bf16 v[16:19], v[166:169], v[216:219], v[16:19]
	v_mfma_f32_16x16x32_bf16 v[12:15], v[192:195], v[216:219], v[12:15]
	v_mfma_f32_16x16x32_bf16 v[4:7], v[166:169], v[224:227], v[4:7]
	v_mfma_f32_16x16x32_bf16 v[0:3], v[192:195], v[224:227], v[0:3]
	v_mfma_f32_16x16x32_bf16 v[44:47], v[176:179], v[204:207], v[44:47]
	v_mfma_f32_16x16x32_bf16 v[40:43], v[196:199], v[204:207], v[40:43]
	v_mfma_f32_16x16x32_bf16 v[36:39], v[176:179], v[212:215], v[36:39]
	v_mfma_f32_16x16x32_bf16 v[32:35], v[196:199], v[212:215], v[32:35]
	v_mfma_f32_16x16x32_bf16 v[16:19], v[176:179], v[220:223], v[16:19]
	v_mfma_f32_16x16x32_bf16 v[12:15], v[196:199], v[220:223], v[12:15]
	v_mfma_f32_16x16x32_bf16 v[4:7], v[176:179], v[228:231], v[4:7]
	v_mfma_f32_16x16x32_bf16 v[0:3], v[196:199], v[228:231], v[0:3]
	s_barrier
	s_add_i32 s48, 0, 0x18000
	s_add_i32 s49, 0, 0x1c000
	v_add_u32_e32 v108, s48, v173
	v_add_u32_e32 v175, s49, v173
	ds_read_b128 v[64:67], v108
	ds_read_b128 v[68:71], v108 offset:1024
	ds_read_b128 v[72:75], v108 offset:2048
	ds_read_b128 v[108:111], v108 offset:3072
	ds_read_b128 v[166:169], v175
	ds_read_b128 v[176:179], v175 offset:1024
	ds_read_b128 v[192:195], v175 offset:2048
	ds_read_b128 v[196:199], v175 offset:3072
	s_add_u32 s34, s34, 0x200000
	s_addc_u32 s35, s35, 0
	s_mov_b32 m0, s5
	v_lshl_add_u64 v[236:237], s[34:35], 0, v[144:145]
	ds_read_b128 v[200:203], v174 offset:32768
	ds_read_b128 v[204:207], v174 offset:33792
	ds_read_b128 v[208:211], v174 offset:34816
	ds_read_b128 v[212:215], v174 offset:35840
	ds_read_b128 v[216:219], v174 offset:36864
	ds_read_b128 v[220:223], v174 offset:37888
	ds_read_b128 v[224:227], v174 offset:38912
	ds_read_b128 v[228:231], v174 offset:39936
	global_load_lds_dwordx4 v[236:237], off
	v_lshl_add_u64 v[236:237], s[34:35], 0, v[160:161]
	s_mov_b32 m0, s6
	s_nop 0
	global_load_lds_dwordx4 v[236:237], off
	s_waitcnt vmcnt(8)
	s_waitcnt lgkmcnt(0)
	s_barrier
	v_mfma_f32_16x16x32_bf16 v[140:143], v[64:67], v[200:203], v[140:143]
	v_mfma_f32_16x16x32_bf16 v[136:139], v[72:75], v[200:203], v[136:139]
	v_mfma_f32_16x16x32_bf16 v[132:135], v[64:67], v[208:211], v[132:135]
	v_mfma_f32_16x16x32_bf16 v[128:131], v[72:75], v[208:211], v[128:131]
	v_mfma_f32_16x16x32_bf16 v[104:107], v[64:67], v[216:219], v[104:107]
	v_mfma_f32_16x16x32_bf16 v[100:103], v[72:75], v[216:219], v[100:103]
	v_mfma_f32_16x16x32_bf16 v[96:99], v[64:67], v[224:227], v[96:99]
	v_mfma_f32_16x16x32_bf16 v[92:95], v[72:75], v[224:227], v[92:95]
	v_mfma_f32_16x16x32_bf16 v[140:143], v[68:71], v[204:207], v[140:143]
	v_mfma_f32_16x16x32_bf16 v[136:139], v[108:111], v[204:207], v[136:139]
	v_mfma_f32_16x16x32_bf16 v[132:135], v[68:71], v[212:215], v[132:135]
	v_mfma_f32_16x16x32_bf16 v[128:131], v[108:111], v[212:215], v[128:131]
	v_mfma_f32_16x16x32_bf16 v[104:107], v[68:71], v[220:223], v[104:107]
	v_mfma_f32_16x16x32_bf16 v[100:103], v[108:111], v[220:223], v[100:103]
	v_mfma_f32_16x16x32_bf16 v[96:99], v[68:71], v[228:231], v[96:99]
	v_mfma_f32_16x16x32_bf16 v[92:95], v[108:111], v[228:231], v[92:95]
	v_mfma_f32_16x16x32_bf16 v[124:127], v[166:169], v[200:203], v[124:127]
	v_mfma_f32_16x16x32_bf16 v[120:123], v[192:195], v[200:203], v[120:123]
	v_mfma_f32_16x16x32_bf16 v[116:119], v[166:169], v[208:211], v[116:119]
	v_mfma_f32_16x16x32_bf16 v[112:115], v[192:195], v[208:211], v[112:115]
	v_mfma_f32_16x16x32_bf16 v[88:91], v[166:169], v[216:219], v[88:91]
	v_mfma_f32_16x16x32_bf16 v[84:87], v[192:195], v[216:219], v[84:87]
	v_mfma_f32_16x16x32_bf16 v[80:83], v[166:169], v[224:227], v[80:83]
	v_mfma_f32_16x16x32_bf16 v[76:79], v[192:195], v[224:227], v[76:79]
	v_mfma_f32_16x16x32_bf16 v[124:127], v[176:179], v[204:207], v[124:127]
	v_mfma_f32_16x16x32_bf16 v[120:123], v[196:199], v[204:207], v[120:123]
	v_mfma_f32_16x16x32_bf16 v[116:119], v[176:179], v[212:215], v[116:119]
	v_mfma_f32_16x16x32_bf16 v[112:115], v[196:199], v[212:215], v[112:115]
	v_mfma_f32_16x16x32_bf16 v[88:91], v[176:179], v[220:223], v[88:91]
	v_mfma_f32_16x16x32_bf16 v[84:87], v[196:199], v[220:223], v[84:87]
	v_mfma_f32_16x16x32_bf16 v[80:83], v[176:179], v[228:231], v[80:83]
	v_mfma_f32_16x16x32_bf16 v[76:79], v[196:199], v[228:231], v[76:79]
	s_barrier
; #define PG8_STAGE(bufoff, gbase, voff) do { _Pragma("unroll") for (int _i = 0; _i < 2; ++_i) \
;         __builtin_amdgcn_global_load_lds((const unsigned*)((const char*)(gbase) + (voff)[_i]), (LAS unsigned*)(lds + (bufoff) + ldsw + _i * 8192), 16, 0, 0); } while (0)
; #define PG8_LDA(dst, b, h) do { _Pragma("unroll") for (int m = 0; m < 4; ++m) _Pragma("unroll") for (int k = 0; k < 2; ++k) dst[m][k] = *(const LAS bf16x8*)(lds + PG8_SA(b, h) + aoff + m * 2048 + k * 1024); } while (0)
; #define PG8_MMA(ai, bj, At, Bt) do { __builtin_amdgcn_s_setprio(1); _Pragma("unroll") for (int m = 0; m < 4; ++m) _Pragma("unroll") for (int n = 0; n < 2; ++n) _Pragma("unroll") for (int k = 0; k < 2; ++k) \
;         acc[ai][bj][m][n] = __builtin_amdgcn_mfma_f32_16x16x32_bf16(Bt[n][k], At[m][k], acc[ai][bj][m][n], 0, 0, 0); __builtin_amdgcn_s_setprio(0); } while (0)
; #define PG8_WAIT_V(n) asm volatile("s_waitcnt vmcnt(" #n ")" ::: "memory")
; #define PG8_WAIT_L(n) asm volatile("s_waitcnt lgkmcnt(" #n ")" ::: "memory")
; #define PG8_BAR __builtin_amdgcn_s_barrier()
; #define PG8_SCHED __builtin_amdgcn_sched_barrier(0)
; template <class Epi, class Map>
; __device__ __forceinline__ void gemm_phase(LAS unsigned char* lds, const Gemm g, const Sched<Map>& S, const Epi& E) {
;     ...
;             PG8_LDA(At, 1, 1); PG8_STAGE(PG8_SB(1, 0), b3, voffB); PG8_STAGE(PG8_SB(1, 1), b3 + hstepB, voffB); PG8_STAGE(PG8_SA(1, 0), a3, voffA);
;             PG8_WAIT_V(8); PG8_WAIT_L(0); PG8_BAR; PG8_MMA(1, 0, At, B0); PG8_MMA(1, 1, At, B1); PG8_BAR; PG8_SCHED;
;         }
	s_add_i32 s34, s48, s2
	v_lshl_add_u64 v[170:171], v[170:171], 0, s[82:83]
	s_mov_b32 m0, s34
	ds_read_b128 v[200:203], v174 offset:49152
	ds_read_b128 v[204:207], v174 offset:50176
	ds_read_b128 v[208:211], v174 offset:51200
	ds_read_b128 v[212:215], v174 offset:52224
	ds_read_b128 v[216:219], v174 offset:53248
	ds_read_b128 v[220:223], v174 offset:54272
	ds_read_b128 v[224:227], v174 offset:55296
	ds_read_b128 v[228:231], v174 offset:56320
	global_load_lds_dwordx4 v[170:171], off
	s_add_i32 m0, s34, 0x2000
	s_add_u32 s30, s30, 0x200080
	v_lshl_add_u64 v[170:171], v[180:181], 0, s[82:83]
	s_addc_u32 s31, s31, 0
	s_add_i32 s34, s49, s2
	global_load_lds_dwordx4 v[170:171], off
	v_lshl_add_u64 v[170:171], s[30:31], 0, v[144:145]
	s_mov_b32 m0, s34
	s_nop 0
	global_load_lds_dwordx4 v[170:171], off
	v_lshl_add_u64 v[170:171], s[30:31], 0, v[160:161]
	s_add_i32 m0, s34, 0x2000
	s_nop 0
	global_load_lds_dwordx4 v[170:171], off
	v_lshl_add_u64 v[170:171], v[232:233], 0, s[82:83]
	s_mov_b32 m0, s9
	s_nop 0
	global_load_lds_dwordx4 v[170:171], off
	v_lshl_add_u64 v[170:171], v[234:235], 0, s[82:83]
	s_mov_b32 m0, s10
	s_nop 0
	global_load_lds_dwordx4 v[170:171], off
	s_waitcnt vmcnt(8)
	s_waitcnt lgkmcnt(0)
	s_barrier
	v_mfma_f32_16x16x32_bf16 v[60:63], v[64:67], v[200:203], v[60:63]
	v_mfma_f32_16x16x32_bf16 v[56:59], v[72:75], v[200:203], v[56:59]
	v_mfma_f32_16x16x32_bf16 v[52:55], v[64:67], v[208:211], v[52:55]
	v_mfma_f32_16x16x32_bf16 v[48:51], v[72:75], v[208:211], v[48:51]
	v_mfma_f32_16x16x32_bf16 v[28:31], v[64:67], v[216:219], v[28:31]
	v_mfma_f32_16x16x32_bf16 v[24:27], v[72:75], v[216:219], v[24:27]
	v_mfma_f32_16x16x32_bf16 v[20:23], v[64:67], v[224:227], v[20:23]
	v_mfma_f32_16x16x32_bf16 v[8:11], v[72:75], v[224:227], v[8:11]
	v_mfma_f32_16x16x32_bf16 v[60:63], v[68:71], v[204:207], v[60:63]
	v_mfma_f32_16x16x32_bf16 v[56:59], v[108:111], v[204:207], v[56:59]
	v_mfma_f32_16x16x32_bf16 v[52:55], v[68:71], v[212:215], v[52:55]
	v_mfma_f32_16x16x32_bf16 v[48:51], v[108:111], v[212:215], v[48:51]
	v_mfma_f32_16x16x32_bf16 v[28:31], v[68:71], v[220:223], v[28:31]
	v_mfma_f32_16x16x32_bf16 v[24:27], v[108:111], v[220:223], v[24:27]
	v_mfma_f32_16x16x32_bf16 v[20:23], v[68:71], v[228:231], v[20:23]
	v_mfma_f32_16x16x32_bf16 v[8:11], v[108:111], v[228:231], v[8:11]
	v_mfma_f32_16x16x32_bf16 v[44:47], v[166:169], v[200:203], v[44:47]
	v_mfma_f32_16x16x32_bf16 v[40:43], v[192:195], v[200:203], v[40:43]
	v_mfma_f32_16x16x32_bf16 v[36:39], v[166:169], v[208:211], v[36:39]
	v_mfma_f32_16x16x32_bf16 v[32:35], v[192:195], v[208:211], v[32:35]
	v_mfma_f32_16x16x32_bf16 v[16:19], v[166:169], v[216:219], v[16:19]
	v_mfma_f32_16x16x32_bf16 v[12:15], v[192:195], v[216:219], v[12:15]
	v_mfma_f32_16x16x32_bf16 v[4:7], v[166:169], v[224:227], v[4:7]
	v_mfma_f32_16x16x32_bf16 v[0:3], v[192:195], v[224:227], v[0:3]
	v_mfma_f32_16x16x32_bf16 v[44:47], v[176:179], v[204:207], v[44:47]
	v_mfma_f32_16x16x32_bf16 v[40:43], v[196:199], v[204:207], v[40:43]
	v_mfma_f32_16x16x32_bf16 v[36:39], v[176:179], v[212:215], v[36:39]
	v_mfma_f32_16x16x32_bf16 v[32:35], v[196:199], v[212:215], v[32:35]
	v_mfma_f32_16x16x32_bf16 v[16:19], v[176:179], v[220:223], v[16:19]
	v_mfma_f32_16x16x32_bf16 v[12:15], v[196:199], v[220:223], v[12:15]
	v_mfma_f32_16x16x32_bf16 v[4:7], v[176:179], v[228:231], v[4:7]
	v_mfma_f32_16x16x32_bf16 v[0:3], v[196:199], v[228:231], v[0:3]
	s_barrier
	s_add_i32 s47, s47, 2
	s_add_u32 s28, s28, 0x100
	s_addc_u32 s29, s29, 0
	s_add_u32 s45, s45, 0x100
	s_addc_u32 s46, s46, 0
	s_cmpk_gt_u32 s47, 0x7d
	s_cbranch_scc0 .LBB0_1183
	s_and_b64 vcc, exec, s[18:19]
	s_cbranch_vccz .LBB0_1186
	s_barrier
